# perm + leading half's pre-epilogue alignment barrier moved to the epilogue's first vmcnt wait (its epilogue loads and address math overlap the trailing half's last MFMA block)
# speedup vs baseline: 1.0037x; 1.0037x over previous
; __device__ __forceinline__ void rstd8(const float* ss, int row0, int fq, float (&rs)[8]) {
;     f32x4 a[8];
; #pragma unroll
;     for (int k = 0; k < 8; ++k) a[k] = *(const f32x4*)(ss + (size_t)(row0 + (k >> 2) * 128 + (k & 3) * 16) * 16 + 4 * fq);
; #pragma unroll
;     for (int k = 0; k < 8; ++k) { float s = (a[k][0] + a[k][1]) + (a[k][2] + a[k][3]); s += __shfl_xor(s, 16); s += __shfl_xor(s, 32); rs[k] = __builtin_amdgcn_rsqf(s * (1.f / 1024.f) + EPS); }
; }
;     __device__ __forceinline__ void operator()(const pg8::f32x4 (&acc)[2][2][4][2], const Unit& u, int wr, int wc, int fr, int fq) const {
;         const int pn = u.pn; const int row0 = u.pm * BM + wr * 64 + fr; const int sp = pn / tps, pt = pn - sp * tps; bf16* const Ob = O + (size_t)sp * sstride;
;         float rsv[8]; rstd8(ss, row0, fq, rsv);
;         if (pn < rope_tiles) {
;             const float s_ = (pn >= sc_lo && pn < sc_hi) ? sc : 1.f;
.LBB0_200:
	s_lshl_b32 s19, s4, 8
	s_add_i32 s19, s19, s48
	v_or_b32_e32 v178, s19, v1
	v_or_b32_e32 v176, 16, v178
	v_ashrrev_i32_e32 v179, 31, v178
	v_ashrrev_i32_e32 v177, 31, v176
	v_lshlrev_b64 v[158:159], 6, v[178:179]
	v_lshlrev_b64 v[168:169], 6, v[176:177]
	v_lshl_add_u64 v[158:159], v[144:145], 0, v[158:159]
	v_lshl_add_u64 v[168:169], v[144:145], 0, v[168:169]
	v_or_b32_e32 v170, 32, v178
	global_load_dwordx4 v[190:193], v[158:159], off
	global_load_dwordx4 v[194:197], v[168:169], off
	v_ashrrev_i32_e32 v171, 31, v170
	v_or_b32_e32 v168, 48, v178
	v_lshlrev_b64 v[158:159], 6, v[170:171]
	v_ashrrev_i32_e32 v169, 31, v168
	v_lshl_add_u64 v[158:159], v[144:145], 0, v[158:159]
	v_lshlrev_b64 v[180:181], 6, v[168:169]
	v_lshl_add_u64 v[180:181], v[144:145], 0, v[180:181]
	global_load_dwordx4 v[198:201], v[158:159], off
	global_load_dwordx4 v[202:205], v[180:181], off
	v_add_u32_e32 v158, 0x80, v178
	v_ashrrev_i32_e32 v159, 31, v158
	v_lshlrev_b64 v[180:181], 6, v[158:159]
	v_lshl_add_u64 v[180:181], v[144:145], 0, v[180:181]
	global_load_dwordx4 v[206:209], v[180:181], off
	v_add_u32_e32 v188, 0x90, v178
	v_ashrrev_i32_e32 v189, 31, v188
	v_lshlrev_b64 v[180:181], 6, v[188:189]
	v_lshl_add_u64 v[180:181], v[144:145], 0, v[180:181]
	global_load_dwordx4 v[210:213], v[180:181], off
	v_add_u32_e32 v186, 0xa0, v178
	v_ashrrev_i32_e32 v187, 31, v186
	v_add_u32_e32 v184, 0xb0, v178
	v_lshlrev_b64 v[180:181], 6, v[186:187]
	v_lshl_add_u64 v[180:181], v[144:145], 0, v[180:181]
	v_ashrrev_i32_e32 v185, 31, v184
	global_load_dwordx4 v[214:217], v[180:181], off
	v_lshlrev_b64 v[180:181], 6, v[184:185]
	v_lshl_add_u64 v[180:181], v[144:145], 0, v[180:181]
	global_load_dwordx4 v[218:221], v[180:181], off
	v_and_b32_e32 v155, 64, v173
	v_xor_b32_e32 v138, 16, v173
	v_add_u32_e32 v155, 64, v155
	v_xor_b32_e32 v157, 32, v173
	v_cmp_lt_i32_e32 vcc, v138, v155
	s_ashr_i32 s1, s0, 31
	s_lshr_b32 s1, s1, 12
	v_cndmask_b32_e32 v138, v173, v138, vcc
	v_cmp_lt_i32_e32 vcc, v157, v155
	v_lshlrev_b32_e32 v138, 2, v138
	s_add_i32 s1, s0, s1
	v_cndmask_b32_e32 v155, v173, v157, vcc
	v_lshlrev_b32_e32 v155, 2, v155
	s_ashr_i32 s4, s1, 20
	s_ashr_i32 s5, s4, 31
	s_lshl_b64 s[26:27], s[4:5], 26
	s_add_u32 s1, s46, s26
	s_addc_u32 s2, s47, s27
	s_and_b64 s[98:99], exec, s[16:17]
	s_cbranch_scc0 .Lal_0
	s_barrier
.Lal_0:
	s_cmp_gt_i32 s0, 3
	s_mov_b64 s[26:27], -1
	s_waitcnt vmcnt(0)
	v_add_f32_e32 v157, v190, v191
	v_add_f32_e32 v160, v192, v193
	v_add_f32_e32 v157, v157, v160
	v_add_f32_e32 v160, v194, v195
	v_add_f32_e32 v162, v196, v197
	v_mov_b32_e32 v191, v157
	s_nop 1
	v_permlane16_swap_b32 v157, v191
	v_add_f32_e32 v160, v160, v162
	v_add_f32_e32 v164, v198, v199
	v_add_f32_e32 v166, v200, v201
	v_add_f32_e32 v172, v202, v203
	v_add_f32_e32 v174, v204, v205
	v_add_f32_e32 v162, v164, v166
	v_add_f32_e32 v164, v172, v174
	v_add_f32_e32 v180, v206, v207
	v_add_f32_e32 v181, v208, v209
	v_mov_b32_e32 v172, v160
	s_nop 1
	v_permlane16_swap_b32 v160, v172
	v_add_f32_e32 v166, v180, v181
	v_mov_b32_e32 v180, v164
	s_nop 1
	v_permlane16_swap_b32 v164, v180
	v_add_f32_e32 v182, v210, v211
	v_add_f32_e32 v190, v212, v213
	s_waitcnt lgkmcnt(2)
	v_add_f32_e32 v157, v157, v191
	v_add_f32_e32 v181, v182, v190
	v_mov_b32_e32 v174, v162
	s_nop 1
	v_permlane16_swap_b32 v162, v174
	v_mov_b32_e32 v190, v157
	s_nop 1
	v_permlane32_swap_b32 v157, v190
	s_waitcnt lgkmcnt(3)
	v_add_f32_e32 v160, v160, v172
	s_waitcnt lgkmcnt(2)
	v_add_f32_e32 v164, v164, v180
	v_mov_b32_e32 v172, v160
	s_nop 1
	v_permlane32_swap_b32 v160, v172
	v_mov_b32_e32 v182, v166
	s_nop 1
	v_permlane16_swap_b32 v166, v182
	v_mov_b32_e32 v180, v164
	s_nop 1
	v_permlane32_swap_b32 v164, v180
	s_waitcnt lgkmcnt(4)
	v_add_f32_e32 v162, v162, v174
	s_waitcnt lgkmcnt(3)
	v_add_f32_e32 v157, v157, v190
	v_mov_b32_e32 v174, v162
	s_nop 1
	v_permlane32_swap_b32 v162, v174
	v_fmamk_f32 v157, v157, 0x3a800000, v175
	s_waitcnt lgkmcnt(3)
	v_add_f32_e32 v160, v160, v172
	s_waitcnt lgkmcnt(2)
	v_add_f32_e32 v166, v166, v182
	s_waitcnt lgkmcnt(1)
	v_add_f32_e32 v164, v164, v180
	v_rsq_f32_e32 v180, v157
	v_fmamk_f32 v157, v160, 0x3a800000, v175
	v_mov_b32_e32 v191, v166
	s_nop 1
	v_permlane32_swap_b32 v166, v191
	v_rsq_f32_e32 v182, v157
	v_mov_b32_e32 v157, v181
	s_nop 1
	v_permlane16_swap_b32 v181, v157
	s_waitcnt lgkmcnt(2)
	v_add_f32_e32 v162, v162, v174
	v_fmamk_f32 v160, v162, 0x3a800000, v175
	v_fmamk_f32 v162, v164, 0x3a800000, v175
	v_rsq_f32_e32 v172, v160
	v_rsq_f32_e32 v174, v162
	s_waitcnt lgkmcnt(1)
	v_add_f32_e32 v160, v166, v191
	s_waitcnt lgkmcnt(0)
	v_add_f32_e32 v157, v181, v157
	v_add_f32_e32 v162, v214, v215
	v_add_f32_e32 v166, v216, v217
	v_add_f32_e32 v181, v218, v219
	v_add_f32_e32 v190, v220, v221
	v_fmamk_f32 v160, v160, 0x3a800000, v175
	v_add_f32_e32 v162, v162, v166
	v_add_f32_e32 v181, v181, v190
	v_rsq_f32_e32 v164, v160
	v_mov_b32_e32 v160, v157
	s_nop 1
	v_permlane32_swap_b32 v157, v160
	v_mov_b32_e32 v166, v162
	s_nop 1
	v_permlane16_swap_b32 v162, v166
	v_mov_b32_e32 v138, v181
	s_nop 1
	v_permlane16_swap_b32 v181, v138
	s_waitcnt lgkmcnt(2)
	v_add_f32_e32 v157, v157, v160
	s_waitcnt lgkmcnt(1)
	v_add_f32_e32 v160, v162, v166
	s_waitcnt lgkmcnt(0)
	v_add_f32_e32 v138, v181, v138
	v_mov_b32_e32 v162, v160
	s_nop 1
	v_permlane32_swap_b32 v160, v162
	v_mov_b32_e32 v155, v138
	s_nop 1
	v_permlane32_swap_b32 v138, v155
	v_fmamk_f32 v157, v157, 0x3a800000, v175
	v_rsq_f32_e32 v166, v157
	s_waitcnt lgkmcnt(1)
	v_add_f32_e32 v157, v160, v162
	s_waitcnt lgkmcnt(0)
	v_add_f32_e32 v138, v138, v155
	v_fmamk_f32 v157, v157, 0x3a800000, v175
	v_fmamk_f32 v138, v138, 0x3a800000, v175
	v_rsq_f32_e32 v160, v157
	v_rsq_f32_e32 v162, v138
	s_cbranch_scc1 .LBB0_203
	s_andn2_b64 vcc, exec, s[26:27]
	s_cbranch_vccz .LBB0_208

; __device__ __forceinline__ unsigned cvt_pk_bf16(float lo, float hi) { unsigned r; asm volatile("v_cvt_pk_bf16_f32 %0, %1, %2" : "=v"(r) : "v"(lo), "v"(hi)); return r; }
; __device__ __forceinline__ float bflo(unsigned w) { return __uint_as_float(w << 16); }
; __device__ __forceinline__ float bfhi(unsigned w) { return __uint_as_float(w & 0xffff0000u); }
; __device__ __forceinline__ float gelu_tanh(float v) { const float z = 1.5957691216057308f * (v + 0.044715f * v * v * v); return v * sigm(z); }
;     __device__ __forceinline__ void operator()(const pg8::f32x4 (&acc)[2][2][4][2], const Unit& u, int wr, int wc, int fr, int fq) const {
;         const int row0 = u.pm * BM + wr * 64 + fr; const int c0 = 8 * (fq & 1);
;         const f32x4 d0 = *(const f32x4*)(dsk + u.g * 16 + c0), d1 = *(const f32x4*)(dsk + u.g * 16 + c0 + 4);
;         const int colb = u.pn * BM + wc * 32 + 8 * fq;
;         v4u nu[2];
; #pragma unroll
;         for (int bj = 0; bj < 2; ++bj) nu[bj] = *(const v4u*)(UX + ((size_t)u.g * 1024 + row0) * 640 + ((colb + bj * HALF) >> 4) * 16 + c0);
; #pragma unroll
;         for (int k = 0; k < 8; ++k) { const int ai = k >> 2, m = k & 3; const int row = row0 + ai * HALF + m * 16; v4u cu[2];
; #pragma unroll
;             for (int bj = 0; bj < 2; ++bj) cu[bj] = nu[bj];
;             if (k < 7) {
; #pragma unroll
;                 for (int bj = 0; bj < 2; ++bj) nu[bj] = *(const v4u*)(UX + ((size_t)u.g * 1024 + row0 + ((k + 1) >> 2) * HALF + ((k + 1) & 3) * 16) * 640 + ((colb + bj * HALF) >> 4) * 16 + c0); }
; #pragma unroll
;             for (int bj = 0; bj < 2; ++bj) { const int tau = (colb + bj * HALF) >> 4;
;                 const v4u uw = cu[bj]; const f32x4 a0 = acc[ai][bj][m][0], a1 = acc[ai][bj][m][1];
;                 float r[8]; r[0] = a0[0] + d0[0] * bflo(uw.x); r[1] = a0[1] + d0[1] * bfhi(uw.x); r[2] = a0[2] + d0[2] * bflo(uw.y); r[3] = a0[3] + d0[3] * bfhi(uw.y);
;                 r[4] = a1[0] + d1[0] * bflo(uw.z); r[5] = a1[1] + d1[1] * bfhi(uw.z); r[6] = a1[2] + d1[2] * bflo(uw.w); r[7] = a1[3] + d1[3] * bfhi(uw.w);
; #pragma unroll
;                 for (int e = 0; e < 8; ++e) r[e] = gelu_tanh(r[e]);
;                 v4u w; w.x = cvt_pk_bf16(r[0], r[1]); w.y = cvt_pk_bf16(r[2], r[3]); w.z = cvt_pk_bf16(r[4], r[5]); w.w = cvt_pk_bf16(r[6], r[7]);
;                 *(v4u*)(Y + ((size_t)row * 32 + tau) * 512 + u.g * 16 + c0) = w; } }
.LBB0_433:
	v_lshl_add_u32 v162, s1, 8, v1
	s_ashr_i32 s5, s4, 31
	s_lshl_b32 s2, s0, 8
	s_lshl_b64 s[0:1], s[4:5], 10
	v_ashrrev_i32_e32 v163, 31, v162
	v_lshl_add_u64 v[62:63], s[0:1], 0, v[162:163]
	v_mov_b64_e32 v[64:65], s[8:9]
	v_mad_u64_u32 v[64:65], s[0:1], v62, s61, v[64:65]
	v_mad_i32_i24 v65, v63, s61, v65
	v_bitop3_b32 v62, s2, v171, v167 bitop3:0xc8
	v_lshl_add_u64 v[64:65], v[64:65], 0, v[154:155]
	v_ashrrev_i32_e32 v63, 31, v62
	v_lshl_add_u64 v[164:165], v[62:63], 1, v[64:65]
	s_lshl_b32 s4, s4, 4
	global_load_dwordx4 v[172:175], v[164:165], off
	s_ashr_i32 s5, s4, 31
	v_lshl_add_u64 v[62:63], s[4:5], 2, v[156:157]
	global_load_dwordx4 v[66:69], v[62:63], off
	s_nop 0
	global_load_dwordx4 v[62:65], v[62:63], off offset:16
	v_add_co_u32_e32 v142, vcc, s62, v164
	global_load_dwordx4 v[176:179], v[164:165], off offset:256
	v_lshl_add_u64 v[138:139], v[164:165], 0, s[20:21]
	v_addc_co_u32_e32 v143, vcc, 0, v165, vcc
	global_load_dwordx4 v[138:141], v[138:139], off offset:256
	s_nop 0
	global_load_dwordx4 v[142:145], v[142:143], off
	v_lshlrev_b64 v[180:181], 15, v[162:163]
	v_or_b32_e32 v182, s2, v167
	s_lshl_b64 s[4:5], s[4:5], 1
	s_and_b64 s[98:99], exec, s[18:19]
	s_cbranch_scc0 .Lal_1
	s_barrier
.Lal_1:
	s_waitcnt vmcnt(0)
	v_lshlrev_b32_e32 v163, 16, v172
	v_lshlrev_b32_e32 v183, 16, v173
	v_fma_f32 v134, v66, v163, v134
	v_mul_f32_e32 v163, 0x3d372713, v134
	v_mul_f32_e32 v163, v134, v163
	v_fma_f32 v163, v134, v163, v134
	v_mul_f32_e32 v163, 0x3fcc422a, v163
	v_mul_f32_e32 v163, 0xbfb8aa3b, v163
	v_exp_f32_e32 v163, v163
	v_and_b32_e32 v173, 0xffff0000, v173
	v_fma_f32 v136, v68, v183, v136
	v_and_b32_e32 v172, 0xffff0000, v172
	v_fmac_f32_e32 v137, v69, v173
	v_mul_f32_e32 v173, 0x3d372713, v136
	v_fma_f32 v135, v67, v172, v135
	v_mul_f32_e32 v173, v136, v173
	v_add_f32_e32 v163, 1.0, v163
	v_mul_f32_e32 v172, 0x3d372713, v135
	v_fma_f32 v173, v136, v173, v136
	v_rcp_f32_e32 v163, v163
	v_lshlrev_b32_e32 v184, 16, v174
	v_lshlrev_b32_e32 v185, 16, v175
	v_and_b32_e32 v175, 0xffff0000, v175
	v_mul_f32_e32 v172, v135, v172
	v_mul_f32_e32 v173, 0x3fcc422a, v173
	v_and_b32_e32 v174, 0xffff0000, v174
	v_fma_f32 v130, v62, v184, v130
	v_fma_f32 v132, v64, v185, v132
	v_fmac_f32_e32 v133, v65, v175
	v_fma_f32 v172, v135, v172, v135
	v_mul_f32_e32 v173, 0xbfb8aa3b, v173
	v_fma_f32 v131, v63, v174, v131
	v_mul_f32_e32 v175, 0x3d372713, v130
	v_mul_f32_e32 v184, 0x3d372713, v132
	v_mul_f32_e32 v185, 0x3d372713, v133
	v_mul_f32_e32 v172, 0x3fcc422a, v172
	v_exp_f32_e32 v173, v173
	v_mul_f32_e32 v174, 0x3d372713, v137
	v_mul_f32_e32 v183, 0x3d372713, v131
	v_mul_f32_e32 v175, v130, v175
	v_mul_f32_e32 v184, v132, v184
	v_mul_f32_e32 v172, 0xbfb8aa3b, v172
	v_mul_f32_e32 v134, v134, v163
	v_mul_f32_e32 v163, v133, v185
	v_mul_f32_e32 v174, v137, v174
	v_mul_f32_e32 v183, v131, v183
	v_fma_f32 v175, v130, v175, v130
	v_fma_f32 v184, v132, v184, v132
	v_exp_f32_e32 v172, v172
	v_fma_f32 v163, v133, v163, v133
	v_fma_f32 v174, v137, v174, v137
	v_fma_f32 v183, v131, v183, v131
	v_mul_f32_e32 v175, 0x3fcc422a, v175
	v_mul_f32_e32 v184, 0x3fcc422a, v184
	v_mul_f32_e32 v163, 0x3fcc422a, v163
	v_mul_f32_e32 v174, 0x3fcc422a, v174
	v_mul_f32_e32 v183, 0x3fcc422a, v183
	v_mul_f32_e32 v175, 0xbfb8aa3b, v175
	v_mul_f32_e32 v184, 0xbfb8aa3b, v184
	v_add_f32_e32 v173, 1.0, v173
	v_mul_f32_e32 v163, 0xbfb8aa3b, v163
	v_mul_f32_e32 v174, 0xbfb8aa3b, v174
	v_mul_f32_e32 v183, 0xbfb8aa3b, v183
	v_exp_f32_e32 v175, v175
	v_exp_f32_e32 v184, v184
	v_rcp_f32_e32 v173, v173
	v_exp_f32_e32 v163, v163
	v_exp_f32_e32 v174, v174
	v_exp_f32_e32 v183, v183
	v_add_f32_e32 v172, 1.0, v172
	v_rcp_f32_e32 v172, v172
	v_add_f32_e32 v175, 1.0, v175
	v_mul_f32_e32 v136, v136, v173
	v_add_f32_e32 v173, 1.0, v184
	v_add_f32_e32 v163, 1.0, v163
	v_add_f32_e32 v174, 1.0, v174
	v_add_f32_e32 v183, 1.0, v183
	v_rcp_f32_e32 v175, v175
	v_rcp_f32_e32 v173, v173
	v_rcp_f32_e32 v163, v163
	v_rcp_f32_e32 v174, v174
	v_mul_f32_e32 v135, v135, v172
	v_rcp_f32_e32 v172, v183
	v_mul_f32_e32 v130, v130, v175
	v_mul_f32_e32 v175, v132, v173
	v_mul_f32_e32 v133, v133, v163
	v_ashrrev_i32_e32 v132, 4, v182
	v_mul_f32_e32 v137, v137, v174
	v_mul_f32_e32 v131, v131, v172
	v_cvt_pk_bf16_f32 v172, v134, v135
	v_cvt_pk_bf16_f32 v173, v136, v137
	v_cvt_pk_bf16_f32 v174, v130, v131
	v_cvt_pk_bf16_f32 v175, v175, v133
	v_ashrrev_i32_e32 v133, 31, v132
	v_lshl_add_u64 v[134:135], s[14:15], 0, v[180:181]
	v_lshlrev_b64 v[130:131], 10, v[132:133]
	v_lshl_add_u64 v[136:137], v[134:135], 0, v[130:131]
	v_lshl_add_u64 v[136:137], v[136:137], 0, s[4:5]
	v_lshlrev_b32_e32 v133, 16, v176
	v_lshl_add_u64 v[136:137], v[136:137], 0, v[154:155]
	v_fma_f32 v126, v66, v133, v126
	global_store_dwordx4 v[136:137], v[172:175], off
	v_mul_f32_e32 v136, 0x3d372713, v126
	v_mul_f32_e32 v136, v126, v136
	v_and_b32_e32 v133, 0xffff0000, v176
	v_fma_f32 v136, v126, v136, v126
	v_fma_f32 v127, v67, v133, v127
	v_lshlrev_b32_e32 v133, 16, v177
	v_mul_f32_e32 v136, 0x3fcc422a, v136
	v_fma_f32 v128, v68, v133, v128
	v_and_b32_e32 v133, 0xffff0000, v177
	v_mul_f32_e32 v136, 0xbfb8aa3b, v136
	v_fmac_f32_e32 v129, v69, v133
	v_lshlrev_b32_e32 v133, 16, v178
	v_exp_f32_e32 v136, v136
	v_fma_f32 v122, v62, v133, v122
	v_and_b32_e32 v133, 0xffff0000, v178
	v_fma_f32 v123, v63, v133, v123
	v_lshlrev_b32_e32 v133, 16, v179
	v_fma_f32 v124, v64, v133, v124
	v_and_b32_e32 v133, 0xffff0000, v179
	v_mul_f32_e32 v163, 0x3d372713, v129
	v_fmac_f32_e32 v125, v65, v133
	v_add_f32_e32 v133, 1.0, v136
	v_mul_f32_e32 v136, 0x3d372713, v127
	v_mul_f32_e32 v137, 0x3d372713, v128
	v_mul_f32_e32 v163, v129, v163
	v_mul_f32_e32 v136, v127, v136
; __device__ __forceinline__ unsigned cvt_pk_bf16(float lo, float hi) { unsigned r; asm volatile("v_cvt_pk_bf16_f32 %0, %1, %2" : "=v"(r) : "v"(lo), "v"(hi)); return r; }
; __device__ __forceinline__ float sigm(float x) { return __builtin_amdgcn_rcpf(1.f + __expf(-x)); }
; __device__ __forceinline__ float wave_sum(float v) {
; #pragma unroll
;     for (int o = 1; o < 64; o <<= 1) v += __shfl_xor(v, o);
;     return v;
; }
; __device__ __forceinline__ void sincos_rad(float x, float& s, float& c) {
;     double r = (double)x * 0.15915494309189535; r -= __builtin_rint(r); const float fr = (float)r;
;     s = __builtin_amdgcn_sinf(fr); c = __builtin_amdgcn_cosf(fr);
; }
; __device__ __forceinline__ void cpow(float lr, float li, float delta, float j, float& re, float& im) {
;     const float mag = expf(j * delta * lr); float s, c; sincos_rad(j * delta * li, s, c); re = mag * c; im = mag * s;
; }
;     __device__ __forceinline__ void operator()(const pg8::f32x4 (&acc)[2][2][4][2], const Unit& u, int wr, int wc, int fr, int fq) const {
;     ...
;         for (int k = 0; k < 8; ++k) { const int ai = k >> 2, m = k & 3; const int row = row0 + ai * HALF + m * 16; v4u cu[2];
; #pragma unroll
;             for (int bj = 0; bj < 2; ++bj) cu[bj] = nu[bj];
;             if (k < 7) {
; #pragma unroll
;                 for (int bj = 0; bj < 2; ++bj) nu[bj] = *(const v4u*)(UX + ((size_t)u.g * 1024 + row0 + ((k + 1) >> 2) * HALF + ((k + 1) & 3) * 16) * 640 + ((colb + bj * HALF) >> 4) * 16 + c0); }
; #pragma unroll
;             for (int bj = 0; bj < 2; ++bj) { const int tau = (colb + bj * HALF) >> 4;
;                 const v4u uw = cu[bj]; const f32x4 a0 = acc[ai][bj][m][0], a1 = acc[ai][bj][m][1];
;                 float r[8]; r[0] = a0[0] + d0[0] * bflo(uw.x); r[1] = a0[1] + d0[1] * bfhi(uw.x); r[2] = a0[2] + d0[2] * bflo(uw.y); r[3] = a0[3] + d0[3] * bfhi(uw.y);
;                 r[4] = a1[0] + d1[0] * bflo(uw.z); r[5] = a1[1] + d1[1] * bfhi(uw.z); r[6] = a1[2] + d1[2] * bflo(uw.w); r[7] = a1[3] + d1[3] * bfhi(uw.w);
; #pragma unroll
;                 for (int e = 0; e < 8; ++e) r[e] = gelu_tanh(r[e]);
;                 v4u w; w.x = cvt_pk_bf16(r[0], r[1]); w.y = cvt_pk_bf16(r[2], r[3]); w.z = cvt_pk_bf16(r[4], r[5]); w.w = cvt_pk_bf16(r[6], r[7]);
;                 *(v4u*)(Y + ((size_t)row * 32 + tau) * 512 + u.g * 16 + c0) = w; } }
	v_mul_f32_e32 v137, v128, v137
	v_fma_f32 v163, v129, v163, v129
	v_fma_f32 v136, v127, v136, v127
	v_fma_f32 v137, v128, v137, v128
	v_mul_f32_e32 v163, 0x3fcc422a, v163
	v_mul_f32_e32 v136, 0x3fcc422a, v136
	v_mul_f32_e32 v137, 0x3fcc422a, v137
	v_mul_f32_e32 v163, 0xbfb8aa3b, v163
	v_mul_f32_e32 v136, 0xbfb8aa3b, v136
	v_mul_f32_e32 v137, 0xbfb8aa3b, v137
	v_rcp_f32_e32 v133, v133
	v_exp_f32_e32 v163, v163
	v_exp_f32_e32 v136, v136
	v_exp_f32_e32 v137, v137
	v_mul_f32_e32 v133, v126, v133
	v_add_f32_e32 v126, 1.0, v163
	v_mul_f32_e32 v163, 0x3d372713, v125
	v_add_f32_e32 v136, 1.0, v136
	v_add_f32_e32 v137, 1.0, v137
	v_mul_f32_e32 v163, v125, v163
	v_rcp_f32_e32 v136, v136
	v_rcp_f32_e32 v137, v137
	v_fma_f32 v163, v125, v163, v125
	v_mul_f32_e32 v163, 0x3fcc422a, v163
	v_mul_f32_e32 v163, 0xbfb8aa3b, v163
	v_exp_f32_e32 v163, v163
	v_mul_f32_e32 v127, v127, v136
	v_mul_f32_e32 v128, v128, v137
	v_mul_f32_e32 v136, 0x3d372713, v122
	v_mul_f32_e32 v137, 0x3d372713, v123
	v_mul_f32_e32 v136, v122, v136
	v_mul_f32_e32 v137, v123, v137
	v_fma_f32 v136, v122, v136, v122
	v_fma_f32 v137, v123, v137, v123
	v_mul_f32_e32 v136, 0x3fcc422a, v136
	v_mul_f32_e32 v137, 0x3fcc422a, v137
	v_add_f32_e32 v163, 1.0, v163
	v_mul_f32_e32 v136, 0xbfb8aa3b, v136
	v_mul_f32_e32 v137, 0xbfb8aa3b, v137
	v_rcp_f32_e32 v163, v163
	v_rcp_f32_e32 v126, v126
	v_exp_f32_e32 v136, v136
	v_exp_f32_e32 v137, v137
	v_mul_f32_e32 v125, v125, v163
	v_lshlrev_b32_e32 v163, 16, v142
	v_and_b32_e32 v142, 0xffff0000, v142
	v_mul_f32_e32 v129, v129, v126
	v_add_f32_e32 v126, 1.0, v136
	v_add_f32_e32 v136, 1.0, v137
	v_mul_f32_e32 v137, 0x3d372713, v124
	v_fma_f32 v118, v66, v163, v118
	v_fma_f32 v119, v67, v142, v119
	v_lshlrev_b32_e32 v142, 16, v143
	v_mul_f32_e32 v137, v124, v137
	v_fma_f32 v120, v68, v142, v120
	v_and_b32_e32 v142, 0xffff0000, v143
	v_mul_f32_e32 v143, 0x3d372713, v118
	v_fma_f32 v137, v124, v137, v124
	v_mul_f32_e32 v143, v118, v143
	v_mul_f32_e32 v137, 0x3fcc422a, v137
	v_fma_f32 v143, v118, v143, v118
	v_rcp_f32_e32 v126, v126
	v_mul_f32_e32 v137, 0xbfb8aa3b, v137
	v_mul_f32_e32 v143, 0x3fcc422a, v143
	v_exp_f32_e32 v137, v137
	v_mul_f32_e32 v143, 0xbfb8aa3b, v143
	v_fmac_f32_e32 v121, v69, v142
	v_lshlrev_b32_e32 v142, 16, v144
	v_exp_f32_e32 v143, v143
	v_fma_f32 v114, v62, v142, v114
	v_and_b32_e32 v142, 0xffff0000, v144
	v_mul_f32_e32 v172, v122, v126
	v_or_b32_e32 v126, 8, v132
	v_fma_f32 v115, v63, v142, v115
	v_lshlrev_b32_e32 v142, 16, v145
	v_add_f32_e32 v137, 1.0, v137
	v_cvt_pk_bf16_f32 v122, v133, v127
	v_ashrrev_i32_e32 v127, 31, v126
	v_fma_f32 v116, v64, v142, v116
	v_and_b32_e32 v142, 0xffff0000, v145
	v_rcp_f32_e32 v136, v136
	v_rcp_f32_e32 v137, v137
	v_lshlrev_b64 v[132:133], 10, v[126:127]
	v_fmac_f32_e32 v117, v65, v142
	v_add_f32_e32 v142, 1.0, v143
	v_mul_f32_e32 v143, 0x3d372713, v119
	v_mul_f32_e32 v144, 0x3d372713, v120
	v_lshl_add_u64 v[126:127], v[134:135], 0, v[132:133]
	v_mul_f32_e32 v143, v119, v143
	v_mul_f32_e32 v144, v120, v144
	v_lshl_add_u64 v[126:127], v[126:127], 0, s[4:5]
	v_fma_f32 v143, v119, v143, v119
	v_fma_f32 v144, v120, v144, v120
	v_lshl_add_u64 v[126:127], v[126:127], 0, v[154:155]
	v_mul_f32_e32 v143, 0x3fcc422a, v143
	v_mul_f32_e32 v144, 0x3fcc422a, v144
	v_mul_f32_e32 v136, v123, v136
	v_mul_f32_e32 v137, v124, v137
	v_cvt_pk_bf16_f32 v123, v128, v129
	v_cvt_pk_bf16_f32 v124, v172, v136
	v_cvt_pk_bf16_f32 v125, v137, v125
	global_store_dwordx4 v[126:127], v[122:125], off
	v_add_co_u32_e32 v126, vcc, s58, v164
	v_mul_f32_e32 v143, 0xbfb8aa3b, v143
	v_mul_f32_e32 v144, 0xbfb8aa3b, v144
	v_lshl_add_u64 v[122:123], v[164:165], 0, s[22:23]
	v_addc_co_u32_e32 v127, vcc, 0, v165, vcc
	v_exp_f32_e32 v143, v143
	v_exp_f32_e32 v144, v144
	global_load_dwordx4 v[122:125], v[122:123], off offset:256
	s_nop 0
	global_load_dwordx4 v[126:129], v[126:127], off
	v_mul_f32_e32 v145, 0x3d372713, v121
	v_add_f32_e32 v143, 1.0, v143
	v_add_f32_e32 v144, 1.0, v144
	v_rcp_f32_e32 v143, v143
	v_rcp_f32_e32 v144, v144
	v_mul_f32_e32 v145, v121, v145
	v_fma_f32 v145, v121, v145, v121
	v_mul_f32_e32 v145, 0x3fcc422a, v145
	v_mul_f32_e32 v145, 0xbfb8aa3b, v145
	v_rcp_f32_e32 v142, v142
	v_exp_f32_e32 v145, v145
	v_mul_f32_e32 v119, v119, v143
	v_mul_f32_e32 v120, v120, v144
	v_mul_f32_e32 v143, 0x3d372713, v114
	v_mul_f32_e32 v144, 0x3d372713, v115
	v_mul_f32_e32 v143, v114, v143
	v_mul_f32_e32 v144, v115, v144
	v_fma_f32 v143, v114, v143, v114
	v_fma_f32 v144, v115, v144, v115
	v_mul_f32_e32 v143, 0x3fcc422a, v143
	v_mul_f32_e32 v144, 0x3fcc422a, v144
	v_mul_f32_e32 v118, v118, v142
	v_add_f32_e32 v142, 1.0, v145
	v_mul_f32_e32 v143, 0xbfb8aa3b, v143
	v_mul_f32_e32 v144, 0xbfb8aa3b, v144
	v_rcp_f32_e32 v142, v142
	v_exp_f32_e32 v143, v143
	v_exp_f32_e32 v144, v144
	v_mul_f32_e32 v145, 0x3d372713, v117
	v_mul_f32_e32 v121, v121, v142
	v_add_f32_e32 v142, 1.0, v143
	v_add_f32_e32 v143, 1.0, v144
	v_mul_f32_e32 v144, 0x3d372713, v116
	v_mul_f32_e32 v145, v117, v145
	v_mul_f32_e32 v144, v116, v144
	v_fma_f32 v145, v117, v145, v117
	v_fma_f32 v144, v116, v144, v116
	v_mul_f32_e32 v145, 0x3fcc422a, v145
	v_mul_f32_e32 v144, 0x3fcc422a, v144
	v_mul_f32_e32 v145, 0xbfb8aa3b, v145
	v_mul_f32_e32 v144, 0xbfb8aa3b, v144
	v_exp_f32_e32 v145, v145
	v_exp_f32_e32 v144, v144
	v_rcp_f32_e32 v142, v142
	v_or_b32_e32 v136, 16, v162
	v_rcp_f32_e32 v143, v143
	v_ashrrev_i32_e32 v137, 31, v136
	v_add_f32_e32 v145, 1.0, v145
	v_lshlrev_b64 v[136:137], 15, v[136:137]
	v_add_f32_e32 v144, 1.0, v144
	v_rcp_f32_e32 v145, v145
	v_rcp_f32_e32 v144, v144
	v_mul_f32_e32 v142, v114, v142
	v_cvt_pk_bf16_f32 v114, v118, v119
	v_lshl_add_u64 v[118:119], s[14:15], 0, v[136:137]
; __device__ __forceinline__ unsigned cvt_pk_bf16(float lo, float hi) { unsigned r; asm volatile("v_cvt_pk_bf16_f32 %0, %1, %2" : "=v"(r) : "v"(lo), "v"(hi)); return r; }
; __device__ __forceinline__ float sigm(float x) { return __builtin_amdgcn_rcpf(1.f + __expf(-x)); }
; __device__ __forceinline__ float wave_sum(float v) {
; #pragma unroll
;     for (int o = 1; o < 64; o <<= 1) v += __shfl_xor(v, o);
;     return v;
; }
; __device__ __forceinline__ void sincos_rad(float x, float& s, float& c) {
;     double r = (double)x * 0.15915494309189535; r -= __builtin_rint(r); const float fr = (float)r;
;     s = __builtin_amdgcn_sinf(fr); c = __builtin_amdgcn_cosf(fr);
; }
; __device__ __forceinline__ void cpow(float lr, float li, float delta, float j, float& re, float& im) {
;     const float mag = expf(j * delta * lr); float s, c; sincos_rad(j * delta * li, s, c); re = mag * c; im = mag * s;
; }
;     __device__ __forceinline__ void operator()(const pg8::f32x4 (&acc)[2][2][4][2], const Unit& u, int wr, int wc, int fr, int fq) const {
;     ...
;         for (int k = 0; k < 8; ++k) { const int ai = k >> 2, m = k & 3; const int row = row0 + ai * HALF + m * 16; v4u cu[2];
; #pragma unroll
;             for (int bj = 0; bj < 2; ++bj) cu[bj] = nu[bj];
;             if (k < 7) {
; #pragma unroll
;                 for (int bj = 0; bj < 2; ++bj) nu[bj] = *(const v4u*)(UX + ((size_t)u.g * 1024 + row0 + ((k + 1) >> 2) * HALF + ((k + 1) & 3) * 16) * 640 + ((colb + bj * HALF) >> 4) * 16 + c0); }
; #pragma unroll
;             for (int bj = 0; bj < 2; ++bj) { const int tau = (colb + bj * HALF) >> 4;
;                 const v4u uw = cu[bj]; const f32x4 a0 = acc[ai][bj][m][0], a1 = acc[ai][bj][m][1];
;                 float r[8]; r[0] = a0[0] + d0[0] * bflo(uw.x); r[1] = a0[1] + d0[1] * bfhi(uw.x); r[2] = a0[2] + d0[2] * bflo(uw.y); r[3] = a0[3] + d0[3] * bfhi(uw.y);
;                 r[4] = a1[0] + d1[0] * bflo(uw.z); r[5] = a1[1] + d1[1] * bfhi(uw.z); r[6] = a1[2] + d1[2] * bflo(uw.w); r[7] = a1[3] + d1[3] * bfhi(uw.w);
; #pragma unroll
;                 for (int e = 0; e < 8; ++e) r[e] = gelu_tanh(r[e]);
;                 v4u w; w.x = cvt_pk_bf16(r[0], r[1]); w.y = cvt_pk_bf16(r[2], r[3]); w.z = cvt_pk_bf16(r[4], r[5]); w.w = cvt_pk_bf16(r[6], r[7]);
;                 *(v4u*)(Y + ((size_t)row * 32 + tau) * 512 + u.g * 16 + c0) = w; } }
	v_mul_f32_e32 v143, v115, v143
	v_cvt_pk_bf16_f32 v115, v120, v121
	v_lshl_add_u64 v[120:121], v[118:119], 0, v[130:131]
	v_lshl_add_u64 v[120:121], v[120:121], 0, s[4:5]
	v_mul_f32_e32 v117, v117, v145
	v_lshl_add_u64 v[120:121], v[120:121], 0, v[154:155]
	v_mul_f32_e32 v144, v116, v144
	v_cvt_pk_bf16_f32 v116, v142, v143
	v_cvt_pk_bf16_f32 v117, v144, v117
	global_store_dwordx4 v[120:121], v[114:117], off
	s_nop 1
	v_lshlrev_b32_e32 v114, 16, v138
	v_fma_f32 v110, v66, v114, v110
	v_mul_f32_e32 v115, 0x3d372713, v110
	v_mul_f32_e32 v115, v110, v115
	v_and_b32_e32 v114, 0xffff0000, v138
	v_fma_f32 v115, v110, v115, v110
	v_fma_f32 v111, v67, v114, v111
	v_lshlrev_b32_e32 v114, 16, v139
	v_mul_f32_e32 v115, 0x3fcc422a, v115
	v_fma_f32 v112, v68, v114, v112
	v_and_b32_e32 v114, 0xffff0000, v139
	v_mul_f32_e32 v115, 0xbfb8aa3b, v115
	v_fmac_f32_e32 v113, v69, v114
	v_lshlrev_b32_e32 v114, 16, v140
	v_exp_f32_e32 v115, v115
	v_fma_f32 v106, v62, v114, v106
	v_and_b32_e32 v114, 0xffff0000, v140
	v_fma_f32 v107, v63, v114, v107
	v_lshlrev_b32_e32 v114, 16, v141
	v_fma_f32 v108, v64, v114, v108
	v_and_b32_e32 v114, 0xffff0000, v141
	v_fmac_f32_e32 v109, v65, v114
	v_add_f32_e32 v114, 1.0, v115
	v_mul_f32_e32 v115, 0x3d372713, v111
	v_mul_f32_e32 v116, 0x3d372713, v112
	v_mul_f32_e32 v115, v111, v115
	v_mul_f32_e32 v116, v112, v116
	v_fma_f32 v115, v111, v115, v111
	v_fma_f32 v116, v112, v116, v112
	v_mul_f32_e32 v115, 0x3fcc422a, v115
	v_mul_f32_e32 v116, 0x3fcc422a, v116
	v_mul_f32_e32 v115, 0xbfb8aa3b, v115
	v_mul_f32_e32 v116, 0xbfb8aa3b, v116
	v_exp_f32_e32 v115, v115
	v_exp_f32_e32 v116, v116
	v_mul_f32_e32 v117, 0x3d372713, v113
	v_mul_f32_e32 v117, v113, v117
	v_add_f32_e32 v115, 1.0, v115
	v_add_f32_e32 v116, 1.0, v116
	v_rcp_f32_e32 v115, v115
	v_rcp_f32_e32 v116, v116
	v_fma_f32 v117, v113, v117, v113
	v_mul_f32_e32 v117, 0x3fcc422a, v117
	v_mul_f32_e32 v117, 0xbfb8aa3b, v117
	v_rcp_f32_e32 v114, v114
	v_exp_f32_e32 v117, v117
	v_mul_f32_e32 v111, v111, v115
	v_mul_f32_e32 v112, v112, v116
	v_mul_f32_e32 v115, 0x3d372713, v106
	v_mul_f32_e32 v116, 0x3d372713, v107
	v_mul_f32_e32 v115, v106, v115
	v_mul_f32_e32 v116, v107, v116
	v_fma_f32 v115, v106, v115, v106
	v_fma_f32 v116, v107, v116, v107
	v_mul_f32_e32 v115, 0x3fcc422a, v115
	v_mul_f32_e32 v116, 0x3fcc422a, v116
	v_mul_f32_e32 v110, v110, v114
	v_add_f32_e32 v114, 1.0, v117
	v_mul_f32_e32 v115, 0xbfb8aa3b, v115
	v_mul_f32_e32 v116, 0xbfb8aa3b, v116
	v_rcp_f32_e32 v114, v114
	v_exp_f32_e32 v115, v115
	v_exp_f32_e32 v116, v116
	v_mul_f32_e32 v117, 0x3d372713, v109
	v_mul_f32_e32 v113, v113, v114
	v_add_f32_e32 v114, 1.0, v115
	v_add_f32_e32 v115, 1.0, v116
	v_mul_f32_e32 v116, 0x3d372713, v108
	v_mul_f32_e32 v116, v108, v116
	v_mul_f32_e32 v117, v109, v117
	v_fma_f32 v116, v108, v116, v108
	v_fma_f32 v117, v109, v117, v109
	v_mul_f32_e32 v116, 0x3fcc422a, v116
	v_mul_f32_e32 v117, 0x3fcc422a, v117
	v_mul_f32_e32 v116, 0xbfb8aa3b, v116
	v_mul_f32_e32 v117, 0xbfb8aa3b, v117
	v_exp_f32_e32 v116, v116
	v_exp_f32_e32 v117, v117
	v_rcp_f32_e32 v114, v114
	v_rcp_f32_e32 v115, v115
	v_add_f32_e32 v116, 1.0, v116
	v_add_f32_e32 v117, 1.0, v117
	v_rcp_f32_e32 v116, v116
	v_rcp_f32_e32 v117, v117
	v_mul_f32_e32 v114, v106, v114
	v_mul_f32_e32 v115, v107, v115
	v_mul_f32_e32 v116, v108, v116
	v_mul_f32_e32 v109, v109, v117
	v_cvt_pk_bf16_f32 v106, v110, v111
	v_cvt_pk_bf16_f32 v107, v112, v113
	v_cvt_pk_bf16_f32 v108, v114, v115
	v_cvt_pk_bf16_f32 v109, v116, v109
	s_waitcnt vmcnt(1)
	v_lshlrev_b32_e32 v116, 16, v126
	v_fma_f32 v102, v66, v116, v102
	v_mul_f32_e32 v117, 0x3d372713, v102
	v_mul_f32_e32 v117, v102, v117
	v_and_b32_e32 v116, 0xffff0000, v126
	v_fma_f32 v117, v102, v117, v102
	v_fma_f32 v103, v67, v116, v103
	v_lshlrev_b32_e32 v116, 16, v127
	v_mul_f32_e32 v117, 0x3fcc422a, v117
	v_fma_f32 v104, v68, v116, v104
	v_and_b32_e32 v116, 0xffff0000, v127
	v_mul_f32_e32 v117, 0xbfb8aa3b, v117
	v_fmac_f32_e32 v105, v69, v116
	v_lshlrev_b32_e32 v116, 16, v128
	v_exp_f32_e32 v117, v117
	v_fma_f32 v98, v62, v116, v98
	v_and_b32_e32 v116, 0xffff0000, v128
	v_fma_f32 v99, v63, v116, v99
	v_lshlrev_b32_e32 v116, 16, v129
	v_fma_f32 v100, v64, v116, v100
	v_and_b32_e32 v116, 0xffff0000, v129
	v_lshl_add_u64 v[110:111], v[118:119], 0, v[132:133]
	v_fmac_f32_e32 v101, v65, v116
	v_add_f32_e32 v116, 1.0, v117
	v_mul_f32_e32 v117, 0x3d372713, v103
	v_mul_f32_e32 v118, 0x3d372713, v104
	v_mul_f32_e32 v117, v103, v117
	v_mul_f32_e32 v118, v104, v118
	v_lshl_add_u64 v[110:111], v[110:111], 0, s[4:5]
	v_fma_f32 v117, v103, v117, v103
	v_fma_f32 v118, v104, v118, v104
	v_lshl_add_u64 v[110:111], v[110:111], 0, v[154:155]
	v_mul_f32_e32 v117, 0x3fcc422a, v117
	v_mul_f32_e32 v118, 0x3fcc422a, v118
	global_store_dwordx4 v[110:111], v[106:109], off
	v_add_co_u32_e32 v110, vcc, s63, v164
	v_mul_f32_e32 v117, 0xbfb8aa3b, v117
	v_mul_f32_e32 v118, 0xbfb8aa3b, v118
	v_lshl_add_u64 v[106:107], v[164:165], 0, s[24:25]
	v_addc_co_u32_e32 v111, vcc, 0, v165, vcc
	v_exp_f32_e32 v117, v117
	v_exp_f32_e32 v118, v118
	global_load_dwordx4 v[106:109], v[106:107], off offset:256
	s_nop 0
	global_load_dwordx4 v[110:113], v[110:111], off
	v_mul_f32_e32 v119, 0x3d372713, v105
	v_add_f32_e32 v117, 1.0, v117
	v_add_f32_e32 v118, 1.0, v118
	v_rcp_f32_e32 v117, v117
	v_rcp_f32_e32 v118, v118
	v_mul_f32_e32 v119, v105, v119
	v_fma_f32 v119, v105, v119, v105
	v_mul_f32_e32 v119, 0x3fcc422a, v119
	v_mul_f32_e32 v119, 0xbfb8aa3b, v119
	v_rcp_f32_e32 v116, v116
	v_exp_f32_e32 v119, v119
	v_mul_f32_e32 v103, v103, v117
	v_mul_f32_e32 v104, v104, v118
	v_mul_f32_e32 v117, 0x3d372713, v98
	v_mul_f32_e32 v118, 0x3d372713, v99
; __device__ __forceinline__ unsigned cvt_pk_bf16(float lo, float hi) { unsigned r; asm volatile("v_cvt_pk_bf16_f32 %0, %1, %2" : "=v"(r) : "v"(lo), "v"(hi)); return r; }
; __device__ __forceinline__ float sigm(float x) { return __builtin_amdgcn_rcpf(1.f + __expf(-x)); }
; __device__ __forceinline__ float wave_sum(float v) {
; #pragma unroll
;     for (int o = 1; o < 64; o <<= 1) v += __shfl_xor(v, o);
;     return v;
; }
; __device__ __forceinline__ void sincos_rad(float x, float& s, float& c) {
;     double r = (double)x * 0.15915494309189535; r -= __builtin_rint(r); const float fr = (float)r;
;     s = __builtin_amdgcn_sinf(fr); c = __builtin_amdgcn_cosf(fr);
; }
; __device__ __forceinline__ void cpow(float lr, float li, float delta, float j, float& re, float& im) {
;     const float mag = expf(j * delta * lr); float s, c; sincos_rad(j * delta * li, s, c); re = mag * c; im = mag * s;
; }
;     __device__ __forceinline__ void operator()(const pg8::f32x4 (&acc)[2][2][4][2], const Unit& u, int wr, int wc, int fr, int fq) const {
;     ...
;         for (int k = 0; k < 8; ++k) { const int ai = k >> 2, m = k & 3; const int row = row0 + ai * HALF + m * 16; v4u cu[2];
; #pragma unroll
;             for (int bj = 0; bj < 2; ++bj) cu[bj] = nu[bj];
;             if (k < 7) {
; #pragma unroll
;                 for (int bj = 0; bj < 2; ++bj) nu[bj] = *(const v4u*)(UX + ((size_t)u.g * 1024 + row0 + ((k + 1) >> 2) * HALF + ((k + 1) & 3) * 16) * 640 + ((colb + bj * HALF) >> 4) * 16 + c0); }
; #pragma unroll
;             for (int bj = 0; bj < 2; ++bj) { const int tau = (colb + bj * HALF) >> 4;
;                 const v4u uw = cu[bj]; const f32x4 a0 = acc[ai][bj][m][0], a1 = acc[ai][bj][m][1];
;                 float r[8]; r[0] = a0[0] + d0[0] * bflo(uw.x); r[1] = a0[1] + d0[1] * bfhi(uw.x); r[2] = a0[2] + d0[2] * bflo(uw.y); r[3] = a0[3] + d0[3] * bfhi(uw.y);
;                 r[4] = a1[0] + d1[0] * bflo(uw.z); r[5] = a1[1] + d1[1] * bfhi(uw.z); r[6] = a1[2] + d1[2] * bflo(uw.w); r[7] = a1[3] + d1[3] * bfhi(uw.w);
; #pragma unroll
;                 for (int e = 0; e < 8; ++e) r[e] = gelu_tanh(r[e]);
;                 v4u w; w.x = cvt_pk_bf16(r[0], r[1]); w.y = cvt_pk_bf16(r[2], r[3]); w.z = cvt_pk_bf16(r[4], r[5]); w.w = cvt_pk_bf16(r[6], r[7]);
;                 *(v4u*)(Y + ((size_t)row * 32 + tau) * 512 + u.g * 16 + c0) = w; } }
	v_mul_f32_e32 v117, v98, v117
	v_mul_f32_e32 v118, v99, v118
	v_fma_f32 v117, v98, v117, v98
	v_fma_f32 v118, v99, v118, v99
	v_mul_f32_e32 v117, 0x3fcc422a, v117
	v_mul_f32_e32 v118, 0x3fcc422a, v118
	v_mul_f32_e32 v102, v102, v116
	v_add_f32_e32 v116, 1.0, v119
	v_mul_f32_e32 v117, 0xbfb8aa3b, v117
	v_mul_f32_e32 v118, 0xbfb8aa3b, v118
	v_rcp_f32_e32 v116, v116
	v_exp_f32_e32 v117, v117
	v_exp_f32_e32 v118, v118
	v_mul_f32_e32 v119, 0x3d372713, v101
	v_mul_f32_e32 v105, v105, v116
	v_add_f32_e32 v116, 1.0, v117
	v_add_f32_e32 v117, 1.0, v118
	v_mul_f32_e32 v118, 0x3d372713, v100
	v_mul_f32_e32 v119, v101, v119
	v_mul_f32_e32 v118, v100, v118
	v_fma_f32 v119, v101, v119, v101
	v_fma_f32 v118, v100, v118, v100
	v_mul_f32_e32 v119, 0x3fcc422a, v119
	v_mul_f32_e32 v118, 0x3fcc422a, v118
	v_mul_f32_e32 v119, 0xbfb8aa3b, v119
	v_mul_f32_e32 v118, 0xbfb8aa3b, v118
	v_exp_f32_e32 v119, v119
	v_exp_f32_e32 v118, v118
	v_rcp_f32_e32 v116, v116
	v_or_b32_e32 v114, 32, v162
	v_rcp_f32_e32 v117, v117
	v_ashrrev_i32_e32 v115, 31, v114
	v_add_f32_e32 v119, 1.0, v119
	v_lshlrev_b64 v[114:115], 15, v[114:115]
	v_add_f32_e32 v118, 1.0, v118
	v_rcp_f32_e32 v119, v119
	v_rcp_f32_e32 v118, v118
	v_mul_f32_e32 v116, v98, v116
	v_cvt_pk_bf16_f32 v98, v102, v103
	v_lshl_add_u64 v[102:103], s[14:15], 0, v[114:115]
	v_mul_f32_e32 v117, v99, v117
	v_cvt_pk_bf16_f32 v99, v104, v105
	v_lshl_add_u64 v[104:105], v[102:103], 0, v[130:131]
	v_lshl_add_u64 v[104:105], v[104:105], 0, s[4:5]
	v_mul_f32_e32 v101, v101, v119
	v_lshl_add_u64 v[104:105], v[104:105], 0, v[154:155]
	v_mul_f32_e32 v118, v100, v118
	v_cvt_pk_bf16_f32 v100, v116, v117
	v_cvt_pk_bf16_f32 v101, v118, v101
	global_store_dwordx4 v[104:105], v[98:101], off
	s_nop 1
	v_lshlrev_b32_e32 v98, 16, v122
	v_fma_f32 v94, v66, v98, v94
	v_mul_f32_e32 v99, 0x3d372713, v94
	v_mul_f32_e32 v99, v94, v99
	v_and_b32_e32 v98, 0xffff0000, v122
	v_fma_f32 v99, v94, v99, v94
	v_fma_f32 v95, v67, v98, v95
	v_lshlrev_b32_e32 v98, 16, v123
	v_mul_f32_e32 v99, 0x3fcc422a, v99
	v_fma_f32 v96, v68, v98, v96
	v_and_b32_e32 v98, 0xffff0000, v123
	v_mul_f32_e32 v99, 0xbfb8aa3b, v99
	v_fmac_f32_e32 v97, v69, v98
	v_lshlrev_b32_e32 v98, 16, v124
	v_exp_f32_e32 v99, v99
	v_fma_f32 v90, v62, v98, v90
	v_and_b32_e32 v98, 0xffff0000, v124
	v_fma_f32 v91, v63, v98, v91
	v_lshlrev_b32_e32 v98, 16, v125
	v_fma_f32 v92, v64, v98, v92
	v_and_b32_e32 v98, 0xffff0000, v125
	v_fmac_f32_e32 v93, v65, v98
	v_add_f32_e32 v98, 1.0, v99
	v_mul_f32_e32 v99, 0x3d372713, v95
	v_mul_f32_e32 v100, 0x3d372713, v96
	v_mul_f32_e32 v99, v95, v99
	v_mul_f32_e32 v100, v96, v100
	v_fma_f32 v99, v95, v99, v95
	v_fma_f32 v100, v96, v100, v96
	v_mul_f32_e32 v99, 0x3fcc422a, v99
	v_mul_f32_e32 v100, 0x3fcc422a, v100
	v_mul_f32_e32 v99, 0xbfb8aa3b, v99
	v_mul_f32_e32 v100, 0xbfb8aa3b, v100
	v_exp_f32_e32 v99, v99
	v_exp_f32_e32 v100, v100
	v_mul_f32_e32 v101, 0x3d372713, v97
	v_mul_f32_e32 v101, v97, v101
	v_add_f32_e32 v99, 1.0, v99
	v_add_f32_e32 v100, 1.0, v100
	v_rcp_f32_e32 v99, v99
	v_rcp_f32_e32 v100, v100
	v_fma_f32 v101, v97, v101, v97
	v_mul_f32_e32 v101, 0x3fcc422a, v101
	v_mul_f32_e32 v101, 0xbfb8aa3b, v101
	v_rcp_f32_e32 v98, v98
	v_exp_f32_e32 v101, v101
	v_mul_f32_e32 v95, v95, v99
	v_mul_f32_e32 v96, v96, v100
	v_mul_f32_e32 v99, 0x3d372713, v90
	v_mul_f32_e32 v100, 0x3d372713, v91
	v_mul_f32_e32 v99, v90, v99
	v_mul_f32_e32 v100, v91, v100
	v_fma_f32 v99, v90, v99, v90
	v_fma_f32 v100, v91, v100, v91
	v_mul_f32_e32 v99, 0x3fcc422a, v99
	v_mul_f32_e32 v100, 0x3fcc422a, v100
	v_mul_f32_e32 v94, v94, v98
	v_add_f32_e32 v98, 1.0, v101
	v_mul_f32_e32 v99, 0xbfb8aa3b, v99
	v_mul_f32_e32 v100, 0xbfb8aa3b, v100
	v_rcp_f32_e32 v98, v98
	v_exp_f32_e32 v99, v99
	v_exp_f32_e32 v100, v100
	v_mul_f32_e32 v101, 0x3d372713, v93
	v_mul_f32_e32 v97, v97, v98
	v_add_f32_e32 v98, 1.0, v99
	v_add_f32_e32 v99, 1.0, v100
	v_mul_f32_e32 v100, 0x3d372713, v92
	v_mul_f32_e32 v100, v92, v100
	v_mul_f32_e32 v101, v93, v101
	v_fma_f32 v100, v92, v100, v92
	v_fma_f32 v101, v93, v101, v93
	v_mul_f32_e32 v100, 0x3fcc422a, v100
	v_mul_f32_e32 v101, 0x3fcc422a, v101
	v_mul_f32_e32 v100, 0xbfb8aa3b, v100
	v_mul_f32_e32 v101, 0xbfb8aa3b, v101
	v_exp_f32_e32 v100, v100
	v_exp_f32_e32 v101, v101
	v_rcp_f32_e32 v98, v98
	v_rcp_f32_e32 v99, v99
	v_add_f32_e32 v100, 1.0, v100
	v_add_f32_e32 v101, 1.0, v101
	v_rcp_f32_e32 v100, v100
	v_rcp_f32_e32 v101, v101
	v_mul_f32_e32 v98, v90, v98
	v_mul_f32_e32 v99, v91, v99
	v_mul_f32_e32 v100, v92, v100
	v_mul_f32_e32 v93, v93, v101
	v_cvt_pk_bf16_f32 v90, v94, v95
	v_cvt_pk_bf16_f32 v91, v96, v97
	v_cvt_pk_bf16_f32 v92, v98, v99
	v_cvt_pk_bf16_f32 v93, v100, v93
	s_waitcnt vmcnt(1)
; __device__ __forceinline__ unsigned cvt_pk_bf16(float lo, float hi) { unsigned r; asm volatile("v_cvt_pk_bf16_f32 %0, %1, %2" : "=v"(r) : "v"(lo), "v"(hi)); return r; }
; __device__ __forceinline__ float sigm(float x) { return __builtin_amdgcn_rcpf(1.f + __expf(-x)); }
; __device__ __forceinline__ float wave_sum(float v) {
; #pragma unroll
;     for (int o = 1; o < 64; o <<= 1) v += __shfl_xor(v, o);
;     return v;
; }
; __device__ __forceinline__ void sincos_rad(float x, float& s, float& c) {
;     double r = (double)x * 0.15915494309189535; r -= __builtin_rint(r); const float fr = (float)r;
;     s = __builtin_amdgcn_sinf(fr); c = __builtin_amdgcn_cosf(fr);
; }
; __device__ __forceinline__ void cpow(float lr, float li, float delta, float j, float& re, float& im) {
;     const float mag = expf(j * delta * lr); float s, c; sincos_rad(j * delta * li, s, c); re = mag * c; im = mag * s;
; }
;     __device__ __forceinline__ void operator()(const pg8::f32x4 (&acc)[2][2][4][2], const Unit& u, int wr, int wc, int fr, int fq) const {
;     ...
;         for (int k = 0; k < 8; ++k) { const int ai = k >> 2, m = k & 3; const int row = row0 + ai * HALF + m * 16; v4u cu[2];
; #pragma unroll
;             for (int bj = 0; bj < 2; ++bj) cu[bj] = nu[bj];
;             if (k < 7) {
; #pragma unroll
;                 for (int bj = 0; bj < 2; ++bj) nu[bj] = *(const v4u*)(UX + ((size_t)u.g * 1024 + row0 + ((k + 1) >> 2) * HALF + ((k + 1) & 3) * 16) * 640 + ((colb + bj * HALF) >> 4) * 16 + c0); }
; #pragma unroll
;             for (int bj = 0; bj < 2; ++bj) { const int tau = (colb + bj * HALF) >> 4;
;                 const v4u uw = cu[bj]; const f32x4 a0 = acc[ai][bj][m][0], a1 = acc[ai][bj][m][1];
;                 float r[8]; r[0] = a0[0] + d0[0] * bflo(uw.x); r[1] = a0[1] + d0[1] * bfhi(uw.x); r[2] = a0[2] + d0[2] * bflo(uw.y); r[3] = a0[3] + d0[3] * bfhi(uw.y);
;                 r[4] = a1[0] + d1[0] * bflo(uw.z); r[5] = a1[1] + d1[1] * bfhi(uw.z); r[6] = a1[2] + d1[2] * bflo(uw.w); r[7] = a1[3] + d1[3] * bfhi(uw.w);
; #pragma unroll
;                 for (int e = 0; e < 8; ++e) r[e] = gelu_tanh(r[e]);
;                 v4u w; w.x = cvt_pk_bf16(r[0], r[1]); w.y = cvt_pk_bf16(r[2], r[3]); w.z = cvt_pk_bf16(r[4], r[5]); w.w = cvt_pk_bf16(r[6], r[7]);
;                 *(v4u*)(Y + ((size_t)row * 32 + tau) * 512 + u.g * 16 + c0) = w; } }
	v_lshlrev_b32_e32 v100, 16, v110
	v_fma_f32 v86, v66, v100, v86
	v_mul_f32_e32 v101, 0x3d372713, v86
	v_mul_f32_e32 v101, v86, v101
	v_and_b32_e32 v100, 0xffff0000, v110
	v_fma_f32 v101, v86, v101, v86
	v_fma_f32 v87, v67, v100, v87
	v_lshlrev_b32_e32 v100, 16, v111
	v_mul_f32_e32 v101, 0x3fcc422a, v101
	v_fma_f32 v88, v68, v100, v88
	v_and_b32_e32 v100, 0xffff0000, v111
	v_mul_f32_e32 v101, 0xbfb8aa3b, v101
	v_fmac_f32_e32 v89, v69, v100
	v_lshlrev_b32_e32 v100, 16, v112
	v_exp_f32_e32 v101, v101
	v_fma_f32 v82, v62, v100, v82
	v_and_b32_e32 v100, 0xffff0000, v112
	v_fma_f32 v83, v63, v100, v83
	v_lshlrev_b32_e32 v100, 16, v113
	v_fma_f32 v84, v64, v100, v84
	v_and_b32_e32 v100, 0xffff0000, v113
	v_lshl_add_u64 v[94:95], v[102:103], 0, v[132:133]
	v_fmac_f32_e32 v85, v65, v100
	v_add_f32_e32 v100, 1.0, v101
	v_mul_f32_e32 v101, 0x3d372713, v87
	v_mul_f32_e32 v102, 0x3d372713, v88
	v_lshl_add_u64 v[94:95], v[94:95], 0, s[4:5]
	v_mul_f32_e32 v101, v87, v101
	v_mul_f32_e32 v102, v88, v102
	v_lshl_add_u64 v[94:95], v[94:95], 0, v[154:155]
	v_fma_f32 v101, v87, v101, v87
	v_fma_f32 v102, v88, v102, v88
	global_store_dwordx4 v[94:95], v[90:93], off
	v_add_co_u32_e32 v94, vcc, s64, v164
	v_mul_f32_e32 v101, 0x3fcc422a, v101
	v_mul_f32_e32 v102, 0x3fcc422a, v102
	v_lshl_add_u64 v[90:91], v[164:165], 0, s[10:11]
	v_addc_co_u32_e32 v95, vcc, 0, v165, vcc
	v_mul_f32_e32 v101, 0xbfb8aa3b, v101
	v_mul_f32_e32 v102, 0xbfb8aa3b, v102
	global_load_dwordx4 v[90:93], v[90:91], off offset:256
	s_nop 0
	global_load_dwordx4 v[94:97], v[94:95], off
	v_exp_f32_e32 v101, v101
	v_exp_f32_e32 v102, v102
	v_mul_f32_e32 v103, 0x3d372713, v89
	v_mul_f32_e32 v103, v89, v103
	v_add_f32_e32 v101, 1.0, v101
	v_add_f32_e32 v102, 1.0, v102
	v_rcp_f32_e32 v101, v101
	v_rcp_f32_e32 v102, v102
	v_fma_f32 v103, v89, v103, v89
	v_mul_f32_e32 v103, 0x3fcc422a, v103
	v_mul_f32_e32 v103, 0xbfb8aa3b, v103
	v_rcp_f32_e32 v100, v100
	v_exp_f32_e32 v103, v103
	v_mul_f32_e32 v87, v87, v101
	v_mul_f32_e32 v88, v88, v102
	v_mul_f32_e32 v101, 0x3d372713, v82
	v_mul_f32_e32 v102, 0x3d372713, v83
	v_mul_f32_e32 v101, v82, v101
	v_mul_f32_e32 v102, v83, v102
	v_fma_f32 v101, v82, v101, v82
	v_fma_f32 v102, v83, v102, v83
	v_mul_f32_e32 v101, 0x3fcc422a, v101
	v_mul_f32_e32 v102, 0x3fcc422a, v102
	v_mul_f32_e32 v86, v86, v100
	v_add_f32_e32 v100, 1.0, v103
	v_mul_f32_e32 v101, 0xbfb8aa3b, v101
	v_mul_f32_e32 v102, 0xbfb8aa3b, v102
	v_rcp_f32_e32 v100, v100
	v_exp_f32_e32 v101, v101
	v_exp_f32_e32 v102, v102
	v_mul_f32_e32 v103, 0x3d372713, v85
	v_mul_f32_e32 v89, v89, v100
	v_add_f32_e32 v100, 1.0, v101
	v_add_f32_e32 v101, 1.0, v102
	v_mul_f32_e32 v102, 0x3d372713, v84
	v_mul_f32_e32 v103, v85, v103
	v_mul_f32_e32 v102, v84, v102
	v_fma_f32 v103, v85, v103, v85
	v_fma_f32 v102, v84, v102, v84
	v_mul_f32_e32 v103, 0x3fcc422a, v103
	v_mul_f32_e32 v102, 0x3fcc422a, v102
	v_mul_f32_e32 v103, 0xbfb8aa3b, v103
	v_mul_f32_e32 v102, 0xbfb8aa3b, v102
	v_exp_f32_e32 v103, v103
	v_exp_f32_e32 v102, v102
	v_rcp_f32_e32 v100, v100
	v_or_b32_e32 v98, 48, v162
	v_rcp_f32_e32 v101, v101
	v_ashrrev_i32_e32 v99, 31, v98
	v_add_f32_e32 v103, 1.0, v103
	v_lshlrev_b64 v[98:99], 15, v[98:99]
	v_add_f32_e32 v102, 1.0, v102
	v_rcp_f32_e32 v103, v103
	v_rcp_f32_e32 v102, v102
	v_mul_f32_e32 v100, v82, v100
	v_cvt_pk_bf16_f32 v82, v86, v87
	v_lshl_add_u64 v[86:87], s[14:15], 0, v[98:99]
	v_mul_f32_e32 v101, v83, v101
	v_cvt_pk_bf16_f32 v83, v88, v89
	v_lshl_add_u64 v[88:89], v[86:87], 0, v[130:131]
	v_lshl_add_u64 v[88:89], v[88:89], 0, s[4:5]
	v_mul_f32_e32 v85, v85, v103
	v_lshl_add_u64 v[88:89], v[88:89], 0, v[154:155]
	v_mul_f32_e32 v102, v84, v102
	v_cvt_pk_bf16_f32 v84, v100, v101
	v_cvt_pk_bf16_f32 v85, v102, v85
	global_store_dwordx4 v[88:89], v[82:85], off
	s_nop 1
	v_lshlrev_b32_e32 v82, 16, v106
	v_fma_f32 v78, v66, v82, v78
	v_mul_f32_e32 v83, 0x3d372713, v78
	v_mul_f32_e32 v83, v78, v83
	v_and_b32_e32 v82, 0xffff0000, v106
	v_fma_f32 v83, v78, v83, v78
	v_fma_f32 v79, v67, v82, v79
	v_lshlrev_b32_e32 v82, 16, v107
	v_mul_f32_e32 v83, 0x3fcc422a, v83
	v_fma_f32 v80, v68, v82, v80
	v_and_b32_e32 v82, 0xffff0000, v107
	v_mul_f32_e32 v83, 0xbfb8aa3b, v83
	v_fmac_f32_e32 v81, v69, v82
	v_lshlrev_b32_e32 v82, 16, v108
	v_exp_f32_e32 v83, v83
	v_fma_f32 v74, v62, v82, v74
	v_and_b32_e32 v82, 0xffff0000, v108
	v_fma_f32 v75, v63, v82, v75
	v_lshlrev_b32_e32 v82, 16, v109
	v_fma_f32 v76, v64, v82, v76
	v_and_b32_e32 v82, 0xffff0000, v109
	v_fmac_f32_e32 v77, v65, v82
	v_add_f32_e32 v82, 1.0, v83
	v_mul_f32_e32 v83, 0x3d372713, v79
	v_mul_f32_e32 v84, 0x3d372713, v80
	v_mul_f32_e32 v83, v79, v83
	v_mul_f32_e32 v84, v80, v84
	v_fma_f32 v83, v79, v83, v79
	v_fma_f32 v84, v80, v84, v80
	v_mul_f32_e32 v83, 0x3fcc422a, v83
	v_mul_f32_e32 v84, 0x3fcc422a, v84
	v_mul_f32_e32 v83, 0xbfb8aa3b, v83
	v_mul_f32_e32 v84, 0xbfb8aa3b, v84
	v_exp_f32_e32 v83, v83
	v_exp_f32_e32 v84, v84
	v_mul_f32_e32 v85, 0x3d372713, v81
	v_mul_f32_e32 v85, v81, v85
	v_add_f32_e32 v83, 1.0, v83
	v_add_f32_e32 v84, 1.0, v84
	v_rcp_f32_e32 v83, v83
	v_rcp_f32_e32 v84, v84
	v_fma_f32 v85, v81, v85, v81
	v_mul_f32_e32 v85, 0x3fcc422a, v85
	v_mul_f32_e32 v85, 0xbfb8aa3b, v85
	v_rcp_f32_e32 v82, v82
	v_exp_f32_e32 v85, v85
	v_mul_f32_e32 v79, v79, v83
	v_mul_f32_e32 v80, v80, v84
	v_mul_f32_e32 v83, 0x3d372713, v74
	v_mul_f32_e32 v84, 0x3d372713, v75
	v_mul_f32_e32 v83, v74, v83
	v_mul_f32_e32 v84, v75, v84
	v_fma_f32 v83, v74, v83, v74
	v_fma_f32 v84, v75, v84, v75
	v_mul_f32_e32 v83, 0x3fcc422a, v83
	v_mul_f32_e32 v84, 0x3fcc422a, v84
	v_mul_f32_e32 v78, v78, v82
	v_add_f32_e32 v82, 1.0, v85
	v_mul_f32_e32 v83, 0xbfb8aa3b, v83
	v_mul_f32_e32 v84, 0xbfb8aa3b, v84
	v_rcp_f32_e32 v82, v82
	v_exp_f32_e32 v83, v83
	v_exp_f32_e32 v84, v84
	v_mul_f32_e32 v85, 0x3d372713, v77
	v_mul_f32_e32 v81, v81, v82
	v_add_f32_e32 v82, 1.0, v83
	v_add_f32_e32 v83, 1.0, v84
	v_mul_f32_e32 v84, 0x3d372713, v76
	v_mul_f32_e32 v84, v76, v84
	v_fma_f32 v84, v76, v84, v76
	v_mul_f32_e32 v84, 0x3fcc422a, v84
	v_mul_f32_e32 v84, 0xbfb8aa3b, v84
	v_exp_f32_e32 v84, v84
	v_rcp_f32_e32 v82, v82
	v_rcp_f32_e32 v83, v83
	v_mul_f32_e32 v85, v77, v85
	v_add_f32_e32 v84, 1.0, v84
	v_rcp_f32_e32 v84, v84
	v_fma_f32 v85, v77, v85, v77
	v_mul_f32_e32 v85, 0x3fcc422a, v85
	v_mul_f32_e32 v82, v74, v82
	v_mul_f32_e32 v85, 0xbfb8aa3b, v85
	v_mul_f32_e32 v83, v75, v83
	v_mul_f32_e32 v84, v76, v84
	v_cvt_pk_bf16_f32 v74, v78, v79
	v_cvt_pk_bf16_f32 v75, v80, v81
	v_cvt_pk_bf16_f32 v76, v82, v83
	s_waitcnt vmcnt(1)
; __device__ __forceinline__ unsigned cvt_pk_bf16(float lo, float hi) { unsigned r; asm volatile("v_cvt_pk_bf16_f32 %0, %1, %2" : "=v"(r) : "v"(lo), "v"(hi)); return r; }
; __device__ __forceinline__ float sigm(float x) { return __builtin_amdgcn_rcpf(1.f + __expf(-x)); }
; __device__ __forceinline__ float wave_sum(float v) {
; #pragma unroll
;     for (int o = 1; o < 64; o <<= 1) v += __shfl_xor(v, o);
;     return v;
; }
; __device__ __forceinline__ void sincos_rad(float x, float& s, float& c) {
;     double r = (double)x * 0.15915494309189535; r -= __builtin_rint(r); const float fr = (float)r;
;     s = __builtin_amdgcn_sinf(fr); c = __builtin_amdgcn_cosf(fr);
; }
; __device__ __forceinline__ void cpow(float lr, float li, float delta, float j, float& re, float& im) {
;     const float mag = expf(j * delta * lr); float s, c; sincos_rad(j * delta * li, s, c); re = mag * c; im = mag * s;
; }
;     __device__ __forceinline__ void operator()(const pg8::f32x4 (&acc)[2][2][4][2], const Unit& u, int wr, int wc, int fr, int fq) const {
;     ...
;         for (int k = 0; k < 8; ++k) { const int ai = k >> 2, m = k & 3; const int row = row0 + ai * HALF + m * 16; v4u cu[2];
; #pragma unroll
;             for (int bj = 0; bj < 2; ++bj) cu[bj] = nu[bj];
;             if (k < 7) {
; #pragma unroll
;                 for (int bj = 0; bj < 2; ++bj) nu[bj] = *(const v4u*)(UX + ((size_t)u.g * 1024 + row0 + ((k + 1) >> 2) * HALF + ((k + 1) & 3) * 16) * 640 + ((colb + bj * HALF) >> 4) * 16 + c0); }
; #pragma unroll
;             for (int bj = 0; bj < 2; ++bj) { const int tau = (colb + bj * HALF) >> 4;
;                 const v4u uw = cu[bj]; const f32x4 a0 = acc[ai][bj][m][0], a1 = acc[ai][bj][m][1];
;                 float r[8]; r[0] = a0[0] + d0[0] * bflo(uw.x); r[1] = a0[1] + d0[1] * bfhi(uw.x); r[2] = a0[2] + d0[2] * bflo(uw.y); r[3] = a0[3] + d0[3] * bfhi(uw.y);
;                 r[4] = a1[0] + d1[0] * bflo(uw.z); r[5] = a1[1] + d1[1] * bfhi(uw.z); r[6] = a1[2] + d1[2] * bflo(uw.w); r[7] = a1[3] + d1[3] * bfhi(uw.w);
; #pragma unroll
;                 for (int e = 0; e < 8; ++e) r[e] = gelu_tanh(r[e]);
;                 v4u w; w.x = cvt_pk_bf16(r[0], r[1]); w.y = cvt_pk_bf16(r[2], r[3]); w.z = cvt_pk_bf16(r[4], r[5]); w.w = cvt_pk_bf16(r[6], r[7]);
;                 *(v4u*)(Y + ((size_t)row * 32 + tau) * 512 + u.g * 16 + c0) = w; } }
	v_lshlrev_b32_e32 v82, 16, v94
	v_exp_f32_e32 v85, v85
	v_fma_f32 v70, v66, v82, v70
	v_mul_f32_e32 v83, 0x3d372713, v70
	v_mul_f32_e32 v83, v70, v83
	v_and_b32_e32 v82, 0xffff0000, v94
	v_fma_f32 v83, v70, v83, v70
	v_add_f32_e32 v85, 1.0, v85
	v_fma_f32 v71, v67, v82, v71
	v_lshlrev_b32_e32 v82, 16, v95
	v_mul_f32_e32 v83, 0x3fcc422a, v83
	v_rcp_f32_e32 v85, v85
	v_fma_f32 v72, v68, v82, v72
	v_and_b32_e32 v82, 0xffff0000, v95
	v_mul_f32_e32 v83, 0xbfb8aa3b, v83
	v_fmac_f32_e32 v73, v69, v82
	v_lshlrev_b32_e32 v82, 16, v96
	v_exp_f32_e32 v83, v83
	v_fma_f32 v58, v62, v82, v58
	v_and_b32_e32 v82, 0xffff0000, v96
	v_fma_f32 v59, v63, v82, v59
	v_lshlrev_b32_e32 v82, 16, v97
	v_mul_f32_e32 v77, v77, v85
	v_fma_f32 v60, v64, v82, v60
	v_and_b32_e32 v82, 0xffff0000, v97
	v_cvt_pk_bf16_f32 v77, v84, v77
	v_fmac_f32_e32 v61, v65, v82
	v_add_f32_e32 v82, 1.0, v83
	v_mul_f32_e32 v83, 0x3d372713, v71
	v_mul_f32_e32 v84, 0x3d372713, v72
	v_lshl_add_u64 v[78:79], v[86:87], 0, v[132:133]
	v_mul_f32_e32 v83, v71, v83
	v_mul_f32_e32 v84, v72, v84
	v_lshl_add_u64 v[78:79], v[78:79], 0, s[4:5]
	v_fma_f32 v83, v71, v83, v71
	v_fma_f32 v84, v72, v84, v72
	v_lshl_add_u64 v[78:79], v[78:79], 0, v[154:155]
	v_mul_f32_e32 v83, 0x3fcc422a, v83
	v_mul_f32_e32 v84, 0x3fcc422a, v84
	global_store_dwordx4 v[78:79], v[74:77], off
	v_add_co_u32_e32 v78, vcc, s65, v164
	v_mul_f32_e32 v83, 0xbfb8aa3b, v83
	v_mul_f32_e32 v84, 0xbfb8aa3b, v84
	v_lshl_add_u64 v[74:75], v[164:165], 0, s[26:27]
	v_addc_co_u32_e32 v79, vcc, 0, v165, vcc
	v_exp_f32_e32 v83, v83
	v_exp_f32_e32 v84, v84
	global_load_dwordx4 v[74:77], v[74:75], off offset:256
	s_nop 0
	global_load_dwordx4 v[78:81], v[78:79], off
	v_mul_f32_e32 v85, 0x3d372713, v73
	v_add_f32_e32 v83, 1.0, v83
	v_add_f32_e32 v84, 1.0, v84
	v_rcp_f32_e32 v83, v83
	v_rcp_f32_e32 v84, v84
	v_mul_f32_e32 v85, v73, v85
	v_fma_f32 v85, v73, v85, v73
	v_mul_f32_e32 v85, 0x3fcc422a, v85
	v_mul_f32_e32 v85, 0xbfb8aa3b, v85
	v_rcp_f32_e32 v82, v82
	v_exp_f32_e32 v85, v85
	v_mul_f32_e32 v71, v71, v83
	v_mul_f32_e32 v72, v72, v84
	v_mul_f32_e32 v83, 0x3d372713, v58
	v_mul_f32_e32 v84, 0x3d372713, v59
	v_mul_f32_e32 v83, v58, v83
	v_mul_f32_e32 v84, v59, v84
	v_fma_f32 v83, v58, v83, v58
	v_fma_f32 v84, v59, v84, v59
	v_mul_f32_e32 v83, 0x3fcc422a, v83
	v_mul_f32_e32 v84, 0x3fcc422a, v84
	v_mul_f32_e32 v70, v70, v82
	v_add_f32_e32 v82, 1.0, v85
	v_mul_f32_e32 v83, 0xbfb8aa3b, v83
	v_mul_f32_e32 v84, 0xbfb8aa3b, v84
	v_rcp_f32_e32 v82, v82
	v_exp_f32_e32 v83, v83
	v_exp_f32_e32 v84, v84
	v_mul_f32_e32 v85, 0x3d372713, v61
	v_mul_f32_e32 v73, v73, v82
	v_add_f32_e32 v82, 1.0, v83
	v_add_f32_e32 v83, 1.0, v84
	v_mul_f32_e32 v84, 0x3d372713, v60
	v_mul_f32_e32 v85, v61, v85
	v_mul_f32_e32 v84, v60, v84
	v_fma_f32 v85, v61, v85, v61
	v_fma_f32 v84, v60, v84, v60
	v_mul_f32_e32 v85, 0x3fcc422a, v85
	v_mul_f32_e32 v84, 0x3fcc422a, v84
	v_mul_f32_e32 v85, 0xbfb8aa3b, v85
	v_mul_f32_e32 v84, 0xbfb8aa3b, v84
	v_exp_f32_e32 v85, v85
	v_exp_f32_e32 v84, v84
	v_rcp_f32_e32 v82, v82
	v_rcp_f32_e32 v83, v83
	v_add_f32_e32 v85, 1.0, v85
	v_add_f32_e32 v84, 1.0, v84
	v_rcp_f32_e32 v85, v85
	v_rcp_f32_e32 v84, v84
	v_mul_f32_e32 v82, v58, v82
	v_cvt_pk_bf16_f32 v58, v70, v71
	v_lshl_add_u64 v[70:71], v[134:135], 0, s[28:29]
	v_mul_f32_e32 v83, v59, v83
	v_cvt_pk_bf16_f32 v59, v72, v73
	v_lshl_add_u64 v[72:73], v[70:71], 0, v[130:131]
	v_lshl_add_u64 v[72:73], v[72:73], 0, s[4:5]
	v_mul_f32_e32 v61, v61, v85
	v_lshl_add_u64 v[72:73], v[72:73], 0, v[154:155]
	v_mul_f32_e32 v84, v60, v84
	v_cvt_pk_bf16_f32 v60, v82, v83
	v_cvt_pk_bf16_f32 v61, v84, v61
	global_store_dwordx4 v[72:73], v[58:61], off
	s_nop 1
	v_lshlrev_b32_e32 v58, 16, v90
	v_fma_f32 v54, v66, v58, v54
	v_mul_f32_e32 v59, 0x3d372713, v54
	v_mul_f32_e32 v59, v54, v59
	v_and_b32_e32 v58, 0xffff0000, v90
	v_fma_f32 v59, v54, v59, v54
	v_fma_f32 v55, v67, v58, v55
	v_lshlrev_b32_e32 v58, 16, v91
	v_mul_f32_e32 v59, 0x3fcc422a, v59
	v_fma_f32 v56, v68, v58, v56
	v_and_b32_e32 v58, 0xffff0000, v91
	v_mul_f32_e32 v59, 0xbfb8aa3b, v59
	v_fmac_f32_e32 v57, v69, v58
	v_lshlrev_b32_e32 v58, 16, v92
	v_exp_f32_e32 v59, v59
	v_fma_f32 v50, v62, v58, v50
	v_and_b32_e32 v58, 0xffff0000, v92
	v_fma_f32 v51, v63, v58, v51
	v_lshlrev_b32_e32 v58, 16, v93
	v_fma_f32 v52, v64, v58, v52
	v_and_b32_e32 v58, 0xffff0000, v93
	v_fmac_f32_e32 v53, v65, v58
	v_add_f32_e32 v58, 1.0, v59
	v_mul_f32_e32 v59, 0x3d372713, v55
	v_mul_f32_e32 v60, 0x3d372713, v56
	v_mul_f32_e32 v59, v55, v59
	v_mul_f32_e32 v60, v56, v60
	v_fma_f32 v59, v55, v59, v55
	v_fma_f32 v60, v56, v60, v56
	v_mul_f32_e32 v59, 0x3fcc422a, v59
	v_mul_f32_e32 v60, 0x3fcc422a, v60
	v_mul_f32_e32 v59, 0xbfb8aa3b, v59
	v_mul_f32_e32 v60, 0xbfb8aa3b, v60
	v_exp_f32_e32 v59, v59
	v_exp_f32_e32 v60, v60
	v_mul_f32_e32 v61, 0x3d372713, v57
	v_mul_f32_e32 v61, v57, v61
	v_add_f32_e32 v59, 1.0, v59
	v_add_f32_e32 v60, 1.0, v60
	v_rcp_f32_e32 v59, v59
	v_rcp_f32_e32 v60, v60
	v_fma_f32 v61, v57, v61, v57
	v_mul_f32_e32 v61, 0x3fcc422a, v61
	v_mul_f32_e32 v61, 0xbfb8aa3b, v61
	v_rcp_f32_e32 v58, v58
	v_exp_f32_e32 v61, v61
	v_mul_f32_e32 v55, v55, v59
	v_mul_f32_e32 v56, v56, v60
	v_mul_f32_e32 v59, 0x3d372713, v50
	v_mul_f32_e32 v60, 0x3d372713, v51
	v_mul_f32_e32 v59, v50, v59
	v_mul_f32_e32 v60, v51, v60
	v_fma_f32 v59, v50, v59, v50
	v_fma_f32 v60, v51, v60, v51
	v_mul_f32_e32 v59, 0x3fcc422a, v59
	v_mul_f32_e32 v60, 0x3fcc422a, v60
	v_mul_f32_e32 v54, v54, v58
	v_add_f32_e32 v58, 1.0, v61
	v_mul_f32_e32 v59, 0xbfb8aa3b, v59
	v_mul_f32_e32 v60, 0xbfb8aa3b, v60
	v_rcp_f32_e32 v58, v58
	v_exp_f32_e32 v59, v59
	v_exp_f32_e32 v60, v60
	v_mul_f32_e32 v61, 0x3d372713, v53
	v_mul_f32_e32 v57, v57, v58
	v_add_f32_e32 v58, 1.0, v59
	v_add_f32_e32 v59, 1.0, v60
	v_mul_f32_e32 v60, 0x3d372713, v52
	v_mul_f32_e32 v60, v52, v60
	v_mul_f32_e32 v61, v53, v61
	v_fma_f32 v60, v52, v60, v52
	v_fma_f32 v61, v53, v61, v53
	v_mul_f32_e32 v60, 0x3fcc422a, v60
	v_mul_f32_e32 v61, 0x3fcc422a, v61
	v_mul_f32_e32 v60, 0xbfb8aa3b, v60
	v_mul_f32_e32 v61, 0xbfb8aa3b, v61
	v_exp_f32_e32 v60, v60
	v_exp_f32_e32 v61, v61
	v_rcp_f32_e32 v58, v58
	v_rcp_f32_e32 v59, v59
	v_add_f32_e32 v60, 1.0, v60
	v_add_f32_e32 v61, 1.0, v61
	v_rcp_f32_e32 v60, v60
	v_rcp_f32_e32 v61, v61
	v_mul_f32_e32 v58, v50, v58
	v_mul_f32_e32 v59, v51, v59
	v_mul_f32_e32 v60, v52, v60
	v_mul_f32_e32 v53, v53, v61
	v_cvt_pk_bf16_f32 v50, v54, v55
	v_cvt_pk_bf16_f32 v51, v56, v57
	v_cvt_pk_bf16_f32 v52, v58, v59
	v_cvt_pk_bf16_f32 v53, v60, v53
	s_waitcnt vmcnt(1)
; __device__ __forceinline__ unsigned cvt_pk_bf16(float lo, float hi) { unsigned r; asm volatile("v_cvt_pk_bf16_f32 %0, %1, %2" : "=v"(r) : "v"(lo), "v"(hi)); return r; }
; __device__ __forceinline__ float sigm(float x) { return __builtin_amdgcn_rcpf(1.f + __expf(-x)); }
; __device__ __forceinline__ float wave_sum(float v) {
; #pragma unroll
;     for (int o = 1; o < 64; o <<= 1) v += __shfl_xor(v, o);
;     return v;
; }
; __device__ __forceinline__ void sincos_rad(float x, float& s, float& c) {
;     double r = (double)x * 0.15915494309189535; r -= __builtin_rint(r); const float fr = (float)r;
;     s = __builtin_amdgcn_sinf(fr); c = __builtin_amdgcn_cosf(fr);
; }
; __device__ __forceinline__ void cpow(float lr, float li, float delta, float j, float& re, float& im) {
;     const float mag = expf(j * delta * lr); float s, c; sincos_rad(j * delta * li, s, c); re = mag * c; im = mag * s;
; }
;     __device__ __forceinline__ void operator()(const pg8::f32x4 (&acc)[2][2][4][2], const Unit& u, int wr, int wc, int fr, int fq) const {
;     ...
;         for (int k = 0; k < 8; ++k) { const int ai = k >> 2, m = k & 3; const int row = row0 + ai * HALF + m * 16; v4u cu[2];
; #pragma unroll
;             for (int bj = 0; bj < 2; ++bj) cu[bj] = nu[bj];
;             if (k < 7) {
; #pragma unroll
;                 for (int bj = 0; bj < 2; ++bj) nu[bj] = *(const v4u*)(UX + ((size_t)u.g * 1024 + row0 + ((k + 1) >> 2) * HALF + ((k + 1) & 3) * 16) * 640 + ((colb + bj * HALF) >> 4) * 16 + c0); }
; #pragma unroll
;             for (int bj = 0; bj < 2; ++bj) { const int tau = (colb + bj * HALF) >> 4;
;                 const v4u uw = cu[bj]; const f32x4 a0 = acc[ai][bj][m][0], a1 = acc[ai][bj][m][1];
;                 float r[8]; r[0] = a0[0] + d0[0] * bflo(uw.x); r[1] = a0[1] + d0[1] * bfhi(uw.x); r[2] = a0[2] + d0[2] * bflo(uw.y); r[3] = a0[3] + d0[3] * bfhi(uw.y);
;                 r[4] = a1[0] + d1[0] * bflo(uw.z); r[5] = a1[1] + d1[1] * bfhi(uw.z); r[6] = a1[2] + d1[2] * bflo(uw.w); r[7] = a1[3] + d1[3] * bfhi(uw.w);
; #pragma unroll
;                 for (int e = 0; e < 8; ++e) r[e] = gelu_tanh(r[e]);
;                 v4u w; w.x = cvt_pk_bf16(r[0], r[1]); w.y = cvt_pk_bf16(r[2], r[3]); w.z = cvt_pk_bf16(r[4], r[5]); w.w = cvt_pk_bf16(r[6], r[7]);
;                 *(v4u*)(Y + ((size_t)row * 32 + tau) * 512 + u.g * 16 + c0) = w; } }
	v_lshlrev_b32_e32 v60, 16, v78
	v_fma_f32 v46, v66, v60, v46
	v_mul_f32_e32 v61, 0x3d372713, v46
	v_mul_f32_e32 v61, v46, v61
	v_and_b32_e32 v60, 0xffff0000, v78
	v_fma_f32 v61, v46, v61, v46
	v_fma_f32 v47, v67, v60, v47
	v_lshlrev_b32_e32 v60, 16, v79
	v_mul_f32_e32 v61, 0x3fcc422a, v61
	v_fma_f32 v48, v68, v60, v48
	v_and_b32_e32 v60, 0xffff0000, v79
	v_mul_f32_e32 v61, 0xbfb8aa3b, v61
	v_fmac_f32_e32 v49, v69, v60
	v_lshlrev_b32_e32 v60, 16, v80
	v_exp_f32_e32 v61, v61
	v_fma_f32 v42, v62, v60, v42
	v_and_b32_e32 v60, 0xffff0000, v80
	v_fma_f32 v43, v63, v60, v43
	v_lshlrev_b32_e32 v60, 16, v81
	v_fma_f32 v44, v64, v60, v44
	v_and_b32_e32 v60, 0xffff0000, v81
	v_lshl_add_u64 v[54:55], v[70:71], 0, v[132:133]
	v_fmac_f32_e32 v45, v65, v60
	v_add_f32_e32 v60, 1.0, v61
	v_mul_f32_e32 v61, 0x3d372713, v47
	v_mul_f32_e32 v70, 0x3d372713, v48
	v_mul_f32_e32 v61, v47, v61
	v_mul_f32_e32 v70, v48, v70
	v_lshl_add_u64 v[54:55], v[54:55], 0, s[4:5]
	v_fma_f32 v61, v47, v61, v47
	v_fma_f32 v70, v48, v70, v48
	v_lshl_add_u64 v[54:55], v[54:55], 0, v[154:155]
	v_mul_f32_e32 v61, 0x3fcc422a, v61
	v_mul_f32_e32 v70, 0x3fcc422a, v70
	global_store_dwordx4 v[54:55], v[50:53], off
	v_add_co_u32_e32 v54, vcc, s66, v164
	v_mul_f32_e32 v61, 0xbfb8aa3b, v61
	v_mul_f32_e32 v70, 0xbfb8aa3b, v70
	v_lshl_add_u64 v[50:51], v[164:165], 0, s[30:31]
	v_addc_co_u32_e32 v55, vcc, 0, v165, vcc
	v_exp_f32_e32 v61, v61
	v_exp_f32_e32 v70, v70
	global_load_dwordx4 v[50:53], v[50:51], off offset:256
	s_nop 0
	global_load_dwordx4 v[54:57], v[54:55], off
	v_mul_f32_e32 v71, 0x3d372713, v49
	v_add_f32_e32 v61, 1.0, v61
	v_add_f32_e32 v70, 1.0, v70
	v_rcp_f32_e32 v61, v61
	v_rcp_f32_e32 v70, v70
	v_mul_f32_e32 v71, v49, v71
	v_fma_f32 v71, v49, v71, v49
	v_mul_f32_e32 v71, 0x3fcc422a, v71
	v_mul_f32_e32 v71, 0xbfb8aa3b, v71
	v_rcp_f32_e32 v60, v60
	v_exp_f32_e32 v71, v71
	v_mul_f32_e32 v47, v47, v61
	v_mul_f32_e32 v48, v48, v70
	v_mul_f32_e32 v61, 0x3d372713, v42
	v_mul_f32_e32 v70, 0x3d372713, v43
	v_mul_f32_e32 v61, v42, v61
	v_mul_f32_e32 v70, v43, v70
	v_fma_f32 v61, v42, v61, v42
	v_fma_f32 v70, v43, v70, v43
	v_mul_f32_e32 v61, 0x3fcc422a, v61
	v_mul_f32_e32 v70, 0x3fcc422a, v70
	v_mul_f32_e32 v46, v46, v60
	v_add_f32_e32 v60, 1.0, v71
	v_mul_f32_e32 v61, 0xbfb8aa3b, v61
	v_mul_f32_e32 v70, 0xbfb8aa3b, v70
	v_rcp_f32_e32 v60, v60
	v_exp_f32_e32 v61, v61
	v_exp_f32_e32 v70, v70
	v_mul_f32_e32 v71, 0x3d372713, v45
	v_mul_f32_e32 v49, v49, v60
	v_add_f32_e32 v60, 1.0, v61
	v_add_f32_e32 v61, 1.0, v70
	v_mul_f32_e32 v70, 0x3d372713, v44
	v_mul_f32_e32 v71, v45, v71
	v_mul_f32_e32 v70, v44, v70
	v_fma_f32 v71, v45, v71, v45
	v_fma_f32 v70, v44, v70, v44
	v_mul_f32_e32 v71, 0x3fcc422a, v71
	v_mul_f32_e32 v70, 0x3fcc422a, v70
	v_mul_f32_e32 v71, 0xbfb8aa3b, v71
	v_mul_f32_e32 v70, 0xbfb8aa3b, v70
	v_exp_f32_e32 v71, v71
	v_exp_f32_e32 v70, v70
	v_rcp_f32_e32 v60, v60
	v_add_u32_e32 v58, 0x90, v162
	v_rcp_f32_e32 v61, v61
	v_ashrrev_i32_e32 v59, 31, v58
	v_add_f32_e32 v71, 1.0, v71
	v_lshlrev_b64 v[58:59], 15, v[58:59]
	v_add_f32_e32 v70, 1.0, v70
	v_rcp_f32_e32 v71, v71
	v_rcp_f32_e32 v70, v70
	v_mul_f32_e32 v60, v42, v60
	v_cvt_pk_bf16_f32 v42, v46, v47
	v_lshl_add_u64 v[46:47], s[14:15], 0, v[58:59]
	v_mul_f32_e32 v61, v43, v61
	v_cvt_pk_bf16_f32 v43, v48, v49
	v_lshl_add_u64 v[48:49], v[46:47], 0, v[130:131]
	v_lshl_add_u64 v[48:49], v[48:49], 0, s[4:5]
	v_mul_f32_e32 v45, v45, v71
	v_lshl_add_u64 v[48:49], v[48:49], 0, v[154:155]
	v_mul_f32_e32 v70, v44, v70
	v_cvt_pk_bf16_f32 v44, v60, v61
	v_cvt_pk_bf16_f32 v45, v70, v45
	global_store_dwordx4 v[48:49], v[42:45], off
	s_nop 1
	v_lshlrev_b32_e32 v42, 16, v74
	v_fma_f32 v38, v66, v42, v38
	v_mul_f32_e32 v43, 0x3d372713, v38
	v_mul_f32_e32 v43, v38, v43
	v_and_b32_e32 v42, 0xffff0000, v74
	v_fma_f32 v43, v38, v43, v38
	v_fma_f32 v39, v67, v42, v39
	v_lshlrev_b32_e32 v42, 16, v75
	v_mul_f32_e32 v43, 0x3fcc422a, v43
	v_fma_f32 v40, v68, v42, v40
	v_and_b32_e32 v42, 0xffff0000, v75
	v_mul_f32_e32 v43, 0xbfb8aa3b, v43
	v_fmac_f32_e32 v41, v69, v42
	v_lshlrev_b32_e32 v42, 16, v76
	v_exp_f32_e32 v43, v43
	v_fma_f32 v34, v62, v42, v34
	v_and_b32_e32 v42, 0xffff0000, v76
	v_fma_f32 v35, v63, v42, v35
	v_lshlrev_b32_e32 v42, 16, v77
	v_fma_f32 v36, v64, v42, v36
	v_and_b32_e32 v42, 0xffff0000, v77
	v_fmac_f32_e32 v37, v65, v42
	v_add_f32_e32 v42, 1.0, v43
	v_mul_f32_e32 v43, 0x3d372713, v39
	v_mul_f32_e32 v44, 0x3d372713, v40
	v_mul_f32_e32 v43, v39, v43
	v_mul_f32_e32 v44, v40, v44
	v_fma_f32 v43, v39, v43, v39
	v_fma_f32 v44, v40, v44, v40
	v_mul_f32_e32 v43, 0x3fcc422a, v43
	v_mul_f32_e32 v44, 0x3fcc422a, v44
	v_mul_f32_e32 v43, 0xbfb8aa3b, v43
	v_mul_f32_e32 v44, 0xbfb8aa3b, v44
	v_exp_f32_e32 v43, v43
	v_exp_f32_e32 v44, v44
	v_mul_f32_e32 v45, 0x3d372713, v41
	v_mul_f32_e32 v45, v41, v45
	v_add_f32_e32 v43, 1.0, v43
	v_add_f32_e32 v44, 1.0, v44
	v_rcp_f32_e32 v43, v43
	v_rcp_f32_e32 v44, v44
	v_fma_f32 v45, v41, v45, v41
	v_mul_f32_e32 v45, 0x3fcc422a, v45
	v_mul_f32_e32 v45, 0xbfb8aa3b, v45
	v_rcp_f32_e32 v42, v42
	v_exp_f32_e32 v45, v45
	v_mul_f32_e32 v39, v39, v43
	v_mul_f32_e32 v40, v40, v44
	v_mul_f32_e32 v43, 0x3d372713, v34
	v_mul_f32_e32 v44, 0x3d372713, v35
	v_mul_f32_e32 v43, v34, v43
	v_mul_f32_e32 v44, v35, v44
	v_fma_f32 v43, v34, v43, v34
	v_fma_f32 v44, v35, v44, v35
	v_mul_f32_e32 v43, 0x3fcc422a, v43
	v_mul_f32_e32 v44, 0x3fcc422a, v44
	v_mul_f32_e32 v38, v38, v42
	v_add_f32_e32 v42, 1.0, v45
	v_mul_f32_e32 v43, 0xbfb8aa3b, v43
	v_mul_f32_e32 v44, 0xbfb8aa3b, v44
	v_rcp_f32_e32 v42, v42
	v_exp_f32_e32 v43, v43
	v_exp_f32_e32 v44, v44
	v_mul_f32_e32 v45, 0x3d372713, v37
	v_mul_f32_e32 v41, v41, v42
	v_add_f32_e32 v42, 1.0, v43
	v_add_f32_e32 v43, 1.0, v44
	v_mul_f32_e32 v44, 0x3d372713, v36
	v_mul_f32_e32 v44, v36, v44
	v_mul_f32_e32 v45, v37, v45
	v_fma_f32 v44, v36, v44, v36
	v_fma_f32 v45, v37, v45, v37
	v_mul_f32_e32 v44, 0x3fcc422a, v44
	v_mul_f32_e32 v45, 0x3fcc422a, v45
	v_mul_f32_e32 v44, 0xbfb8aa3b, v44
	v_mul_f32_e32 v45, 0xbfb8aa3b, v45
	v_exp_f32_e32 v44, v44
	v_exp_f32_e32 v45, v45
	v_rcp_f32_e32 v42, v42
	v_rcp_f32_e32 v43, v43
	v_add_f32_e32 v44, 1.0, v44
	v_add_f32_e32 v45, 1.0, v45
	v_rcp_f32_e32 v44, v44
	v_rcp_f32_e32 v45, v45
	v_mul_f32_e32 v42, v34, v42
	v_mul_f32_e32 v43, v35, v43
	v_mul_f32_e32 v44, v36, v44
	v_mul_f32_e32 v37, v37, v45
	v_cvt_pk_bf16_f32 v34, v38, v39
	v_cvt_pk_bf16_f32 v35, v40, v41
	v_cvt_pk_bf16_f32 v36, v42, v43
	v_cvt_pk_bf16_f32 v37, v44, v37
	s_waitcnt vmcnt(1)
; __device__ __forceinline__ unsigned cvt_pk_bf16(float lo, float hi) { unsigned r; asm volatile("v_cvt_pk_bf16_f32 %0, %1, %2" : "=v"(r) : "v"(lo), "v"(hi)); return r; }
; __device__ __forceinline__ float sigm(float x) { return __builtin_amdgcn_rcpf(1.f + __expf(-x)); }
; __device__ __forceinline__ float wave_sum(float v) {
; #pragma unroll
;     for (int o = 1; o < 64; o <<= 1) v += __shfl_xor(v, o);
;     return v;
; }
; __device__ __forceinline__ void sincos_rad(float x, float& s, float& c) {
;     double r = (double)x * 0.15915494309189535; r -= __builtin_rint(r); const float fr = (float)r;
;     s = __builtin_amdgcn_sinf(fr); c = __builtin_amdgcn_cosf(fr);
; }
; __device__ __forceinline__ void cpow(float lr, float li, float delta, float j, float& re, float& im) {
;     const float mag = expf(j * delta * lr); float s, c; sincos_rad(j * delta * li, s, c); re = mag * c; im = mag * s;
; }
;     __device__ __forceinline__ void operator()(const pg8::f32x4 (&acc)[2][2][4][2], const Unit& u, int wr, int wc, int fr, int fq) const {
;     ...
;         for (int k = 0; k < 8; ++k) { const int ai = k >> 2, m = k & 3; const int row = row0 + ai * HALF + m * 16; v4u cu[2];
; #pragma unroll
;             for (int bj = 0; bj < 2; ++bj) cu[bj] = nu[bj];
;             if (k < 7) {
; #pragma unroll
;                 for (int bj = 0; bj < 2; ++bj) nu[bj] = *(const v4u*)(UX + ((size_t)u.g * 1024 + row0 + ((k + 1) >> 2) * HALF + ((k + 1) & 3) * 16) * 640 + ((colb + bj * HALF) >> 4) * 16 + c0); }
; #pragma unroll
;             for (int bj = 0; bj < 2; ++bj) { const int tau = (colb + bj * HALF) >> 4;
;                 const v4u uw = cu[bj]; const f32x4 a0 = acc[ai][bj][m][0], a1 = acc[ai][bj][m][1];
;                 float r[8]; r[0] = a0[0] + d0[0] * bflo(uw.x); r[1] = a0[1] + d0[1] * bfhi(uw.x); r[2] = a0[2] + d0[2] * bflo(uw.y); r[3] = a0[3] + d0[3] * bfhi(uw.y);
;                 r[4] = a1[0] + d1[0] * bflo(uw.z); r[5] = a1[1] + d1[1] * bfhi(uw.z); r[6] = a1[2] + d1[2] * bflo(uw.w); r[7] = a1[3] + d1[3] * bfhi(uw.w);
; #pragma unroll
;                 for (int e = 0; e < 8; ++e) r[e] = gelu_tanh(r[e]);
;                 v4u w; w.x = cvt_pk_bf16(r[0], r[1]); w.y = cvt_pk_bf16(r[2], r[3]); w.z = cvt_pk_bf16(r[4], r[5]); w.w = cvt_pk_bf16(r[6], r[7]);
;                 *(v4u*)(Y + ((size_t)row * 32 + tau) * 512 + u.g * 16 + c0) = w; } }
	v_lshlrev_b32_e32 v44, 16, v54
	v_fma_f32 v30, v66, v44, v30
	v_mul_f32_e32 v45, 0x3d372713, v30
	v_mul_f32_e32 v45, v30, v45
	v_and_b32_e32 v44, 0xffff0000, v54
	v_fma_f32 v45, v30, v45, v30
	v_fma_f32 v31, v67, v44, v31
	v_lshlrev_b32_e32 v44, 16, v55
	v_mul_f32_e32 v45, 0x3fcc422a, v45
	v_fma_f32 v32, v68, v44, v32
	v_and_b32_e32 v44, 0xffff0000, v55
	v_mul_f32_e32 v45, 0xbfb8aa3b, v45
	v_fmac_f32_e32 v33, v69, v44
	v_lshlrev_b32_e32 v44, 16, v56
	v_exp_f32_e32 v45, v45
	v_fma_f32 v26, v62, v44, v26
	v_and_b32_e32 v44, 0xffff0000, v56
	v_fma_f32 v27, v63, v44, v27
	v_lshlrev_b32_e32 v44, 16, v57
	v_fma_f32 v28, v64, v44, v28
	v_and_b32_e32 v44, 0xffff0000, v57
	v_lshl_add_u64 v[38:39], v[46:47], 0, v[132:133]
	v_fmac_f32_e32 v29, v65, v44
	v_add_f32_e32 v44, 1.0, v45
	v_mul_f32_e32 v45, 0x3d372713, v31
	v_mul_f32_e32 v46, 0x3d372713, v32
	v_mul_f32_e32 v45, v31, v45
	v_mul_f32_e32 v46, v32, v46
	v_lshl_add_u64 v[38:39], v[38:39], 0, s[4:5]
	v_fma_f32 v45, v31, v45, v31
	v_fma_f32 v46, v32, v46, v32
	v_lshl_add_u64 v[38:39], v[38:39], 0, v[154:155]
	v_mul_f32_e32 v45, 0x3fcc422a, v45
	v_mul_f32_e32 v46, 0x3fcc422a, v46
	global_store_dwordx4 v[38:39], v[34:37], off
	v_add_co_u32_e32 v38, vcc, s67, v164
	v_mul_f32_e32 v45, 0xbfb8aa3b, v45
	v_mul_f32_e32 v46, 0xbfb8aa3b, v46
	v_lshl_add_u64 v[34:35], v[164:165], 0, s[34:35]
	v_addc_co_u32_e32 v39, vcc, 0, v165, vcc
	v_exp_f32_e32 v45, v45
	v_exp_f32_e32 v46, v46
	global_load_dwordx4 v[34:37], v[34:35], off offset:256
	s_nop 0
	global_load_dwordx4 v[38:41], v[38:39], off
	v_mul_f32_e32 v47, 0x3d372713, v33
	v_add_f32_e32 v45, 1.0, v45
	v_add_f32_e32 v46, 1.0, v46
	v_rcp_f32_e32 v45, v45
	v_rcp_f32_e32 v46, v46
	v_mul_f32_e32 v47, v33, v47
	v_fma_f32 v47, v33, v47, v33
	v_mul_f32_e32 v47, 0x3fcc422a, v47
	v_mul_f32_e32 v47, 0xbfb8aa3b, v47
	v_rcp_f32_e32 v44, v44
	v_exp_f32_e32 v47, v47
	v_mul_f32_e32 v31, v31, v45
	v_mul_f32_e32 v32, v32, v46
	v_mul_f32_e32 v45, 0x3d372713, v26
	v_mul_f32_e32 v46, 0x3d372713, v27
	v_mul_f32_e32 v45, v26, v45
	v_mul_f32_e32 v46, v27, v46
	v_fma_f32 v45, v26, v45, v26
	v_fma_f32 v46, v27, v46, v27
	v_mul_f32_e32 v45, 0x3fcc422a, v45
	v_mul_f32_e32 v46, 0x3fcc422a, v46
	v_mul_f32_e32 v30, v30, v44
	v_add_f32_e32 v44, 1.0, v47
	v_mul_f32_e32 v45, 0xbfb8aa3b, v45
	v_mul_f32_e32 v46, 0xbfb8aa3b, v46
	v_rcp_f32_e32 v44, v44
	v_exp_f32_e32 v45, v45
	v_exp_f32_e32 v46, v46
	v_mul_f32_e32 v47, 0x3d372713, v29
	v_mul_f32_e32 v33, v33, v44
	v_add_f32_e32 v44, 1.0, v45
	v_add_f32_e32 v45, 1.0, v46
	v_mul_f32_e32 v46, 0x3d372713, v28
	v_mul_f32_e32 v47, v29, v47
	v_mul_f32_e32 v46, v28, v46
	v_fma_f32 v47, v29, v47, v29
	v_fma_f32 v46, v28, v46, v28
	v_mul_f32_e32 v47, 0x3fcc422a, v47
	v_mul_f32_e32 v46, 0x3fcc422a, v46
	v_mul_f32_e32 v47, 0xbfb8aa3b, v47
	v_mul_f32_e32 v46, 0xbfb8aa3b, v46
	v_exp_f32_e32 v47, v47
	v_exp_f32_e32 v46, v46
	v_rcp_f32_e32 v44, v44
	v_add_u32_e32 v42, 0xa0, v162
	v_rcp_f32_e32 v45, v45
	v_ashrrev_i32_e32 v43, 31, v42
	v_add_f32_e32 v47, 1.0, v47
	v_lshlrev_b64 v[42:43], 15, v[42:43]
	v_add_f32_e32 v46, 1.0, v46
	v_rcp_f32_e32 v47, v47
	v_rcp_f32_e32 v46, v46
	v_mul_f32_e32 v44, v26, v44
	v_cvt_pk_bf16_f32 v26, v30, v31
	v_lshl_add_u64 v[30:31], s[14:15], 0, v[42:43]
	v_mul_f32_e32 v45, v27, v45
	v_cvt_pk_bf16_f32 v27, v32, v33
	v_lshl_add_u64 v[32:33], v[30:31], 0, v[130:131]
	v_lshl_add_u64 v[32:33], v[32:33], 0, s[4:5]
	v_mul_f32_e32 v29, v29, v47
	v_lshl_add_u64 v[32:33], v[32:33], 0, v[154:155]
	v_mul_f32_e32 v46, v28, v46
	v_cvt_pk_bf16_f32 v28, v44, v45
	v_cvt_pk_bf16_f32 v29, v46, v29
	global_store_dwordx4 v[32:33], v[26:29], off
	s_and_b64 vcc, exec, s[6:7]
	s_nop 0
	v_lshlrev_b32_e32 v26, 16, v50
	v_fma_f32 v22, v66, v26, v22
	v_mul_f32_e32 v27, 0x3d372713, v22
	v_mul_f32_e32 v27, v22, v27
	v_and_b32_e32 v26, 0xffff0000, v50
	v_fma_f32 v27, v22, v27, v22
	v_fma_f32 v23, v67, v26, v23
	v_lshlrev_b32_e32 v26, 16, v51
	v_mul_f32_e32 v27, 0x3fcc422a, v27
	v_fma_f32 v24, v68, v26, v24
	v_and_b32_e32 v26, 0xffff0000, v51
	v_mul_f32_e32 v27, 0xbfb8aa3b, v27
	v_fmac_f32_e32 v25, v69, v26
	v_lshlrev_b32_e32 v26, 16, v52
	v_exp_f32_e32 v27, v27
	v_fma_f32 v18, v62, v26, v18
	v_and_b32_e32 v26, 0xffff0000, v52
	v_fma_f32 v19, v63, v26, v19
	v_lshlrev_b32_e32 v26, 16, v53
	v_fma_f32 v20, v64, v26, v20
	v_and_b32_e32 v26, 0xffff0000, v53
	v_fmac_f32_e32 v21, v65, v26
	v_add_f32_e32 v26, 1.0, v27
	v_mul_f32_e32 v27, 0x3d372713, v23
	v_mul_f32_e32 v28, 0x3d372713, v24
	v_mul_f32_e32 v27, v23, v27
	v_mul_f32_e32 v28, v24, v28
	v_fma_f32 v27, v23, v27, v23
	v_fma_f32 v28, v24, v28, v24
	v_mul_f32_e32 v27, 0x3fcc422a, v27
	v_mul_f32_e32 v28, 0x3fcc422a, v28
	v_mul_f32_e32 v27, 0xbfb8aa3b, v27
	v_mul_f32_e32 v28, 0xbfb8aa3b, v28
	v_exp_f32_e32 v27, v27
	v_exp_f32_e32 v28, v28
	v_mul_f32_e32 v29, 0x3d372713, v25
	v_mul_f32_e32 v29, v25, v29
	v_add_f32_e32 v27, 1.0, v27
	v_add_f32_e32 v28, 1.0, v28
	v_rcp_f32_e32 v27, v27
	v_rcp_f32_e32 v28, v28
	v_fma_f32 v29, v25, v29, v25
	v_mul_f32_e32 v29, 0x3fcc422a, v29
	v_mul_f32_e32 v29, 0xbfb8aa3b, v29
	v_rcp_f32_e32 v26, v26
	v_exp_f32_e32 v29, v29
	v_mul_f32_e32 v23, v23, v27
	v_mul_f32_e32 v24, v24, v28
	v_mul_f32_e32 v27, 0x3d372713, v18
	v_mul_f32_e32 v28, 0x3d372713, v19
	v_mul_f32_e32 v27, v18, v27
	v_mul_f32_e32 v28, v19, v28
	v_fma_f32 v27, v18, v27, v18
	v_fma_f32 v28, v19, v28, v19
	v_mul_f32_e32 v27, 0x3fcc422a, v27
	v_mul_f32_e32 v28, 0x3fcc422a, v28
	v_mul_f32_e32 v22, v22, v26
	v_add_f32_e32 v26, 1.0, v29
	v_mul_f32_e32 v27, 0xbfb8aa3b, v27
	v_mul_f32_e32 v28, 0xbfb8aa3b, v28
	v_rcp_f32_e32 v26, v26
	v_exp_f32_e32 v27, v27
	v_exp_f32_e32 v28, v28
	v_mul_f32_e32 v29, 0x3d372713, v21
	v_mul_f32_e32 v25, v25, v26
	v_add_f32_e32 v26, 1.0, v27
	v_add_f32_e32 v27, 1.0, v28
	v_mul_f32_e32 v28, 0x3d372713, v20
	v_mul_f32_e32 v28, v20, v28
	v_mul_f32_e32 v29, v21, v29
	v_fma_f32 v28, v20, v28, v20
	v_fma_f32 v29, v21, v29, v21
	v_mul_f32_e32 v28, 0x3fcc422a, v28
	v_mul_f32_e32 v29, 0x3fcc422a, v29
	v_mul_f32_e32 v28, 0xbfb8aa3b, v28
	v_mul_f32_e32 v29, 0xbfb8aa3b, v29
	v_exp_f32_e32 v28, v28
	v_exp_f32_e32 v29, v29
	v_rcp_f32_e32 v26, v26
	v_rcp_f32_e32 v27, v27
	v_add_f32_e32 v28, 1.0, v28
	v_add_f32_e32 v29, 1.0, v29
	v_rcp_f32_e32 v28, v28
	v_rcp_f32_e32 v29, v29
	v_mul_f32_e32 v26, v18, v26
	v_cvt_pk_bf16_f32 v18, v22, v23
	v_lshl_add_u64 v[22:23], v[30:31], 0, v[132:133]
	v_lshl_add_u64 v[22:23], v[22:23], 0, s[4:5]
	v_mul_f32_e32 v27, v19, v27
	v_mul_f32_e32 v28, v20, v28
	v_mul_f32_e32 v21, v21, v29
	v_cvt_pk_bf16_f32 v19, v24, v25
	v_cvt_pk_bf16_f32 v20, v26, v27
	v_lshl_add_u64 v[22:23], v[22:23], 0, v[154:155]
	v_cvt_pk_bf16_f32 v21, v28, v21
	global_store_dwordx4 v[22:23], v[18:21], off
	s_waitcnt vmcnt(2)
; #define PG8_BAR __builtin_amdgcn_s_barrier()
; __device__ __forceinline__ float bflo(unsigned w) { return __uint_as_float(w << 16); }
; template <class Epi, class Sched, bool ALIGN_EPI = false, bool SP2 = false>
; __device__ __forceinline__ void gemm_phase(PG8_LAS unsigned char* lds, const Gemm g, const Sched& S, const Epi& E) {
;     ...
;         if constexpr (ALIGN_EPI) { if (wr == 0) PG8_BAR; }
;         if constexpr (!Epi::AFTER_DRAIN) { E(acc, cur, wr, wc, fr, fq); S.done(cur); }
;         if (!has_next) break;
; #pragma unroll
;         for (int a = 0; a < 2; ++a)
; #pragma unroll
;             for (int b = 0; b < 2; ++b)
; #pragma unroll
;                 for (int m = 0; m < 4; ++m)
; #pragma unroll
;                     for (int n = 0; n < 2; ++n) acc[a][b][m][n] = (f32x4){0.f, 0.f, 0.f, 0.f};
;         cur = nxt; cA = nA; cB = nB; ++ui;
;         if constexpr (ALIGN_EPI) { if (wr == 1) PG8_BAR; }
;     }
;     __device__ __forceinline__ void operator()(const pg8::f32x4 (&acc)[2][2][4][2], const Unit& u, int wr, int wc, int fr, int fq) const {
;     ...
;         for (int k = 0; k < 8; ++k) { const int ai = k >> 2, m = k & 3; const int row = row0 + ai * HALF + m * 16; v4u cu[2];
; #pragma unroll
;             for (int bj = 0; bj < 2; ++bj) cu[bj] = nu[bj];
;             if (k < 7) {
; #pragma unroll
;                 for (int bj = 0; bj < 2; ++bj) nu[bj] = *(const v4u*)(UX + ((size_t)u.g * 1024 + row0 + ((k + 1) >> 2) * HALF + ((k + 1) & 3) * 16) * 640 + ((colb + bj * HALF) >> 4) * 16 + c0); }
; #pragma unroll
;             for (int bj = 0; bj < 2; ++bj) { const int tau = (colb + bj * HALF) >> 4;
;                 const v4u uw = cu[bj]; const f32x4 a0 = acc[ai][bj][m][0], a1 = acc[ai][bj][m][1];
;                 float r[8]; r[0] = a0[0] + d0[0] * bflo(uw.x); r[1] = a0[1] + d0[1] * bfhi(uw.x); r[2] = a0[2] + d0[2] * bflo(uw.y); r[3] = a0[3] + d0[3] * bfhi(uw.y);
;                 r[4] = a1[0] + d1[0] * bflo(uw.z); r[5] = a1[1] + d1[1] * bfhi(uw.z); r[6] = a1[2] + d1[2] * bflo(uw.w); r[7] = a1[3] + d1[3] * bfhi(uw.w);
; #pragma unroll
;                 for (int e = 0; e < 8; ++e) r[e] = gelu_tanh(r[e]);
;                 v4u w; w.x = cvt_pk_bf16(r[0], r[1]); w.y = cvt_pk_bf16(r[2], r[3]); w.z = cvt_pk_bf16(r[4], r[5]); w.w = cvt_pk_bf16(r[6], r[7]);
;                 *(v4u*)(Y + ((size_t)row * 32 + tau) * 512 + u.g * 16 + c0) = w; } }
	s_nop 0
	v_lshlrev_b32_e32 v20, 16, v38
	v_fma_f32 v14, v66, v20, v14
	v_mul_f32_e32 v21, 0x3d372713, v14
	v_mul_f32_e32 v21, v14, v21
	v_and_b32_e32 v20, 0xffff0000, v38
	v_fma_f32 v21, v14, v21, v14
	v_fma_f32 v15, v67, v20, v15
	v_lshlrev_b32_e32 v20, 16, v39
	v_mul_f32_e32 v21, 0x3fcc422a, v21
	v_fma_f32 v16, v68, v20, v16
	v_and_b32_e32 v20, 0xffff0000, v39
	v_mul_f32_e32 v21, 0xbfb8aa3b, v21
	v_fmac_f32_e32 v17, v69, v20
	v_lshlrev_b32_e32 v20, 16, v40
	v_exp_f32_e32 v21, v21
	v_fma_f32 v10, v62, v20, v10
	v_and_b32_e32 v20, 0xffff0000, v40
	v_fma_f32 v11, v63, v20, v11
	v_lshlrev_b32_e32 v20, 16, v41
	v_fma_f32 v12, v64, v20, v12
	v_and_b32_e32 v20, 0xffff0000, v41
	v_fmac_f32_e32 v13, v65, v20
	v_add_f32_e32 v20, 1.0, v21
	v_mul_f32_e32 v21, 0x3d372713, v15
	v_mul_f32_e32 v22, 0x3d372713, v16
	v_mul_f32_e32 v21, v15, v21
	v_mul_f32_e32 v22, v16, v22
	v_fma_f32 v21, v15, v21, v15
	v_fma_f32 v22, v16, v22, v16
	v_mul_f32_e32 v21, 0x3fcc422a, v21
	v_mul_f32_e32 v22, 0x3fcc422a, v22
	v_mul_f32_e32 v21, 0xbfb8aa3b, v21
	v_mul_f32_e32 v22, 0xbfb8aa3b, v22
	v_exp_f32_e32 v21, v21
	v_exp_f32_e32 v22, v22
	v_mul_f32_e32 v23, 0x3d372713, v17
	v_mul_f32_e32 v23, v17, v23
	v_add_f32_e32 v21, 1.0, v21
	v_add_f32_e32 v22, 1.0, v22
	v_rcp_f32_e32 v21, v21
	v_rcp_f32_e32 v22, v22
	v_fma_f32 v23, v17, v23, v17
	v_mul_f32_e32 v23, 0x3fcc422a, v23
	v_mul_f32_e32 v23, 0xbfb8aa3b, v23
	v_rcp_f32_e32 v20, v20
	v_exp_f32_e32 v23, v23
	v_mul_f32_e32 v15, v15, v21
	v_mul_f32_e32 v16, v16, v22
	v_mul_f32_e32 v21, 0x3d372713, v10
	v_mul_f32_e32 v22, 0x3d372713, v11
	v_mul_f32_e32 v21, v10, v21
	v_mul_f32_e32 v22, v11, v22
	v_fma_f32 v21, v10, v21, v10
	v_fma_f32 v22, v11, v22, v11
	v_mul_f32_e32 v21, 0x3fcc422a, v21
	v_mul_f32_e32 v22, 0x3fcc422a, v22
	v_mul_f32_e32 v14, v14, v20
	v_add_f32_e32 v20, 1.0, v23
	v_mul_f32_e32 v21, 0xbfb8aa3b, v21
	v_mul_f32_e32 v22, 0xbfb8aa3b, v22
	v_rcp_f32_e32 v20, v20
	v_exp_f32_e32 v21, v21
	v_exp_f32_e32 v22, v22
	v_mul_f32_e32 v23, 0x3d372713, v13
	v_mul_f32_e32 v17, v17, v20
	v_add_f32_e32 v20, 1.0, v21
	v_add_f32_e32 v21, 1.0, v22
	v_mul_f32_e32 v22, 0x3d372713, v12
	v_mul_f32_e32 v23, v13, v23
	v_mul_f32_e32 v22, v12, v22
	v_fma_f32 v23, v13, v23, v13
	v_fma_f32 v22, v12, v22, v12
	v_mul_f32_e32 v23, 0x3fcc422a, v23
	v_mul_f32_e32 v22, 0x3fcc422a, v22
	v_mul_f32_e32 v23, 0xbfb8aa3b, v23
	v_mul_f32_e32 v22, 0xbfb8aa3b, v22
	v_exp_f32_e32 v23, v23
	v_exp_f32_e32 v22, v22
	v_rcp_f32_e32 v20, v20
	v_add_u32_e32 v18, 0xb0, v162
	v_rcp_f32_e32 v21, v21
	v_ashrrev_i32_e32 v19, 31, v18
	v_add_f32_e32 v23, 1.0, v23
	v_lshlrev_b64 v[18:19], 15, v[18:19]
	v_add_f32_e32 v22, 1.0, v22
	v_rcp_f32_e32 v23, v23
	v_rcp_f32_e32 v22, v22
	v_mul_f32_e32 v20, v10, v20
	v_cvt_pk_bf16_f32 v10, v14, v15
	v_lshl_add_u64 v[14:15], s[14:15], 0, v[18:19]
	v_mul_f32_e32 v21, v11, v21
	v_cvt_pk_bf16_f32 v11, v16, v17
	v_lshl_add_u64 v[16:17], v[14:15], 0, v[130:131]
	v_lshl_add_u64 v[16:17], v[16:17], 0, s[4:5]
	v_mul_f32_e32 v13, v13, v23
	v_lshl_add_u64 v[16:17], v[16:17], 0, v[154:155]
	v_mul_f32_e32 v22, v12, v22
	v_cvt_pk_bf16_f32 v12, v20, v21
	v_cvt_pk_bf16_f32 v13, v22, v13
	global_store_dwordx4 v[16:17], v[10:13], off
	s_nop 1
	v_lshlrev_b32_e32 v10, 16, v34
	v_fma_f32 v6, v66, v10, v6
	v_mul_f32_e32 v11, 0x3d372713, v6
	v_mul_f32_e32 v11, v6, v11
	v_and_b32_e32 v10, 0xffff0000, v34
	v_fma_f32 v11, v6, v11, v6
	v_fma_f32 v7, v67, v10, v7
	v_lshlrev_b32_e32 v10, 16, v35
	v_mul_f32_e32 v11, 0x3fcc422a, v11
	v_fma_f32 v8, v68, v10, v8
	v_and_b32_e32 v10, 0xffff0000, v35
	v_mul_f32_e32 v11, 0xbfb8aa3b, v11
	v_fmac_f32_e32 v9, v69, v10
	v_lshlrev_b32_e32 v10, 16, v36
	v_exp_f32_e32 v11, v11
	v_fma_f32 v2, v62, v10, v2
	v_and_b32_e32 v10, 0xffff0000, v36
	v_fma_f32 v3, v63, v10, v3
	v_lshlrev_b32_e32 v10, 16, v37
	v_fma_f32 v4, v64, v10, v4
	v_and_b32_e32 v10, 0xffff0000, v37
	v_fmac_f32_e32 v5, v65, v10
	v_add_f32_e32 v10, 1.0, v11
	v_mul_f32_e32 v11, 0x3d372713, v7
	v_mul_f32_e32 v12, 0x3d372713, v8
	v_mul_f32_e32 v11, v7, v11
	v_mul_f32_e32 v12, v8, v12
	v_fma_f32 v11, v7, v11, v7
	v_fma_f32 v12, v8, v12, v8
	v_mul_f32_e32 v11, 0x3fcc422a, v11
	v_mul_f32_e32 v12, 0x3fcc422a, v12
	v_mul_f32_e32 v11, 0xbfb8aa3b, v11
	v_mul_f32_e32 v12, 0xbfb8aa3b, v12
	v_exp_f32_e32 v11, v11
	v_exp_f32_e32 v12, v12
	v_mul_f32_e32 v13, 0x3d372713, v9
	v_mul_f32_e32 v13, v9, v13
	v_add_f32_e32 v11, 1.0, v11
	v_add_f32_e32 v12, 1.0, v12
	v_rcp_f32_e32 v11, v11
	v_rcp_f32_e32 v12, v12
	v_fma_f32 v13, v9, v13, v9
	v_mul_f32_e32 v13, 0x3fcc422a, v13
	v_mul_f32_e32 v13, 0xbfb8aa3b, v13
	v_rcp_f32_e32 v10, v10
	v_exp_f32_e32 v13, v13
	v_mul_f32_e32 v7, v7, v11
	v_mul_f32_e32 v8, v8, v12
	v_mul_f32_e32 v11, 0x3d372713, v2
	v_mul_f32_e32 v12, 0x3d372713, v3
	v_mul_f32_e32 v11, v2, v11
	v_mul_f32_e32 v12, v3, v12
	v_fma_f32 v11, v2, v11, v2
	v_fma_f32 v12, v3, v12, v3
	v_mul_f32_e32 v11, 0x3fcc422a, v11
	v_mul_f32_e32 v12, 0x3fcc422a, v12
	v_mul_f32_e32 v6, v6, v10
	v_add_f32_e32 v10, 1.0, v13
	v_mul_f32_e32 v11, 0xbfb8aa3b, v11
	v_mul_f32_e32 v12, 0xbfb8aa3b, v12
	v_rcp_f32_e32 v10, v10
	v_exp_f32_e32 v11, v11
	v_exp_f32_e32 v12, v12
	v_mul_f32_e32 v13, 0x3d372713, v5
	v_mul_f32_e32 v9, v9, v10
	v_add_f32_e32 v10, 1.0, v11
	v_add_f32_e32 v11, 1.0, v12
	v_mul_f32_e32 v12, 0x3d372713, v4
	v_mul_f32_e32 v13, v5, v13
	v_mul_f32_e32 v12, v4, v12
	v_fma_f32 v13, v5, v13, v5
	v_fma_f32 v12, v4, v12, v4
	v_mul_f32_e32 v13, 0x3fcc422a, v13
	v_mul_f32_e32 v12, 0x3fcc422a, v12
	v_mul_f32_e32 v13, 0xbfb8aa3b, v13
	v_mul_f32_e32 v12, 0xbfb8aa3b, v12
	v_exp_f32_e32 v13, v13
	v_exp_f32_e32 v12, v12
	v_rcp_f32_e32 v10, v10
	v_rcp_f32_e32 v11, v11
	v_add_f32_e32 v13, 1.0, v13
	v_add_f32_e32 v12, 1.0, v12
	v_rcp_f32_e32 v13, v13
	v_rcp_f32_e32 v12, v12
	v_mul_f32_e32 v10, v2, v10
	v_cvt_pk_bf16_f32 v2, v6, v7
	v_lshl_add_u64 v[6:7], v[14:15], 0, v[132:133]
	v_lshl_add_u64 v[6:7], v[6:7], 0, s[4:5]
	v_mul_f32_e32 v5, v5, v13
	v_lshl_add_u64 v[6:7], v[6:7], 0, v[154:155]
	s_mov_b64 s[4:5], -1
	v_mul_f32_e32 v11, v3, v11
	v_mul_f32_e32 v12, v4, v12
	v_cvt_pk_bf16_f32 v3, v8, v9
	v_cvt_pk_bf16_f32 v4, v10, v11
	v_cvt_pk_bf16_f32 v5, v12, v5
	global_store_dwordx4 v[6:7], v[2:5], off
	s_cbranch_vccnz .LBB0_422
	s_andn2_b64 vcc, exec, s[12:13]
	s_cbranch_vccnz .LBB0_421
	s_barrier
	s_branch .LBB0_421

; __device__ __forceinline__ unsigned cvt_pk_bf16(float lo, float hi) { unsigned r; asm volatile("v_cvt_pk_bf16_f32 %0, %1, %2" : "=v"(r) : "v"(lo), "v"(hi)); return r; }
; __device__ __forceinline__ float bflo(unsigned w) { return __uint_as_float(w << 16); }
; __device__ __forceinline__ float bfhi(unsigned w) { return __uint_as_float(w & 0xffff0000u); }
; __device__ __forceinline__ float sigm(float x) { return __builtin_amdgcn_rcpf(1.f + __expf(-x)); }
;     __device__ __forceinline__ void operator()(const pg8::f32x4 (&acc)[2][2][4][2], const Unit& u, int wr, int wc, int fr, int fq) const {
;         const int row0 = u.pm * BM + wr * 64 + fr, col0 = u.pn * BM + wc * 32 + 8 * fq;
;         v4u ny[2];
; #pragma unroll
;         for (int bj = 0; bj < 2; ++bj) ny[bj] = *(const v4u*)(Y + (size_t)row0 * 512 + col0 + bj * HALF);
; #pragma unroll
;         for (int k = 0; k < 8; ++k) { const int ai = k >> 2, m = k & 3; const int row = row0 + ai * HALF + m * 16; v4u cy[2];
; #pragma unroll
;             for (int bj = 0; bj < 2; ++bj) cy[bj] = ny[bj];
;             if (k < 7) {
; #pragma unroll
;                 for (int bj = 0; bj < 2; ++bj) ny[bj] = *(const v4u*)(Y + (size_t)(row0 + ((k + 1) >> 2) * HALF + ((k + 1) & 3) * 16) * 512 + col0 + bj * HALF); }
; #pragma unroll
;             for (int bj = 0; bj < 2; ++bj) { const int col = col0 + bj * HALF; const v4u yw = cy[bj]; const f32x4 a0 = acc[ai][bj][m][0], a1 = acc[ai][bj][m][1];
;                 v4u w; w.x = cvt_pk_bf16(bflo(yw.x) * sigm(a0[0]), bfhi(yw.x) * sigm(a0[1])); w.y = cvt_pk_bf16(bflo(yw.y) * sigm(a0[2]), bfhi(yw.y) * sigm(a0[3]));
;                 w.z = cvt_pk_bf16(bflo(yw.z) * sigm(a1[0]), bfhi(yw.z) * sigm(a1[1])); w.w = cvt_pk_bf16(bflo(yw.w) * sigm(a1[2]), bfhi(yw.w) * sigm(a1[3]));
;                 *(v4u*)(O + (size_t)row * DM_ + 512 + col) = w; } }
.LBB0_526:
	v_lshl_add_u32 v148, s24, 8, v1
	v_lshl_or_b32 v146, s43, 8, v151
	v_ashrrev_i32_e32 v149, 31, v148
	v_lshlrev_b64 v[156:157], 10, v[148:149]
	v_ashrrev_i32_e32 v147, 31, v146
	v_lshl_add_u64 v[156:157], s[8:9], 0, v[156:157]
	v_lshlrev_b64 v[146:147], 1, v[146:147]
	v_lshl_add_u64 v[160:161], v[156:157], 0, v[146:147]
	global_load_dwordx4 v[156:159], v[160:161], off
	s_nop 0
	global_load_dwordx4 v[160:163], v[160:161], off offset:256
	v_mul_f32_e32 v122, 0xbfb8aa3b, v122
	v_mul_f32_e32 v123, 0xbfb8aa3b, v123
	v_mul_f32_e32 v124, 0xbfb8aa3b, v124
	v_mul_f32_e32 v125, 0xbfb8aa3b, v125
	v_or_b32_e32 v164, 16, v148
	v_mul_f32_e32 v120, 0xbfb8aa3b, v120
	v_mul_f32_e32 v121, 0xbfb8aa3b, v121
	v_exp_f32_e32 v155, v122
	v_exp_f32_e32 v168, v123
	v_exp_f32_e32 v124, v124
	v_exp_f32_e32 v125, v125
	v_ashrrev_i32_e32 v165, 31, v164
	v_mul_f32_e32 v118, 0xbfb8aa3b, v118
	v_mul_f32_e32 v119, 0xbfb8aa3b, v119
	v_exp_f32_e32 v171, v120
	v_exp_f32_e32 v172, v121
	v_lshlrev_b64 v[120:121], 10, v[164:165]
	v_exp_f32_e32 v169, v118
	v_exp_f32_e32 v170, v119
	v_lshlrev_b64 v[118:119], 11, v[148:149]
	v_lshl_add_u64 v[120:121], s[8:9], 0, v[120:121]
	v_lshl_add_u64 v[118:119], s[12:13], 0, v[118:119]
	v_lshl_add_u64 v[122:123], v[120:121], 0, v[146:147]
	v_lshl_add_u64 v[166:167], v[118:119], 0, v[146:147]
	v_add_f32_e32 v149, 1.0, v155
	v_add_f32_e32 v155, 1.0, v168
	v_add_f32_e32 v168, 1.0, v124
	v_add_f32_e32 v173, 1.0, v125
	global_load_dwordx4 v[118:121], v[122:123], off offset:256
	s_nop 0
	global_load_dwordx4 v[122:125], v[122:123], off
	v_mul_f32_e32 v126, 0xbfb8aa3b, v126
	v_mul_f32_e32 v127, 0xbfb8aa3b, v127
	v_mul_f32_e32 v128, 0xbfb8aa3b, v128
	v_mul_f32_e32 v129, 0xbfb8aa3b, v129
	v_exp_f32_e32 v126, v126
	v_exp_f32_e32 v127, v127
	v_exp_f32_e32 v128, v128
	v_exp_f32_e32 v129, v129
	v_add_f32_e32 v126, 1.0, v126
	v_add_f32_e32 v127, 1.0, v127
	v_add_f32_e32 v128, 1.0, v128
	v_add_f32_e32 v129, 1.0, v129
	v_rcp_f32_e32 v126, v126
	v_rcp_f32_e32 v127, v127
	v_rcp_f32_e32 v128, v128
	v_rcp_f32_e32 v129, v129
	v_rcp_f32_e32 v149, v149
	v_rcp_f32_e32 v155, v155
	v_rcp_f32_e32 v168, v168
	v_rcp_f32_e32 v173, v173
	v_mul_f32_e32 v114, 0xbfb8aa3b, v114
	v_exp_f32_e32 v114, v114
	v_mul_f32_e32 v115, 0xbfb8aa3b, v115
	v_exp_f32_e32 v115, v115
	v_add_f32_e32 v169, 1.0, v169
	v_add_f32_e32 v170, 1.0, v170
	v_rcp_f32_e32 v169, v169
	v_rcp_f32_e32 v170, v170
	v_add_f32_e32 v114, 1.0, v114
	v_rcp_f32_e32 v114, v114
	v_add_f32_e32 v115, 1.0, v115
	v_mul_f32_e32 v116, 0xbfb8aa3b, v116
	v_rcp_f32_e32 v115, v115
	v_exp_f32_e32 v116, v116
	v_mul_f32_e32 v117, 0xbfb8aa3b, v117
	v_exp_f32_e32 v117, v117
	v_mul_f32_e32 v110, 0xbfb8aa3b, v110
	v_mul_f32_e32 v111, 0xbfb8aa3b, v111
	v_exp_f32_e32 v110, v110
	v_exp_f32_e32 v111, v111
	v_mul_f32_e32 v112, 0xbfb8aa3b, v112
	v_exp_f32_e32 v112, v112
	v_add_f32_e32 v110, 1.0, v110
	v_add_f32_e32 v111, 1.0, v111
	v_rcp_f32_e32 v110, v110
	v_rcp_f32_e32 v111, v111
	v_mul_f32_e32 v113, 0xbfb8aa3b, v113
	v_exp_f32_e32 v113, v113
	v_mul_f32_e32 v106, 0xbfb8aa3b, v106
	s_and_b64 s[98:99], exec, s[4:5]
	s_cbranch_scc0 .Lal_2
	s_barrier
.Lal_2:
	s_waitcnt vmcnt(0)
	v_lshlrev_b32_e32 v174, 16, v156
	v_and_b32_e32 v156, 0xffff0000, v156
	v_lshlrev_b32_e32 v175, 16, v157
	v_and_b32_e32 v157, 0xffff0000, v157
	v_mul_f32_e32 v126, v126, v174
	v_mul_f32_e32 v127, v127, v156
	v_lshlrev_b32_e32 v176, 16, v158
	v_and_b32_e32 v158, 0xffff0000, v158
	v_lshlrev_b32_e32 v177, 16, v159
	v_and_b32_e32 v159, 0xffff0000, v159
	v_mul_f32_e32 v128, v128, v175
	v_mul_f32_e32 v129, v129, v157
	v_cvt_pk_bf16_f32 v126, v126, v127
	v_cvt_pk_bf16_f32 v127, v128, v129
	v_mul_f32_e32 v149, v149, v176
	v_mul_f32_e32 v155, v155, v158
	v_mul_f32_e32 v156, v168, v177
	v_mul_f32_e32 v157, v173, v159
	v_cvt_pk_bf16_f32 v128, v149, v155
	v_cvt_pk_bf16_f32 v129, v156, v157
	global_store_dwordx4 v[166:167], v[126:129], off offset:1024
	v_lshlrev_b32_e32 v178, 16, v160
	v_and_b32_e32 v160, 0xffff0000, v160
	v_add_f32_e32 v127, 1.0, v171
	v_rcp_f32_e32 v127, v127
	v_add_f32_e32 v128, 1.0, v172
	v_rcp_f32_e32 v128, v128
	v_lshlrev_b32_e32 v129, 16, v161
	v_mul_f32_e32 v127, v127, v129
	v_and_b32_e32 v129, 0xffff0000, v161
	v_mul_f32_e32 v128, v128, v129
	v_mul_f32_e32 v158, v169, v178
	v_mul_f32_e32 v159, v170, v160
	v_cvt_pk_bf16_f32 v126, v158, v159
	v_cvt_pk_bf16_f32 v127, v127, v128
	v_lshlrev_b32_e32 v128, 16, v162
	v_mul_f32_e32 v114, v114, v128
	v_and_b32_e32 v128, 0xffff0000, v162
	v_mul_f32_e32 v115, v115, v128
	v_cvt_pk_bf16_f32 v128, v114, v115
	v_add_f32_e32 v114, 1.0, v116
	v_rcp_f32_e32 v114, v114
	v_add_f32_e32 v115, 1.0, v117
	v_rcp_f32_e32 v115, v115
	v_lshlrev_b32_e32 v116, 16, v163
	v_mul_f32_e32 v114, v114, v116
	v_and_b32_e32 v116, 0xffff0000, v163
	v_or_b32_e32 v156, 32, v148
	v_mul_f32_e32 v115, v115, v116
	v_ashrrev_i32_e32 v157, 31, v156
	v_cvt_pk_bf16_f32 v129, v114, v115
	v_lshlrev_b64 v[114:115], 10, v[156:157]
	v_lshl_add_u64 v[114:115], s[8:9], 0, v[114:115]
	v_lshlrev_b32_e32 v149, 16, v122
	v_and_b32_e32 v122, 0xffff0000, v122
	global_store_dwordx4 v[166:167], v[126:129], off offset:1280
	v_mul_f32_e32 v110, v110, v149
	v_mul_f32_e32 v111, v111, v122
	v_lshl_add_u64 v[126:127], v[114:115], 0, v[146:147]
	v_exp_f32_e32 v106, v106
	v_mul_f32_e32 v107, 0xbfb8aa3b, v107
	global_load_dwordx4 v[114:117], v[126:127], off offset:256
	s_nop 0
	global_load_dwordx4 v[126:129], v[126:127], off
	v_cvt_pk_bf16_f32 v110, v110, v111
	v_add_f32_e32 v111, 1.0, v112
	v_exp_f32_e32 v107, v107
	v_rcp_f32_e32 v111, v111
	v_add_f32_e32 v112, 1.0, v113
	v_rcp_f32_e32 v112, v112
	v_add_f32_e32 v106, 1.0, v106
	v_lshlrev_b32_e32 v113, 16, v123
; __device__ __forceinline__ unsigned cvt_pk_bf16(float lo, float hi) { unsigned r; asm volatile("v_cvt_pk_bf16_f32 %0, %1, %2" : "=v"(r) : "v"(lo), "v"(hi)); return r; }
; __device__ __forceinline__ float bflo(unsigned w) { return __uint_as_float(w << 16); }
; __device__ __forceinline__ float bfhi(unsigned w) { return __uint_as_float(w & 0xffff0000u); }
; __device__ __forceinline__ float sigm(float x) { return __builtin_amdgcn_rcpf(1.f + __expf(-x)); }
;     __device__ __forceinline__ void operator()(const pg8::f32x4 (&acc)[2][2][4][2], const Unit& u, int wr, int wc, int fr, int fq) const {
;     ...
;         for (int k = 0; k < 8; ++k) { const int ai = k >> 2, m = k & 3; const int row = row0 + ai * HALF + m * 16; v4u cy[2];
; #pragma unroll
;             for (int bj = 0; bj < 2; ++bj) cy[bj] = ny[bj];
;             if (k < 7) {
; #pragma unroll
;                 for (int bj = 0; bj < 2; ++bj) ny[bj] = *(const v4u*)(Y + (size_t)(row0 + ((k + 1) >> 2) * HALF + ((k + 1) & 3) * 16) * 512 + col0 + bj * HALF); }
; #pragma unroll
;             for (int bj = 0; bj < 2; ++bj) { const int col = col0 + bj * HALF; const v4u yw = cy[bj]; const f32x4 a0 = acc[ai][bj][m][0], a1 = acc[ai][bj][m][1];
;                 v4u w; w.x = cvt_pk_bf16(bflo(yw.x) * sigm(a0[0]), bfhi(yw.x) * sigm(a0[1])); w.y = cvt_pk_bf16(bflo(yw.y) * sigm(a0[2]), bfhi(yw.y) * sigm(a0[3]));
;                 w.z = cvt_pk_bf16(bflo(yw.z) * sigm(a1[0]), bfhi(yw.z) * sigm(a1[1])); w.w = cvt_pk_bf16(bflo(yw.w) * sigm(a1[2]), bfhi(yw.w) * sigm(a1[3]));
;                 *(v4u*)(O + (size_t)row * DM_ + 512 + col) = w; } }
	v_rcp_f32_e32 v106, v106
	v_add_f32_e32 v107, 1.0, v107
	v_mul_f32_e32 v108, 0xbfb8aa3b, v108
	v_mul_f32_e32 v111, v111, v113
	v_and_b32_e32 v113, 0xffff0000, v123
	v_rcp_f32_e32 v107, v107
	v_exp_f32_e32 v108, v108
	v_mul_f32_e32 v109, 0xbfb8aa3b, v109
	v_mul_f32_e32 v112, v112, v113
	v_exp_f32_e32 v109, v109
	v_mul_f32_e32 v102, 0xbfb8aa3b, v102
	v_cvt_pk_bf16_f32 v111, v111, v112
	v_lshlrev_b32_e32 v112, 16, v124
	v_exp_f32_e32 v102, v102
	v_mul_f32_e32 v103, 0xbfb8aa3b, v103
	v_mul_f32_e32 v106, v106, v112
	v_and_b32_e32 v112, 0xffff0000, v124
	v_exp_f32_e32 v103, v103
	v_mul_f32_e32 v107, v107, v112
	v_cvt_pk_bf16_f32 v112, v106, v107
	v_add_f32_e32 v106, 1.0, v108
	v_rcp_f32_e32 v106, v106
	v_add_f32_e32 v107, 1.0, v109
	v_rcp_f32_e32 v107, v107
	v_add_f32_e32 v102, 1.0, v102
	v_rcp_f32_e32 v102, v102
	v_add_f32_e32 v103, 1.0, v103
	v_lshlrev_b32_e32 v108, 16, v125
	v_rcp_f32_e32 v103, v103
	v_mul_f32_e32 v104, 0xbfb8aa3b, v104
	v_mul_f32_e32 v106, v106, v108
	v_and_b32_e32 v108, 0xffff0000, v125
	v_exp_f32_e32 v104, v104
	v_mul_f32_e32 v105, 0xbfb8aa3b, v105
	v_lshlrev_b64 v[158:159], 11, v[164:165]
	v_mul_f32_e32 v107, v107, v108
	v_lshlrev_b32_e32 v108, 16, v118
	v_exp_f32_e32 v105, v105
	v_cvt_pk_bf16_f32 v113, v106, v107
	v_lshl_add_u64 v[106:107], s[12:13], 0, v[158:159]
	v_mul_f32_e32 v102, v102, v108
	v_and_b32_e32 v108, 0xffff0000, v118
	v_mul_f32_e32 v98, 0xbfb8aa3b, v98
	v_lshl_add_u64 v[106:107], v[106:107], 0, v[146:147]
	v_mul_f32_e32 v103, v103, v108
	v_exp_f32_e32 v98, v98
	v_mul_f32_e32 v99, 0xbfb8aa3b, v99
	global_store_dwordx4 v[106:107], v[110:113], off offset:1024
	v_cvt_pk_bf16_f32 v102, v102, v103
	v_add_f32_e32 v103, 1.0, v104
	v_exp_f32_e32 v99, v99
	v_rcp_f32_e32 v103, v103
	v_add_f32_e32 v104, 1.0, v105
	v_rcp_f32_e32 v104, v104
	v_add_f32_e32 v98, 1.0, v98
	v_lshlrev_b32_e32 v105, 16, v119
	v_rcp_f32_e32 v98, v98
	v_add_f32_e32 v99, 1.0, v99
	v_mul_f32_e32 v100, 0xbfb8aa3b, v100
	v_mul_f32_e32 v103, v103, v105
	v_and_b32_e32 v105, 0xffff0000, v119
	v_rcp_f32_e32 v99, v99
	v_exp_f32_e32 v100, v100
	v_mul_f32_e32 v101, 0xbfb8aa3b, v101
	v_mul_f32_e32 v104, v104, v105
	v_exp_f32_e32 v101, v101
	v_cvt_pk_bf16_f32 v103, v103, v104
	v_lshlrev_b32_e32 v104, 16, v120
	v_mul_f32_e32 v98, v98, v104
	v_and_b32_e32 v104, 0xffff0000, v120
	v_mul_f32_e32 v99, v99, v104
	v_cvt_pk_bf16_f32 v104, v98, v99
	v_add_f32_e32 v98, 1.0, v100
	v_rcp_f32_e32 v98, v98
	v_add_f32_e32 v99, 1.0, v101
	v_rcp_f32_e32 v99, v99
	v_lshlrev_b32_e32 v100, 16, v121
	v_mul_f32_e32 v98, v98, v100
	v_and_b32_e32 v100, 0xffff0000, v121
	v_mul_f32_e32 v99, v99, v100
	v_cvt_pk_bf16_f32 v105, v98, v99
	global_store_dwordx4 v[106:107], v[102:105], off offset:1280
	v_or_b32_e32 v106, 48, v148
	v_ashrrev_i32_e32 v107, 31, v106
	v_lshlrev_b64 v[98:99], 10, v[106:107]
	v_lshl_add_u64 v[98:99], s[8:9], 0, v[98:99]
	v_lshl_add_u64 v[102:103], v[98:99], 0, v[146:147]
	global_load_dwordx4 v[98:101], v[102:103], off offset:256
	s_nop 0
	global_load_dwordx4 v[102:105], v[102:103], off
	v_mul_f32_e32 v94, 0xbfb8aa3b, v94
	v_exp_f32_e32 v94, v94
	v_mul_f32_e32 v95, 0xbfb8aa3b, v95
	v_exp_f32_e32 v95, v95
	v_mul_f32_e32 v96, 0xbfb8aa3b, v96
	v_add_f32_e32 v94, 1.0, v94
	v_rcp_f32_e32 v94, v94
	v_add_f32_e32 v95, 1.0, v95
	v_rcp_f32_e32 v95, v95
	v_exp_f32_e32 v96, v96
	v_mul_f32_e32 v97, 0xbfb8aa3b, v97
	s_waitcnt vmcnt(4)
	v_lshlrev_b32_e32 v110, 16, v126
	v_exp_f32_e32 v97, v97
	v_mul_f32_e32 v94, v94, v110
	v_and_b32_e32 v110, 0xffff0000, v126
	v_mul_f32_e32 v90, 0xbfb8aa3b, v90
	v_mul_f32_e32 v95, v95, v110
	v_exp_f32_e32 v90, v90
	v_mul_f32_e32 v91, 0xbfb8aa3b, v91
	v_cvt_pk_bf16_f32 v94, v94, v95
	v_add_f32_e32 v95, 1.0, v96
	v_exp_f32_e32 v91, v91
	v_rcp_f32_e32 v95, v95
	v_add_f32_e32 v96, 1.0, v97
	v_rcp_f32_e32 v96, v96
	v_add_f32_e32 v90, 1.0, v90
	v_lshlrev_b32_e32 v97, 16, v127
	v_rcp_f32_e32 v90, v90
	v_add_f32_e32 v91, 1.0, v91
	v_mul_f32_e32 v92, 0xbfb8aa3b, v92
	v_mul_f32_e32 v95, v95, v97
	v_and_b32_e32 v97, 0xffff0000, v127
	v_rcp_f32_e32 v91, v91
	v_exp_f32_e32 v92, v92
	v_mul_f32_e32 v93, 0xbfb8aa3b, v93
	v_mul_f32_e32 v96, v96, v97
	v_exp_f32_e32 v93, v93
	v_mul_f32_e32 v86, 0xbfb8aa3b, v86
	v_cvt_pk_bf16_f32 v95, v95, v96
	v_lshlrev_b32_e32 v96, 16, v128
	v_exp_f32_e32 v86, v86
	v_mul_f32_e32 v87, 0xbfb8aa3b, v87
	v_mul_f32_e32 v90, v90, v96
	v_and_b32_e32 v96, 0xffff0000, v128
	v_exp_f32_e32 v87, v87
	v_mul_f32_e32 v91, v91, v96
	v_cvt_pk_bf16_f32 v96, v90, v91
	v_add_f32_e32 v90, 1.0, v92
	v_rcp_f32_e32 v90, v90
	v_add_f32_e32 v91, 1.0, v93
	v_rcp_f32_e32 v91, v91
	v_add_f32_e32 v86, 1.0, v86
	v_rcp_f32_e32 v86, v86
	v_add_f32_e32 v87, 1.0, v87
	v_lshlrev_b32_e32 v92, 16, v129
	v_rcp_f32_e32 v87, v87
	v_mul_f32_e32 v88, 0xbfb8aa3b, v88
	v_mul_f32_e32 v90, v90, v92
	v_and_b32_e32 v92, 0xffff0000, v129
	v_exp_f32_e32 v88, v88
	v_mul_f32_e32 v89, 0xbfb8aa3b, v89
	v_lshlrev_b64 v[108:109], 11, v[156:157]
	v_mul_f32_e32 v91, v91, v92
	v_lshlrev_b32_e32 v92, 16, v114
	v_exp_f32_e32 v89, v89
	v_cvt_pk_bf16_f32 v97, v90, v91
	v_lshl_add_u64 v[90:91], s[12:13], 0, v[108:109]
	v_mul_f32_e32 v86, v86, v92
	v_and_b32_e32 v92, 0xffff0000, v114
	v_mul_f32_e32 v82, 0xbfb8aa3b, v82
	v_lshl_add_u64 v[90:91], v[90:91], 0, v[146:147]
	v_mul_f32_e32 v87, v87, v92
	v_exp_f32_e32 v82, v82
	v_mul_f32_e32 v83, 0xbfb8aa3b, v83
	global_store_dwordx4 v[90:91], v[94:97], off offset:1024
	v_cvt_pk_bf16_f32 v86, v86, v87
	v_add_f32_e32 v87, 1.0, v88
	v_exp_f32_e32 v83, v83
	v_rcp_f32_e32 v87, v87
	v_add_f32_e32 v88, 1.0, v89
	v_rcp_f32_e32 v88, v88
	v_add_f32_e32 v82, 1.0, v82
	v_lshlrev_b32_e32 v89, 16, v115
	v_rcp_f32_e32 v82, v82
	v_add_f32_e32 v83, 1.0, v83
	v_mul_f32_e32 v84, 0xbfb8aa3b, v84
	v_mul_f32_e32 v87, v87, v89
	v_and_b32_e32 v89, 0xffff0000, v115
	v_rcp_f32_e32 v83, v83
	v_exp_f32_e32 v84, v84
	v_mul_f32_e32 v85, 0xbfb8aa3b, v85
	v_mul_f32_e32 v88, v88, v89
	v_exp_f32_e32 v85, v85
	v_cvt_pk_bf16_f32 v87, v87, v88
	v_lshlrev_b32_e32 v88, 16, v116
	v_mul_f32_e32 v82, v82, v88
	v_and_b32_e32 v88, 0xffff0000, v116
	v_mul_f32_e32 v78, 0xbfb8aa3b, v78
	v_mul_f32_e32 v83, v83, v88
	v_cvt_pk_bf16_f32 v88, v82, v83
	v_add_f32_e32 v82, 1.0, v84
	v_exp_f32_e32 v78, v78
	v_mul_f32_e32 v79, 0xbfb8aa3b, v79
	v_rcp_f32_e32 v82, v82
	v_add_f32_e32 v83, 1.0, v85
	v_exp_f32_e32 v79, v79
	v_rcp_f32_e32 v83, v83
	v_lshlrev_b32_e32 v84, 16, v117
	v_add_f32_e32 v78, 1.0, v78
	v_mul_f32_e32 v82, v82, v84
	v_and_b32_e32 v84, 0xffff0000, v117
	v_rcp_f32_e32 v78, v78
	v_add_f32_e32 v79, 1.0, v79
	v_mul_f32_e32 v83, v83, v84
	v_cvt_pk_bf16_f32 v89, v82, v83
	global_store_dwordx4 v[90:91], v[86:89], off offset:1280
	v_add_u32_e32 v90, 0x80, v148
	v_rcp_f32_e32 v79, v79
	v_mul_f32_e32 v80, 0xbfb8aa3b, v80
	v_ashrrev_i32_e32 v91, 31, v90
	v_exp_f32_e32 v80, v80
	v_mul_f32_e32 v81, 0xbfb8aa3b, v81
	v_lshlrev_b64 v[82:83], 10, v[90:91]
	s_waitcnt vmcnt(2)
; __device__ __forceinline__ unsigned cvt_pk_bf16(float lo, float hi) { unsigned r; asm volatile("v_cvt_pk_bf16_f32 %0, %1, %2" : "=v"(r) : "v"(lo), "v"(hi)); return r; }
; __device__ __forceinline__ float bflo(unsigned w) { return __uint_as_float(w << 16); }
; __device__ __forceinline__ float bfhi(unsigned w) { return __uint_as_float(w & 0xffff0000u); }
; __device__ __forceinline__ float sigm(float x) { return __builtin_amdgcn_rcpf(1.f + __expf(-x)); }
;     __device__ __forceinline__ void operator()(const pg8::f32x4 (&acc)[2][2][4][2], const Unit& u, int wr, int wc, int fr, int fq) const {
;     ...
;         for (int k = 0; k < 8; ++k) { const int ai = k >> 2, m = k & 3; const int row = row0 + ai * HALF + m * 16; v4u cy[2];
; #pragma unroll
;             for (int bj = 0; bj < 2; ++bj) cy[bj] = ny[bj];
;             if (k < 7) {
; #pragma unroll
;                 for (int bj = 0; bj < 2; ++bj) ny[bj] = *(const v4u*)(Y + (size_t)(row0 + ((k + 1) >> 2) * HALF + ((k + 1) & 3) * 16) * 512 + col0 + bj * HALF); }
; #pragma unroll
;             for (int bj = 0; bj < 2; ++bj) { const int col = col0 + bj * HALF; const v4u yw = cy[bj]; const f32x4 a0 = acc[ai][bj][m][0], a1 = acc[ai][bj][m][1];
;                 v4u w; w.x = cvt_pk_bf16(bflo(yw.x) * sigm(a0[0]), bfhi(yw.x) * sigm(a0[1])); w.y = cvt_pk_bf16(bflo(yw.y) * sigm(a0[2]), bfhi(yw.y) * sigm(a0[3]));
;                 w.z = cvt_pk_bf16(bflo(yw.z) * sigm(a1[0]), bfhi(yw.z) * sigm(a1[1])); w.w = cvt_pk_bf16(bflo(yw.w) * sigm(a1[2]), bfhi(yw.w) * sigm(a1[3]));
;                 *(v4u*)(O + (size_t)row * DM_ + 512 + col) = w; } }
	v_lshlrev_b32_e32 v94, 16, v102
	v_exp_f32_e32 v81, v81
	v_lshl_add_u64 v[82:83], s[8:9], 0, v[82:83]
	v_mul_f32_e32 v78, v78, v94
	v_and_b32_e32 v94, 0xffff0000, v102
	v_mul_f32_e32 v74, 0xbfb8aa3b, v74
	v_lshl_add_u64 v[86:87], v[82:83], 0, v[146:147]
	v_mul_f32_e32 v79, v79, v94
	v_exp_f32_e32 v74, v74
	v_mul_f32_e32 v75, 0xbfb8aa3b, v75
	global_load_dwordx4 v[82:85], v[86:87], off offset:256
	s_nop 0
	global_load_dwordx4 v[86:89], v[86:87], off
	v_cvt_pk_bf16_f32 v78, v78, v79
	v_add_f32_e32 v79, 1.0, v80
	v_exp_f32_e32 v75, v75
	v_rcp_f32_e32 v79, v79
	v_add_f32_e32 v80, 1.0, v81
	v_rcp_f32_e32 v80, v80
	v_add_f32_e32 v74, 1.0, v74
	v_lshlrev_b32_e32 v81, 16, v103
	v_rcp_f32_e32 v74, v74
	v_add_f32_e32 v75, 1.0, v75
	v_mul_f32_e32 v76, 0xbfb8aa3b, v76
	v_mul_f32_e32 v79, v79, v81
	v_and_b32_e32 v81, 0xffff0000, v103
	v_rcp_f32_e32 v75, v75
	v_exp_f32_e32 v76, v76
	v_mul_f32_e32 v77, 0xbfb8aa3b, v77
	v_mul_f32_e32 v80, v80, v81
	v_exp_f32_e32 v77, v77
	v_mul_f32_e32 v70, 0xbfb8aa3b, v70
	v_cvt_pk_bf16_f32 v79, v79, v80
	v_lshlrev_b32_e32 v80, 16, v104
	v_exp_f32_e32 v70, v70
	v_mul_f32_e32 v71, 0xbfb8aa3b, v71
	v_mul_f32_e32 v74, v74, v80
	v_and_b32_e32 v80, 0xffff0000, v104
	v_exp_f32_e32 v71, v71
	v_mul_f32_e32 v75, v75, v80
	v_cvt_pk_bf16_f32 v80, v74, v75
	v_add_f32_e32 v74, 1.0, v76
	v_rcp_f32_e32 v74, v74
	v_add_f32_e32 v75, 1.0, v77
	v_rcp_f32_e32 v75, v75
	v_add_f32_e32 v70, 1.0, v70
	v_rcp_f32_e32 v70, v70
	v_add_f32_e32 v71, 1.0, v71
	v_lshlrev_b32_e32 v76, 16, v105
	v_rcp_f32_e32 v71, v71
	v_mul_f32_e32 v72, 0xbfb8aa3b, v72
	v_mul_f32_e32 v74, v74, v76
	v_and_b32_e32 v76, 0xffff0000, v105
	v_exp_f32_e32 v72, v72
	v_mul_f32_e32 v73, 0xbfb8aa3b, v73
	v_lshlrev_b64 v[92:93], 11, v[106:107]
	v_mul_f32_e32 v75, v75, v76
	v_lshlrev_b32_e32 v76, 16, v98
	v_exp_f32_e32 v73, v73
	v_cvt_pk_bf16_f32 v81, v74, v75
	v_lshl_add_u64 v[74:75], s[12:13], 0, v[92:93]
	v_mul_f32_e32 v70, v70, v76
	v_and_b32_e32 v76, 0xffff0000, v98
	v_mul_f32_e32 v66, 0xbfb8aa3b, v66
	v_lshl_add_u64 v[74:75], v[74:75], 0, v[146:147]
	v_mul_f32_e32 v71, v71, v76
	v_exp_f32_e32 v66, v66
	v_mul_f32_e32 v67, 0xbfb8aa3b, v67
	global_store_dwordx4 v[74:75], v[78:81], off offset:1024
	v_cvt_pk_bf16_f32 v70, v70, v71
	v_add_f32_e32 v71, 1.0, v72
	v_exp_f32_e32 v67, v67
	v_rcp_f32_e32 v71, v71
	v_add_f32_e32 v72, 1.0, v73
	v_rcp_f32_e32 v72, v72
	v_add_f32_e32 v66, 1.0, v66
	v_lshlrev_b32_e32 v73, 16, v99
	v_rcp_f32_e32 v66, v66
	v_add_f32_e32 v67, 1.0, v67
	v_mul_f32_e32 v68, 0xbfb8aa3b, v68
	v_mul_f32_e32 v71, v71, v73
	v_and_b32_e32 v73, 0xffff0000, v99
	v_rcp_f32_e32 v67, v67
	v_exp_f32_e32 v68, v68
	v_mul_f32_e32 v69, 0xbfb8aa3b, v69
	v_mul_f32_e32 v72, v72, v73
	v_exp_f32_e32 v69, v69
	v_cvt_pk_bf16_f32 v71, v71, v72
	v_lshlrev_b32_e32 v72, 16, v100
	v_mul_f32_e32 v66, v66, v72
	v_and_b32_e32 v72, 0xffff0000, v100
	v_mul_f32_e32 v67, v67, v72
	v_cvt_pk_bf16_f32 v72, v66, v67
	v_add_f32_e32 v66, 1.0, v68
	v_rcp_f32_e32 v66, v66
	v_add_f32_e32 v67, 1.0, v69
	v_rcp_f32_e32 v67, v67
	v_lshlrev_b32_e32 v68, 16, v101
	v_mul_f32_e32 v66, v66, v68
	v_and_b32_e32 v68, 0xffff0000, v101
	v_mul_f32_e32 v67, v67, v68
	v_cvt_pk_bf16_f32 v73, v66, v67
	global_store_dwordx4 v[74:75], v[70:73], off offset:1280
	v_add_u32_e32 v74, 0x90, v148
	v_ashrrev_i32_e32 v75, 31, v74
	v_lshlrev_b64 v[66:67], 10, v[74:75]
	v_lshl_add_u64 v[66:67], s[8:9], 0, v[66:67]
	v_lshl_add_u64 v[70:71], v[66:67], 0, v[146:147]
	global_load_dwordx4 v[66:69], v[70:71], off offset:256
	s_nop 0
	global_load_dwordx4 v[70:73], v[70:71], off
	v_mul_f32_e32 v62, 0xbfb8aa3b, v62
	v_exp_f32_e32 v62, v62
	v_mul_f32_e32 v63, 0xbfb8aa3b, v63
	v_exp_f32_e32 v63, v63
	v_mul_f32_e32 v64, 0xbfb8aa3b, v64
	v_add_f32_e32 v62, 1.0, v62
	v_rcp_f32_e32 v62, v62
	v_add_f32_e32 v63, 1.0, v63
	v_rcp_f32_e32 v63, v63
	v_exp_f32_e32 v64, v64
	v_mul_f32_e32 v65, 0xbfb8aa3b, v65
	s_waitcnt vmcnt(4)
	v_lshlrev_b32_e32 v78, 16, v86
	v_exp_f32_e32 v65, v65
	v_mul_f32_e32 v62, v62, v78
	v_and_b32_e32 v78, 0xffff0000, v86
	v_mul_f32_e32 v58, 0xbfb8aa3b, v58
	v_mul_f32_e32 v63, v63, v78
	v_exp_f32_e32 v58, v58
	v_mul_f32_e32 v59, 0xbfb8aa3b, v59
	v_cvt_pk_bf16_f32 v62, v62, v63
	v_add_f32_e32 v63, 1.0, v64
	v_exp_f32_e32 v59, v59
	v_rcp_f32_e32 v63, v63
	v_add_f32_e32 v64, 1.0, v65
	v_rcp_f32_e32 v64, v64
	v_add_f32_e32 v58, 1.0, v58
	v_lshlrev_b32_e32 v65, 16, v87
	v_rcp_f32_e32 v58, v58
	v_add_f32_e32 v59, 1.0, v59
	v_mul_f32_e32 v60, 0xbfb8aa3b, v60
	v_mul_f32_e32 v63, v63, v65
	v_and_b32_e32 v65, 0xffff0000, v87
	v_rcp_f32_e32 v59, v59
	v_exp_f32_e32 v60, v60
	v_mul_f32_e32 v61, 0xbfb8aa3b, v61
	v_mul_f32_e32 v64, v64, v65
	v_exp_f32_e32 v61, v61
	v_mul_f32_e32 v54, 0xbfb8aa3b, v54
	v_cvt_pk_bf16_f32 v63, v63, v64
	v_lshlrev_b32_e32 v64, 16, v88
	v_exp_f32_e32 v54, v54
	v_mul_f32_e32 v55, 0xbfb8aa3b, v55
	v_mul_f32_e32 v58, v58, v64
	v_and_b32_e32 v64, 0xffff0000, v88
	v_exp_f32_e32 v55, v55
	v_mul_f32_e32 v59, v59, v64
	v_cvt_pk_bf16_f32 v64, v58, v59
	v_add_f32_e32 v58, 1.0, v60
	v_rcp_f32_e32 v58, v58
	v_add_f32_e32 v59, 1.0, v61
	v_rcp_f32_e32 v59, v59
	v_add_f32_e32 v54, 1.0, v54
	v_rcp_f32_e32 v54, v54
	v_add_f32_e32 v55, 1.0, v55
	v_lshlrev_b32_e32 v60, 16, v89
	v_rcp_f32_e32 v55, v55
	v_mul_f32_e32 v56, 0xbfb8aa3b, v56
	v_mul_f32_e32 v58, v58, v60
	v_and_b32_e32 v60, 0xffff0000, v89
	v_exp_f32_e32 v56, v56
	v_mul_f32_e32 v57, 0xbfb8aa3b, v57
	v_lshlrev_b64 v[76:77], 11, v[90:91]
	v_mul_f32_e32 v59, v59, v60
	v_lshlrev_b32_e32 v60, 16, v82
	v_exp_f32_e32 v57, v57
	v_cvt_pk_bf16_f32 v65, v58, v59
	v_lshl_add_u64 v[58:59], s[12:13], 0, v[76:77]
	v_mul_f32_e32 v54, v54, v60
	v_and_b32_e32 v60, 0xffff0000, v82
; __device__ __forceinline__ unsigned cvt_pk_bf16(float lo, float hi) { unsigned r; asm volatile("v_cvt_pk_bf16_f32 %0, %1, %2" : "=v"(r) : "v"(lo), "v"(hi)); return r; }
; __device__ __forceinline__ float bflo(unsigned w) { return __uint_as_float(w << 16); }
; __device__ __forceinline__ float bfhi(unsigned w) { return __uint_as_float(w & 0xffff0000u); }
; __device__ __forceinline__ float sigm(float x) { return __builtin_amdgcn_rcpf(1.f + __expf(-x)); }
;     __device__ __forceinline__ void operator()(const pg8::f32x4 (&acc)[2][2][4][2], const Unit& u, int wr, int wc, int fr, int fq) const {
;     ...
;         for (int k = 0; k < 8; ++k) { const int ai = k >> 2, m = k & 3; const int row = row0 + ai * HALF + m * 16; v4u cy[2];
; #pragma unroll
;             for (int bj = 0; bj < 2; ++bj) cy[bj] = ny[bj];
;             if (k < 7) {
; #pragma unroll
;                 for (int bj = 0; bj < 2; ++bj) ny[bj] = *(const v4u*)(Y + (size_t)(row0 + ((k + 1) >> 2) * HALF + ((k + 1) & 3) * 16) * 512 + col0 + bj * HALF); }
; #pragma unroll
;             for (int bj = 0; bj < 2; ++bj) { const int col = col0 + bj * HALF; const v4u yw = cy[bj]; const f32x4 a0 = acc[ai][bj][m][0], a1 = acc[ai][bj][m][1];
;                 v4u w; w.x = cvt_pk_bf16(bflo(yw.x) * sigm(a0[0]), bfhi(yw.x) * sigm(a0[1])); w.y = cvt_pk_bf16(bflo(yw.y) * sigm(a0[2]), bfhi(yw.y) * sigm(a0[3]));
;                 w.z = cvt_pk_bf16(bflo(yw.z) * sigm(a1[0]), bfhi(yw.z) * sigm(a1[1])); w.w = cvt_pk_bf16(bflo(yw.w) * sigm(a1[2]), bfhi(yw.w) * sigm(a1[3]));
;                 *(v4u*)(O + (size_t)row * DM_ + 512 + col) = w; } }
	v_mul_f32_e32 v50, 0xbfb8aa3b, v50
	v_lshl_add_u64 v[58:59], v[58:59], 0, v[146:147]
	v_mul_f32_e32 v55, v55, v60
	v_exp_f32_e32 v50, v50
	v_mul_f32_e32 v51, 0xbfb8aa3b, v51
	global_store_dwordx4 v[58:59], v[62:65], off offset:1024
	v_cvt_pk_bf16_f32 v54, v54, v55
	v_add_f32_e32 v55, 1.0, v56
	v_exp_f32_e32 v51, v51
	v_rcp_f32_e32 v55, v55
	v_add_f32_e32 v56, 1.0, v57
	v_rcp_f32_e32 v56, v56
	v_add_f32_e32 v50, 1.0, v50
	v_lshlrev_b32_e32 v57, 16, v83
	v_rcp_f32_e32 v50, v50
	v_add_f32_e32 v51, 1.0, v51
	v_mul_f32_e32 v52, 0xbfb8aa3b, v52
	v_mul_f32_e32 v55, v55, v57
	v_and_b32_e32 v57, 0xffff0000, v83
	v_rcp_f32_e32 v51, v51
	v_exp_f32_e32 v52, v52
	v_mul_f32_e32 v53, 0xbfb8aa3b, v53
	v_mul_f32_e32 v56, v56, v57
	v_exp_f32_e32 v53, v53
	v_cvt_pk_bf16_f32 v55, v55, v56
	v_lshlrev_b32_e32 v56, 16, v84
	v_mul_f32_e32 v50, v50, v56
	v_and_b32_e32 v56, 0xffff0000, v84
	v_mul_f32_e32 v46, 0xbfb8aa3b, v46
	v_mul_f32_e32 v51, v51, v56
	v_cvt_pk_bf16_f32 v56, v50, v51
	v_add_f32_e32 v50, 1.0, v52
	v_exp_f32_e32 v46, v46
	v_mul_f32_e32 v47, 0xbfb8aa3b, v47
	v_rcp_f32_e32 v50, v50
	v_add_f32_e32 v51, 1.0, v53
	v_exp_f32_e32 v47, v47
	v_rcp_f32_e32 v51, v51
	v_lshlrev_b32_e32 v52, 16, v85
	v_add_f32_e32 v46, 1.0, v46
	v_mul_f32_e32 v50, v50, v52
	v_and_b32_e32 v52, 0xffff0000, v85
	v_rcp_f32_e32 v46, v46
	v_add_f32_e32 v47, 1.0, v47
	v_mul_f32_e32 v51, v51, v52
	v_cvt_pk_bf16_f32 v57, v50, v51
	global_store_dwordx4 v[58:59], v[54:57], off offset:1280
	v_add_u32_e32 v58, 0xa0, v148
	v_rcp_f32_e32 v47, v47
	v_mul_f32_e32 v48, 0xbfb8aa3b, v48
	v_ashrrev_i32_e32 v59, 31, v58
	v_exp_f32_e32 v48, v48
	v_mul_f32_e32 v49, 0xbfb8aa3b, v49
	v_lshlrev_b64 v[50:51], 10, v[58:59]
	s_waitcnt vmcnt(2)
	v_lshlrev_b32_e32 v62, 16, v70
	v_exp_f32_e32 v49, v49
	v_lshl_add_u64 v[50:51], s[8:9], 0, v[50:51]
	v_mul_f32_e32 v46, v46, v62
	v_and_b32_e32 v62, 0xffff0000, v70
	v_mul_f32_e32 v42, 0xbfb8aa3b, v42
	v_lshl_add_u64 v[54:55], v[50:51], 0, v[146:147]
	v_mul_f32_e32 v47, v47, v62
	v_exp_f32_e32 v42, v42
	v_mul_f32_e32 v43, 0xbfb8aa3b, v43
	global_load_dwordx4 v[50:53], v[54:55], off offset:256
	s_nop 0
	global_load_dwordx4 v[54:57], v[54:55], off
	v_cvt_pk_bf16_f32 v46, v46, v47
	v_add_f32_e32 v47, 1.0, v48
	v_exp_f32_e32 v43, v43
	v_rcp_f32_e32 v47, v47
	v_add_f32_e32 v48, 1.0, v49
	v_rcp_f32_e32 v48, v48
	v_add_f32_e32 v42, 1.0, v42
	v_lshlrev_b32_e32 v49, 16, v71
	v_rcp_f32_e32 v42, v42
	v_add_f32_e32 v43, 1.0, v43
	v_mul_f32_e32 v44, 0xbfb8aa3b, v44
	v_mul_f32_e32 v47, v47, v49
	v_and_b32_e32 v49, 0xffff0000, v71
	v_rcp_f32_e32 v43, v43
	v_exp_f32_e32 v44, v44
	v_mul_f32_e32 v45, 0xbfb8aa3b, v45
	v_mul_f32_e32 v48, v48, v49
	v_exp_f32_e32 v45, v45
	v_mul_f32_e32 v38, 0xbfb8aa3b, v38
	v_cvt_pk_bf16_f32 v47, v47, v48
	v_lshlrev_b32_e32 v48, 16, v72
	v_exp_f32_e32 v38, v38
	v_mul_f32_e32 v39, 0xbfb8aa3b, v39
	v_mul_f32_e32 v42, v42, v48
	v_and_b32_e32 v48, 0xffff0000, v72
	v_exp_f32_e32 v39, v39
	v_mul_f32_e32 v43, v43, v48
	v_cvt_pk_bf16_f32 v48, v42, v43
	v_add_f32_e32 v42, 1.0, v44
	v_rcp_f32_e32 v42, v42
	v_add_f32_e32 v43, 1.0, v45
	v_rcp_f32_e32 v43, v43
	v_add_f32_e32 v38, 1.0, v38
	v_rcp_f32_e32 v38, v38
	v_add_f32_e32 v39, 1.0, v39
	v_lshlrev_b32_e32 v44, 16, v73
	v_rcp_f32_e32 v39, v39
	v_mul_f32_e32 v40, 0xbfb8aa3b, v40
	v_mul_f32_e32 v42, v42, v44
	v_and_b32_e32 v44, 0xffff0000, v73
	v_exp_f32_e32 v40, v40
	v_mul_f32_e32 v41, 0xbfb8aa3b, v41
	v_lshlrev_b64 v[60:61], 11, v[74:75]
	v_mul_f32_e32 v43, v43, v44
	v_lshlrev_b32_e32 v44, 16, v66
	v_exp_f32_e32 v41, v41
	v_cvt_pk_bf16_f32 v49, v42, v43
	v_lshl_add_u64 v[42:43], s[12:13], 0, v[60:61]
	v_mul_f32_e32 v38, v38, v44
	v_and_b32_e32 v44, 0xffff0000, v66
	v_mul_f32_e32 v34, 0xbfb8aa3b, v34
	v_lshl_add_u64 v[42:43], v[42:43], 0, v[146:147]
	v_mul_f32_e32 v39, v39, v44
	v_exp_f32_e32 v34, v34
	v_mul_f32_e32 v35, 0xbfb8aa3b, v35
	global_store_dwordx4 v[42:43], v[46:49], off offset:1024
	v_cvt_pk_bf16_f32 v38, v38, v39
	v_add_f32_e32 v39, 1.0, v40
	v_exp_f32_e32 v35, v35
	v_rcp_f32_e32 v39, v39
	v_add_f32_e32 v40, 1.0, v41
	v_rcp_f32_e32 v40, v40
	v_add_f32_e32 v34, 1.0, v34
	v_lshlrev_b32_e32 v41, 16, v67
	v_rcp_f32_e32 v34, v34
	v_add_f32_e32 v35, 1.0, v35
	v_mul_f32_e32 v36, 0xbfb8aa3b, v36
	v_mul_f32_e32 v39, v39, v41
	v_and_b32_e32 v41, 0xffff0000, v67
	v_rcp_f32_e32 v35, v35
	v_exp_f32_e32 v36, v36
	v_mul_f32_e32 v37, 0xbfb8aa3b, v37
	v_mul_f32_e32 v40, v40, v41
	v_exp_f32_e32 v37, v37
	v_cvt_pk_bf16_f32 v39, v39, v40
	v_lshlrev_b32_e32 v40, 16, v68
	v_mul_f32_e32 v34, v34, v40
	v_and_b32_e32 v40, 0xffff0000, v68
	v_mul_f32_e32 v35, v35, v40
	v_cvt_pk_bf16_f32 v40, v34, v35
	v_add_f32_e32 v34, 1.0, v36
	v_rcp_f32_e32 v34, v34
	v_add_f32_e32 v35, 1.0, v37
	v_rcp_f32_e32 v35, v35
	v_lshlrev_b32_e32 v36, 16, v69
	v_mul_f32_e32 v34, v34, v36
	v_and_b32_e32 v36, 0xffff0000, v69
	v_mul_f32_e32 v35, v35, v36
	v_cvt_pk_bf16_f32 v41, v34, v35
	global_store_dwordx4 v[42:43], v[38:41], off offset:1280
	v_add_u32_e32 v42, 0xb0, v148
	v_ashrrev_i32_e32 v43, 31, v42
	v_lshlrev_b64 v[34:35], 10, v[42:43]
	v_lshl_add_u64 v[34:35], s[8:9], 0, v[34:35]
	v_lshl_add_u64 v[38:39], v[34:35], 0, v[146:147]
	global_load_dwordx4 v[34:37], v[38:39], off offset:256
	s_nop 0
	global_load_dwordx4 v[38:41], v[38:39], off
	v_mul_f32_e32 v30, 0xbfb8aa3b, v30
	v_exp_f32_e32 v30, v30
	v_mul_f32_e32 v31, 0xbfb8aa3b, v31
	v_exp_f32_e32 v31, v31
	v_mul_f32_e32 v32, 0xbfb8aa3b, v32
	v_add_f32_e32 v30, 1.0, v30
	v_rcp_f32_e32 v30, v30
	v_add_f32_e32 v31, 1.0, v31
	v_rcp_f32_e32 v31, v31
	v_exp_f32_e32 v32, v32
	v_mul_f32_e32 v33, 0xbfb8aa3b, v33
	s_waitcnt vmcnt(4)
; __device__ __forceinline__ unsigned cvt_pk_bf16(float lo, float hi) { unsigned r; asm volatile("v_cvt_pk_bf16_f32 %0, %1, %2" : "=v"(r) : "v"(lo), "v"(hi)); return r; }
; #define PG8_BAR __builtin_amdgcn_s_barrier()
; __device__ __forceinline__ float bflo(unsigned w) { return __uint_as_float(w << 16); }
; __device__ __forceinline__ float bfhi(unsigned w) { return __uint_as_float(w & 0xffff0000u); }
; template <class Epi, class Sched, bool ALIGN_EPI = false, bool SP2 = false>
; __device__ __forceinline__ void gemm_phase(PG8_LAS unsigned char* lds, const Gemm g, const Sched& S, const Epi& E) {
;     ...
;         if constexpr (ALIGN_EPI) { if (wr == 0) PG8_BAR; }
;         if constexpr (!Epi::AFTER_DRAIN) { E(acc, cur, wr, wc, fr, fq); S.done(cur); }
;         if (!has_next) break;
; #pragma unroll
;         for (int a = 0; a < 2; ++a)
; #pragma unroll
;             for (int b = 0; b < 2; ++b)
; #pragma unroll
;                 for (int m = 0; m < 4; ++m)
; #pragma unroll
;                     for (int n = 0; n < 2; ++n) acc[a][b][m][n] = (f32x4){0.f, 0.f, 0.f, 0.f};
;         cur = nxt; cA = nA; cB = nB; ++ui;
;         if constexpr (ALIGN_EPI) { if (wr == 1) PG8_BAR; }
;     }
;     __device__ __forceinline__ void operator()(const pg8::f32x4 (&acc)[2][2][4][2], const Unit& u, int wr, int wc, int fr, int fq) const {
;     ...
;         for (int k = 0; k < 8; ++k) { const int ai = k >> 2, m = k & 3; const int row = row0 + ai * HALF + m * 16; v4u cy[2];
; #pragma unroll
;             for (int bj = 0; bj < 2; ++bj) cy[bj] = ny[bj];
;             if (k < 7) {
; #pragma unroll
;                 for (int bj = 0; bj < 2; ++bj) ny[bj] = *(const v4u*)(Y + (size_t)(row0 + ((k + 1) >> 2) * HALF + ((k + 1) & 3) * 16) * 512 + col0 + bj * HALF); }
; #pragma unroll
;             for (int bj = 0; bj < 2; ++bj) { const int col = col0 + bj * HALF; const v4u yw = cy[bj]; const f32x4 a0 = acc[ai][bj][m][0], a1 = acc[ai][bj][m][1];
;                 v4u w; w.x = cvt_pk_bf16(bflo(yw.x) * sigm(a0[0]), bfhi(yw.x) * sigm(a0[1])); w.y = cvt_pk_bf16(bflo(yw.y) * sigm(a0[2]), bfhi(yw.y) * sigm(a0[3]));
;                 w.z = cvt_pk_bf16(bflo(yw.z) * sigm(a1[0]), bfhi(yw.z) * sigm(a1[1])); w.w = cvt_pk_bf16(bflo(yw.w) * sigm(a1[2]), bfhi(yw.w) * sigm(a1[3]));
;                 *(v4u*)(O + (size_t)row * DM_ + 512 + col) = w; } }
	v_lshlrev_b32_e32 v46, 16, v54
	v_exp_f32_e32 v33, v33
	v_mul_f32_e32 v30, v30, v46
	v_and_b32_e32 v46, 0xffff0000, v54
	v_mul_f32_e32 v26, 0xbfb8aa3b, v26
	v_mul_f32_e32 v31, v31, v46
	v_exp_f32_e32 v26, v26
	v_mul_f32_e32 v27, 0xbfb8aa3b, v27
	v_cvt_pk_bf16_f32 v30, v30, v31
	v_add_f32_e32 v31, 1.0, v32
	v_exp_f32_e32 v27, v27
	v_rcp_f32_e32 v31, v31
	v_add_f32_e32 v32, 1.0, v33
	v_rcp_f32_e32 v32, v32
	v_add_f32_e32 v26, 1.0, v26
	v_lshlrev_b32_e32 v33, 16, v55
	v_rcp_f32_e32 v26, v26
	v_add_f32_e32 v27, 1.0, v27
	v_mul_f32_e32 v28, 0xbfb8aa3b, v28
	v_mul_f32_e32 v31, v31, v33
	v_and_b32_e32 v33, 0xffff0000, v55
	v_rcp_f32_e32 v27, v27
	v_exp_f32_e32 v28, v28
	v_mul_f32_e32 v29, 0xbfb8aa3b, v29
	v_mul_f32_e32 v32, v32, v33
	v_exp_f32_e32 v29, v29
	v_mul_f32_e32 v22, 0xbfb8aa3b, v22
	v_cvt_pk_bf16_f32 v31, v31, v32
	v_lshlrev_b32_e32 v32, 16, v56
	v_exp_f32_e32 v22, v22
	v_mul_f32_e32 v23, 0xbfb8aa3b, v23
	v_mul_f32_e32 v26, v26, v32
	v_and_b32_e32 v32, 0xffff0000, v56
	v_exp_f32_e32 v23, v23
	v_mul_f32_e32 v27, v27, v32
	v_cvt_pk_bf16_f32 v32, v26, v27
	v_add_f32_e32 v26, 1.0, v28
	v_rcp_f32_e32 v26, v26
	v_add_f32_e32 v27, 1.0, v29
	v_rcp_f32_e32 v27, v27
	v_add_f32_e32 v22, 1.0, v22
	v_rcp_f32_e32 v22, v22
	v_add_f32_e32 v23, 1.0, v23
	v_lshlrev_b32_e32 v28, 16, v57
	v_rcp_f32_e32 v23, v23
	v_mul_f32_e32 v24, 0xbfb8aa3b, v24
	v_mul_f32_e32 v26, v26, v28
	v_and_b32_e32 v28, 0xffff0000, v57
	v_exp_f32_e32 v24, v24
	v_mul_f32_e32 v25, 0xbfb8aa3b, v25
	v_lshlrev_b64 v[44:45], 11, v[58:59]
	v_mul_f32_e32 v27, v27, v28
	v_lshlrev_b32_e32 v28, 16, v50
	v_exp_f32_e32 v25, v25
	v_cvt_pk_bf16_f32 v33, v26, v27
	v_lshl_add_u64 v[26:27], s[12:13], 0, v[44:45]
	v_mul_f32_e32 v22, v22, v28
	v_and_b32_e32 v28, 0xffff0000, v50
	v_mul_f32_e32 v18, 0xbfb8aa3b, v18
	v_lshl_add_u64 v[26:27], v[26:27], 0, v[146:147]
	v_mul_f32_e32 v23, v23, v28
	v_exp_f32_e32 v18, v18
	v_mul_f32_e32 v19, 0xbfb8aa3b, v19
	global_store_dwordx4 v[26:27], v[30:33], off offset:1024
	v_cvt_pk_bf16_f32 v22, v22, v23
	v_add_f32_e32 v23, 1.0, v24
	v_exp_f32_e32 v19, v19
	v_rcp_f32_e32 v23, v23
	v_add_f32_e32 v24, 1.0, v25
	v_rcp_f32_e32 v24, v24
	v_add_f32_e32 v18, 1.0, v18
	v_lshlrev_b32_e32 v25, 16, v51
	v_rcp_f32_e32 v18, v18
	v_add_f32_e32 v19, 1.0, v19
	v_mul_f32_e32 v20, 0xbfb8aa3b, v20
	v_mul_f32_e32 v23, v23, v25
	v_and_b32_e32 v25, 0xffff0000, v51
	v_rcp_f32_e32 v19, v19
	v_exp_f32_e32 v20, v20
	v_mul_f32_e32 v21, 0xbfb8aa3b, v21
	v_mul_f32_e32 v24, v24, v25
	v_exp_f32_e32 v21, v21
	v_mul_f32_e32 v14, 0xbfb8aa3b, v14
	v_cvt_pk_bf16_f32 v23, v23, v24
	v_lshlrev_b32_e32 v24, 16, v52
	v_exp_f32_e32 v14, v14
	v_mul_f32_e32 v15, 0xbfb8aa3b, v15
	v_mul_f32_e32 v18, v18, v24
	v_and_b32_e32 v24, 0xffff0000, v52
	v_exp_f32_e32 v15, v15
	v_mul_f32_e32 v19, v19, v24
	v_cvt_pk_bf16_f32 v24, v18, v19
	v_add_f32_e32 v18, 1.0, v20
	v_rcp_f32_e32 v18, v18
	v_add_f32_e32 v19, 1.0, v21
	v_rcp_f32_e32 v19, v19
	v_add_f32_e32 v14, 1.0, v14
	v_rcp_f32_e32 v14, v14
	v_add_f32_e32 v15, 1.0, v15
	v_lshlrev_b32_e32 v20, 16, v53
	v_rcp_f32_e32 v15, v15
	v_mul_f32_e32 v16, 0xbfb8aa3b, v16
	v_mul_f32_e32 v18, v18, v20
	v_and_b32_e32 v20, 0xffff0000, v53
	v_exp_f32_e32 v16, v16
	v_mul_f32_e32 v17, 0xbfb8aa3b, v17
	v_mul_f32_e32 v19, v19, v20
	s_waitcnt vmcnt(1)
	v_lshlrev_b32_e32 v20, 16, v38
	v_exp_f32_e32 v17, v17
	v_mul_f32_e32 v14, v14, v20
	v_and_b32_e32 v20, 0xffff0000, v38
	v_mul_f32_e32 v10, 0xbfb8aa3b, v10
	v_mul_f32_e32 v15, v15, v20
	v_exp_f32_e32 v10, v10
	v_mul_f32_e32 v11, 0xbfb8aa3b, v11
	v_cvt_pk_bf16_f32 v25, v18, v19
	global_store_dwordx4 v[26:27], v[22:25], off offset:1280
	v_cvt_pk_bf16_f32 v14, v14, v15
	v_add_f32_e32 v15, 1.0, v16
	v_exp_f32_e32 v11, v11
	v_rcp_f32_e32 v15, v15
	v_add_f32_e32 v16, 1.0, v17
	v_rcp_f32_e32 v16, v16
	v_add_f32_e32 v10, 1.0, v10
	v_lshlrev_b32_e32 v17, 16, v39
	v_rcp_f32_e32 v10, v10
	v_add_f32_e32 v11, 1.0, v11
	v_mul_f32_e32 v12, 0xbfb8aa3b, v12
	v_mul_f32_e32 v15, v15, v17
	v_and_b32_e32 v17, 0xffff0000, v39
	v_rcp_f32_e32 v11, v11
	v_exp_f32_e32 v12, v12
	v_mul_f32_e32 v13, 0xbfb8aa3b, v13
	v_mul_f32_e32 v16, v16, v17
	v_exp_f32_e32 v13, v13
	v_mul_f32_e32 v6, 0xbfb8aa3b, v6
	v_cvt_pk_bf16_f32 v15, v15, v16
	v_lshlrev_b32_e32 v16, 16, v40
	v_exp_f32_e32 v6, v6
	v_mul_f32_e32 v7, 0xbfb8aa3b, v7
	v_mul_f32_e32 v10, v10, v16
	v_and_b32_e32 v16, 0xffff0000, v40
	v_exp_f32_e32 v7, v7
	v_mul_f32_e32 v11, v11, v16
	v_cvt_pk_bf16_f32 v16, v10, v11
	v_add_f32_e32 v10, 1.0, v12
	v_rcp_f32_e32 v10, v10
	v_add_f32_e32 v11, 1.0, v13
	v_rcp_f32_e32 v11, v11
	v_add_f32_e32 v6, 1.0, v6
	v_rcp_f32_e32 v6, v6
	v_add_f32_e32 v7, 1.0, v7
	v_lshlrev_b32_e32 v12, 16, v41
	v_rcp_f32_e32 v7, v7
	v_mul_f32_e32 v8, 0xbfb8aa3b, v8
	v_mul_f32_e32 v10, v10, v12
	v_and_b32_e32 v12, 0xffff0000, v41
	v_exp_f32_e32 v8, v8
	v_mul_f32_e32 v9, 0xbfb8aa3b, v9
	v_lshlrev_b64 v[18:19], 11, v[42:43]
	v_mul_f32_e32 v11, v11, v12
	v_lshlrev_b32_e32 v12, 16, v34
	v_exp_f32_e32 v9, v9
	v_cvt_pk_bf16_f32 v17, v10, v11
	v_lshl_add_u64 v[10:11], s[12:13], 0, v[18:19]
	v_mul_f32_e32 v6, v6, v12
	v_and_b32_e32 v12, 0xffff0000, v34
	v_mul_f32_e32 v2, 0xbfb8aa3b, v2
	v_lshl_add_u64 v[10:11], v[10:11], 0, v[146:147]
	v_mul_f32_e32 v7, v7, v12
	v_exp_f32_e32 v2, v2
	v_mul_f32_e32 v3, 0xbfb8aa3b, v3
	global_store_dwordx4 v[10:11], v[14:17], off offset:1024
	v_cvt_pk_bf16_f32 v6, v6, v7
	v_add_f32_e32 v7, 1.0, v8
	v_exp_f32_e32 v3, v3
	v_rcp_f32_e32 v7, v7
	v_add_f32_e32 v8, 1.0, v9
	v_rcp_f32_e32 v8, v8
	v_add_f32_e32 v2, 1.0, v2
	v_lshlrev_b32_e32 v9, 16, v35
	v_rcp_f32_e32 v2, v2
	v_add_f32_e32 v3, 1.0, v3
	v_mul_f32_e32 v4, 0xbfb8aa3b, v4
	v_mul_f32_e32 v7, v7, v9
	v_and_b32_e32 v9, 0xffff0000, v35
	v_rcp_f32_e32 v3, v3
	v_exp_f32_e32 v4, v4
	v_mul_f32_e32 v5, 0xbfb8aa3b, v5
	v_mul_f32_e32 v8, v8, v9
	v_exp_f32_e32 v5, v5
	v_cvt_pk_bf16_f32 v7, v7, v8
	v_lshlrev_b32_e32 v8, 16, v36
	v_mul_f32_e32 v2, v2, v8
	v_and_b32_e32 v8, 0xffff0000, v36
	v_mul_f32_e32 v3, v3, v8
	v_cvt_pk_bf16_f32 v8, v2, v3
	v_add_f32_e32 v2, 1.0, v4
	v_rcp_f32_e32 v2, v2
	v_add_f32_e32 v3, 1.0, v5
	v_rcp_f32_e32 v3, v3
	v_lshlrev_b32_e32 v4, 16, v37
	v_mul_f32_e32 v2, v2, v4
	v_and_b32_e32 v4, 0xffff0000, v37
	s_andn2_b64 vcc, exec, s[6:7]
	s_mov_b64 s[6:7], -1
	v_mul_f32_e32 v3, v3, v4
	v_cvt_pk_bf16_f32 v9, v2, v3
	global_store_dwordx4 v[10:11], v[6:9], off offset:1280
	s_cbranch_vccnz .LBB0_515
	s_andn2_b64 vcc, exec, s[10:11]
	s_cbranch_vccnz .LBB0_514
	s_barrier
	s_branch .LBB0_514

; __device__ __forceinline__ unsigned cvt_pk_bf16(float lo, float hi) { unsigned r; asm volatile("v_cvt_pk_bf16_f32 %0, %1, %2" : "=v"(r) : "v"(lo), "v"(hi)); return r; }
; __device__ __forceinline__ float bflo(unsigned w) { return __uint_as_float(w << 16); }
; __device__ __forceinline__ float bfhi(unsigned w) { return __uint_as_float(w & 0xffff0000u); }
;     __device__ __forceinline__ void ld(Ld& L, size_t o) const {
; #pragma unroll
;         for (int bj = 0; bj < 2; ++bj) { if (BASEF32) { L.a[bj][0] = *(const f32x4*)((const float*)base + o + bj * HALF); L.a[bj][1] = *(const f32x4*)((const float*)base + o + bj * HALF + 4); }
;             else { const v4u w = *(const v4u*)((const bf16*)base + o + bj * HALF); L.a[bj][0] = __builtin_bit_cast(f32x4, w); } }
;     }
;     __device__ __forceinline__ void operator()(const pg8::f32x4 (&acc)[2][2][4][2], const Unit& u, int wr, int wc, int fr, int fq) const {
;         const int row0 = u.pm * BM + wr * 64 + fr, col0 = u.pn * BM + wc * 32 + 8 * fq;
;         Ld nx; ld(nx, (size_t)row0 * DM_ + col0);
; #pragma unroll
;         for (int k = 0; k < 8; ++k) { const int ai = k >> 2, m = k & 3; const int row = row0 + ai * HALF + m * 16; float q = 0.f; const Ld cu = nx;
;             if (k < 7) ld(nx, (size_t)(row0 + ((k + 1) >> 2) * HALF + ((k + 1) & 3) * 16) * DM_ + col0);
; #pragma unroll
;             for (int bj = 0; bj < 2; ++bj) { const size_t o = (size_t)row * DM_ + col0 + bj * HALF; f32x4 b0, b1;
;                 if (BASEF32) { b0 = cu.a[bj][0]; b1 = cu.a[bj][1]; }
;                 else { const v4u w = __builtin_bit_cast(v4u, cu.a[bj][0]); b0 = (f32x4){bflo(w.x), bfhi(w.x), bflo(w.y), bfhi(w.y)}; b1 = (f32x4){bflo(w.z), bfhi(w.z), bflo(w.w), bfhi(w.w)}; }
;                 const f32x4 r0 = b0 + acc[ai][bj][m][0], r1 = b1 + acc[ai][bj][m][1];
;                 q += (r0[0] * r0[0] + r0[1] * r0[1]) + (r0[2] * r0[2] + r0[3] * r0[3]) + (r1[0] * r1[0] + r1[1] * r1[1]) + (r1[2] * r1[2] + r1[3] * r1[3]);
;                 v4u w; w.x = cvt_pk_bf16(r0[0], r0[1]); w.y = cvt_pk_bf16(r0[2], r0[3]); w.z = cvt_pk_bf16(r1[0], r1[1]); w.w = cvt_pk_bf16(r1[2], r1[3]); *(v4u*)(out + o) = w; }
;             q += __shfl_xor(q, 16); q += __shfl_xor(q, 32); if (fq == 0) ssq[(size_t)row * 16 + u.pn * 4 + wc] = q; }
.LBB0_608:
	v_lshl_add_u32 v164, s30, 8, v1
	v_lshl_or_b32 v162, s10, 8, v171
	v_ashrrev_i32_e32 v165, 31, v164
	v_ashrrev_i32_e32 v163, 31, v162
	v_lshlrev_b64 v[130:131], 12, v[164:165]
	v_lshl_add_u64 v[130:131], s[4:5], 0, v[130:131]
	v_lshlrev_b64 v[132:133], 2, v[162:163]
	v_lshl_add_u64 v[130:131], v[130:131], 0, v[132:133]
	global_load_dwordx4 v[178:181], v[130:131], off
	global_load_dwordx4 v[182:185], v[130:131], off offset:16
	global_load_dwordx4 v[186:189], v[130:131], off offset:512
	global_load_dwordx4 v[190:193], v[130:131], off offset:528
	v_or_b32_e32 v166, 16, v164
	v_ashrrev_i32_e32 v167, 31, v166
	v_lshlrev_b64 v[130:131], 12, v[166:167]
	v_lshl_add_u64 v[130:131], s[4:5], 0, v[130:131]
	v_lshl_add_u64 v[134:135], v[130:131], 0, v[132:133]
	global_load_dwordx4 v[138:141], v[134:135], off offset:16
	global_load_dwordx4 v[142:145], v[134:135], off
	global_load_dwordx4 v[130:133], v[134:135], off offset:528
	s_nop 0
	global_load_dwordx4 v[134:137], v[134:135], off offset:512
	v_and_b32_e32 v168, 64, v175
	v_xor_b32_e32 v176, 16, v175
	v_add_u32_e32 v194, 64, v168
	v_cmp_lt_i32_e32 vcc, v176, v194
	v_xor_b32_e32 v177, 32, v175
	v_lshlrev_b64 v[168:169], 11, v[164:165]
	v_cndmask_b32_e32 v176, v175, v176, vcc
	v_lshlrev_b32_e32 v176, 2, v176
	v_cmp_lt_i32_e32 vcc, v177, v194
	v_lshl_add_u64 v[168:169], s[14:15], 0, v[168:169]
	v_lshl_add_u64 v[168:169], v[162:163], 1, v[168:169]
	v_cndmask_b32_e32 v177, v175, v177, vcc
	v_lshlrev_b32_e32 v177, 2, v177
	s_lshl_b32 s30, s10, 2
	s_ashr_i32 s31, s30, 31
	s_and_b64 s[98:99], exec, s[20:21]
	s_cbranch_scc0 .Lal_3
	s_barrier
.Lal_3:
	s_waitcnt vmcnt(0)
	v_pk_add_f32 v[128:129], v[128:129], v[180:181]
	v_pk_add_f32 v[126:127], v[126:127], v[178:179]
	v_pk_add_f32 v[120:121], v[120:121], v[188:189]
	v_pk_add_f32 v[118:119], v[118:119], v[186:187]
	v_pk_add_f32 v[122:123], v[122:123], v[182:183]
	v_pk_add_f32 v[178:179], v[116:117], v[192:193]
	v_pk_add_f32 v[180:181], v[114:115], v[190:191]
	v_mul_f32_e32 v116, v127, v127
	v_mul_f32_e32 v117, v129, v129
	v_cvt_pk_bf16_f32 v114, v126, v127
	v_cvt_pk_bf16_f32 v115, v128, v129
	v_mul_f32_e32 v127, v119, v119
	v_mul_f32_e32 v129, v121, v121
	v_pk_add_f32 v[124:125], v[124:125], v[184:185]
	v_mul_f32_e32 v182, v123, v123
	v_mul_f32_e32 v184, v181, v181
	v_fmac_f32_e32 v116, v126, v126
	v_fmac_f32_e32 v117, v128, v128
	v_fmac_f32_e32 v127, v118, v118
	v_fmac_f32_e32 v129, v120, v120
	v_mul_f32_e32 v183, v125, v125
	v_mul_f32_e32 v185, v179, v179
	v_fmac_f32_e32 v182, v122, v122
	v_fmac_f32_e32 v184, v180, v180
	v_add_f32_e32 v116, v116, v117
	v_add_f32_e32 v117, v127, v129
	v_fmac_f32_e32 v183, v124, v124
	v_fmac_f32_e32 v185, v178, v178
	v_add_f32_e32 v116, v116, v182
	v_add_f32_e32 v117, v117, v184
	v_add_f32_e32 v116, v183, v116
	v_add_f32_e32 v117, v185, v117
	v_add_f32_e32 v126, v116, v117
	v_mov_b32_e32 v127, v126
	s_nop 1
	v_permlane16_swap_b32 v126, v127
	v_cvt_pk_bf16_f32 v116, v122, v123
	v_cvt_pk_bf16_f32 v117, v124, v125
	global_store_dwordx4 v[168:169], v[114:117], off
	s_waitcnt lgkmcnt(0)
	s_nop 0
	v_add_f32_e32 v114, v126, v127
	v_mov_b32_e32 v115, v114
	s_nop 1
	v_permlane32_swap_b32 v114, v115
	v_cvt_pk_bf16_f32 v116, v118, v119
	v_cvt_pk_bf16_f32 v117, v120, v121
	v_cvt_pk_bf16_f32 v118, v180, v181
	v_cvt_pk_bf16_f32 v119, v178, v179
	global_store_dwordx4 v[168:169], v[116:119], off offset:256
	s_and_saveexec_b64 s[34:35], s[6:7]
	s_cbranch_execz .LBB0_610
	v_lshlrev_b64 v[116:117], 6, v[164:165]
	v_lshl_add_u64 v[116:117], s[16:17], 0, v[116:117]
	v_lshl_add_u64 v[116:117], s[30:31], 2, v[116:117]
	s_lshl_b32 s10, s44, 2
	v_lshl_add_u64 v[116:117], v[116:117], 0, s[10:11]
	s_waitcnt lgkmcnt(0)
	v_add_f32_e32 v114, v114, v115
	global_store_dword v[116:117], v114, off

; __device__ __forceinline__ void rstd8(const float* ss, int row0, int fq, float (&rs)[8]) {
;     f32x4 a[8];
; #pragma unroll
;     for (int k = 0; k < 8; ++k) a[k] = *(const f32x4*)(ss + (size_t)(row0 + (k >> 2) * 128 + (k & 3) * 16) * 16 + 4 * fq);
; #pragma unroll
;     for (int k = 0; k < 8; ++k) { float s = (a[k][0] + a[k][1]) + (a[k][2] + a[k][3]); s += __shfl_xor(s, 16); s += __shfl_xor(s, 32); rs[k] = __builtin_amdgcn_rsqf(s * (1.f / 1024.f) + EPS); }
;     __device__ __forceinline__ void operator()(const pg8::f32x4 (&acc)[2][2][4][2], const Unit& u, int wr, int wc, int fr, int fq) const {
;     ...
;         for (int ai = 0; ai < 2; ++ai)
; #pragma unroll
;             for (int m = 0; m < 4; ++m) { float r[8]; const float rs = rsv[ai * 4 + m]; const float c1 = -1.4426950408889634f * rs, rs2 = rs * rs;
; #pragma unroll
;                 for (int n = 0; n < 2; ++n)
; #pragma unroll
;                     for (int e = 0; e < 4; e += 2) { const f32x2 ag = {acc[ai][0][m][n][e], acc[ai][0][m][n][e + 1]}, au = {acc[ai][1][m][n][e], acc[ai][1][m][n][e + 1]};
;                         const f32x2 t = ag * c1; f32x2 d; d.x = __builtin_amdgcn_exp2f(t.x); d.y = __builtin_amdgcn_exp2f(t.y); d = d + 1.0f;
;                         f32x2 q; q.x = __builtin_amdgcn_rcpf(d.x); q.y = __builtin_amdgcn_rcpf(d.y); const f32x2 o = (ag * au) * rs2 * q; r[4 * n + e] = o.x; r[4 * n + e + 1] = o.y; }
.LBB0_694:
	v_lshl_add_u32 v162, s22, 8, v1
	v_ashrrev_i32_e32 v163, 31, v162
	v_or_b32_e32 v160, 16, v162
	v_lshlrev_b64 v[148:149], 6, v[162:163]
	v_ashrrev_i32_e32 v161, 31, v160
	v_or_b32_e32 v158, 32, v162
	v_lshl_add_u64 v[148:149], v[138:139], 0, v[148:149]
	v_lshlrev_b64 v[150:151], 6, v[160:161]
	v_ashrrev_i32_e32 v159, 31, v158
	v_or_b32_e32 v156, 48, v162
	v_lshl_add_u64 v[150:151], v[138:139], 0, v[150:151]
	global_load_dwordx4 v[174:177], v[148:149], off
	global_load_dwordx4 v[178:181], v[150:151], off
	v_lshlrev_b64 v[148:149], 6, v[158:159]
	v_ashrrev_i32_e32 v157, 31, v156
	v_lshl_add_u64 v[148:149], v[138:139], 0, v[148:149]
	v_lshlrev_b64 v[150:151], 6, v[156:157]
	v_lshl_add_u64 v[150:151], v[138:139], 0, v[150:151]
	global_load_dwordx4 v[182:185], v[148:149], off
	global_load_dwordx4 v[186:189], v[150:151], off
	v_add_u32_e32 v154, 0x80, v162
	v_ashrrev_i32_e32 v155, 31, v154
	v_lshlrev_b64 v[148:149], 6, v[154:155]
	v_lshl_add_u64 v[148:149], v[138:139], 0, v[148:149]
	global_load_dwordx4 v[190:193], v[148:149], off
	v_add_u32_e32 v152, 0x90, v162
	v_ashrrev_i32_e32 v153, 31, v152
	v_lshlrev_b64 v[148:149], 6, v[152:153]
	v_add_u32_e32 v150, 0xa0, v162
	v_lshl_add_u64 v[148:149], v[138:139], 0, v[148:149]
	v_ashrrev_i32_e32 v151, 31, v150
	global_load_dwordx4 v[194:197], v[148:149], off
	v_lshlrev_b64 v[148:149], 6, v[150:151]
	v_lshl_add_u64 v[148:149], v[138:139], 0, v[148:149]
	global_load_dwordx4 v[198:201], v[148:149], off
	v_add_u32_e32 v148, 0xb0, v162
	v_ashrrev_i32_e32 v149, 31, v148
	v_lshlrev_b64 v[202:203], 6, v[148:149]
	v_lshl_add_u64 v[202:203], v[138:139], 0, v[202:203]
	global_load_dwordx4 v[202:205], v[202:203], off
	v_and_b32_e32 v151, 64, v171
	v_xor_b32_e32 v149, 16, v171
	v_add_u32_e32 v151, 64, v151
	v_xor_b32_e32 v153, 32, v171
	v_cmp_lt_i32_e32 vcc, v149, v151
	v_pk_mul_f32 v[124:125], v[128:129], v[124:125]
	v_pk_mul_f32 v[122:123], v[126:127], v[122:123]
	v_cndmask_b32_e32 v149, v171, v149, vcc
	v_cmp_lt_i32_e32 vcc, v153, v151
	v_lshlrev_b32_e32 v149, 2, v149
	v_pk_mul_f32 v[114:115], v[118:119], v[114:115]
	v_cndmask_b32_e32 v151, v171, v153, vcc
	v_lshlrev_b32_e32 v151, 2, v151
	v_pk_mul_f32 v[116:117], v[120:121], v[116:117]
	v_lshl_or_b32 v164, s45, 7, v167
	v_pk_mul_f32 v[108:109], v[112:113], v[108:109]
	v_pk_mul_f32 v[106:107], v[110:111], v[106:107]
	v_pk_mul_f32 v[98:99], v[102:103], v[98:99]
	v_pk_mul_f32 v[100:101], v[104:105], v[100:101]
	v_pk_mul_f32 v[92:93], v[96:97], v[92:93]
	v_pk_mul_f32 v[90:91], v[94:95], v[90:91]
	v_pk_mul_f32 v[82:83], v[86:87], v[82:83]
	v_pk_mul_f32 v[84:85], v[88:89], v[84:85]
	v_pk_mul_f32 v[76:77], v[80:81], v[76:77]
	v_pk_mul_f32 v[74:75], v[78:79], v[74:75]
	v_pk_mul_f32 v[66:67], v[70:71], v[66:67]
	v_pk_mul_f32 v[68:69], v[72:73], v[68:69]
	v_pk_mul_f32 v[60:61], v[64:65], v[60:61]
	v_pk_mul_f32 v[58:59], v[62:63], v[58:59]
	v_pk_mul_f32 v[50:51], v[54:55], v[50:51]
	v_pk_mul_f32 v[52:53], v[56:57], v[52:53]
	v_pk_mul_f32 v[44:45], v[48:49], v[44:45]
	v_pk_mul_f32 v[42:43], v[46:47], v[42:43]
	v_pk_mul_f32 v[34:35], v[38:39], v[34:35]
	v_pk_mul_f32 v[36:37], v[40:41], v[36:37]
	v_pk_mul_f32 v[28:29], v[32:33], v[28:29]
	v_pk_mul_f32 v[26:27], v[30:31], v[26:27]
	v_pk_mul_f32 v[18:19], v[22:23], v[18:19]
	v_pk_mul_f32 v[20:21], v[24:25], v[20:21]
	v_pk_mul_f32 v[12:13], v[16:17], v[12:13]
	v_pk_mul_f32 v[10:11], v[14:15], v[10:11]
	v_pk_mul_f32 v[2:3], v[6:7], v[2:3]
	v_pk_mul_f32 v[4:5], v[8:9], v[4:5]
	s_andn2_b64 vcc, exec, s[6:7]
	s_mov_b64 s[6:7], -1
	s_and_b64 s[98:99], exec, s[12:13]
	s_cbranch_scc0 .Lal_4
	s_barrier
.Lal_4:
	s_waitcnt vmcnt(0)
	v_mov_b32_e32 v206, v175
	v_mov_b32_e32 v207, v176
	v_mov_b32_e32 v175, v177
	v_pk_add_f32 v[174:175], v[206:207], v[174:175]
	v_mov_b32_e32 v176, v179
	v_mov_b32_e32 v177, v180
	v_mov_b32_e32 v179, v181
	v_mov_b32_e32 v180, v183
	v_mov_b32_e32 v181, v184
	v_mov_b32_e32 v183, v185
	v_mov_b32_e32 v184, v187
	v_mov_b32_e32 v185, v188
	v_mov_b32_e32 v187, v189
	v_add_f32_e32 v153, v174, v175
	v_pk_add_f32 v[174:175], v[176:177], v[178:179]
	v_pk_add_f32 v[176:177], v[180:181], v[182:183]
	v_pk_add_f32 v[178:179], v[184:185], v[186:187]
	v_add_f32_e32 v157, v174, v175
	v_add_f32_e32 v159, v176, v177
	v_add_f32_e32 v161, v178, v179
	v_mov_b32_e32 v155, v153
	s_nop 1
	v_permlane16_swap_b32 v153, v155
	v_mov_b32_e32 v165, v157
	s_nop 1
	v_permlane16_swap_b32 v157, v165
	v_mov_b32_e32 v173, v159
	s_nop 1
	v_permlane16_swap_b32 v159, v173
	v_mov_b32_e32 v174, v161
	s_nop 1
	v_permlane16_swap_b32 v161, v174
	v_mov_b32_e32 v188, v191
	v_mov_b32_e32 v189, v192
	v_mov_b32_e32 v191, v193
	v_pk_add_f32 v[180:181], v[188:189], v[190:191]
	s_waitcnt lgkmcnt(3)
	v_add_f32_e32 v153, v153, v155
	v_add_f32_e32 v163, v180, v181
	s_waitcnt lgkmcnt(2)
	v_add_f32_e32 v157, v157, v165
	s_waitcnt lgkmcnt(1)
	v_add_f32_e32 v159, v159, v173
	s_waitcnt lgkmcnt(0)
	v_add_f32_e32 v161, v161, v174
	v_mov_b32_e32 v175, v163
	s_nop 1
	v_permlane16_swap_b32 v163, v175
	v_mov_b32_e32 v155, v153
	s_nop 1
	v_permlane32_swap_b32 v153, v155
	v_mov_b32_e32 v165, v157
	s_nop 1
	v_permlane32_swap_b32 v157, v165
	v_mov_b32_e32 v173, v159
	s_nop 1
	v_permlane32_swap_b32 v159, v173
	v_mov_b32_e32 v174, v161
	s_nop 1
	v_permlane32_swap_b32 v161, v174
	s_waitcnt lgkmcnt(4)
	v_add_f32_e32 v163, v163, v175
	s_waitcnt lgkmcnt(3)
	v_add_f32_e32 v153, v153, v155
	s_waitcnt lgkmcnt(2)
	v_add_f32_e32 v155, v157, v165
	s_waitcnt lgkmcnt(1)
	v_add_f32_e32 v157, v159, v173
	s_waitcnt lgkmcnt(0)
; __device__ __forceinline__ unsigned cvt_pk_bf16(float lo, float hi) { unsigned r; asm volatile("v_cvt_pk_bf16_f32 %0, %1, %2" : "=v"(r) : "v"(lo), "v"(hi)); return r; }
;     __device__ __forceinline__ void operator()(const pg8::f32x4 (&acc)[2][2][4][2], const Unit& u, int wr, int wc, int fr, int fq) const {
;     ...
;         float rsv[8]; rstd8(ss, row0, fq, rsv);
; #pragma unroll
;         for (int ai = 0; ai < 2; ++ai)
; #pragma unroll
;             for (int m = 0; m < 4; ++m) { float r[8]; const float rs = rsv[ai * 4 + m]; const float c1 = -1.4426950408889634f * rs, rs2 = rs * rs;
; #pragma unroll
;                 for (int n = 0; n < 2; ++n)
; #pragma unroll
;                     for (int e = 0; e < 4; e += 2) { const f32x2 ag = {acc[ai][0][m][n][e], acc[ai][0][m][n][e + 1]}, au = {acc[ai][1][m][n][e], acc[ai][1][m][n][e + 1]};
;                         const f32x2 t = ag * c1; f32x2 d; d.x = __builtin_amdgcn_exp2f(t.x); d.y = __builtin_amdgcn_exp2f(t.y); d = d + 1.0f;
;                         f32x2 q; q.x = __builtin_amdgcn_rcpf(d.x); q.y = __builtin_amdgcn_rcpf(d.y); const f32x2 o = (ag * au) * rs2 * q; r[4 * n + e] = o.x; r[4 * n + e + 1] = o.y; }
;                 v4u w; w.x = cvt_pk_bf16(r[0], r[1]); w.y = cvt_pk_bf16(r[2], r[3]); w.z = cvt_pk_bf16(r[4], r[5]); w.w = cvt_pk_bf16(r[6], r[7]);
;                 __builtin_nontemporal_store(w, (v4u*)(O + (size_t)(row0 + ai * HALF + m * 16) * FF + col0)); }
	v_add_f32_e32 v159, v161, v174
	v_mov_b32_e32 v174, v195
	v_mov_b32_e32 v175, v196
	v_mov_b32_e32 v195, v197
	v_pk_add_f32 v[174:175], v[174:175], v[194:195]
	v_mov_b32_e32 v176, v163
	s_nop 1
	v_permlane32_swap_b32 v163, v176
	v_add_f32_e32 v161, v174, v175
	v_mov_b32_e32 v174, v199
	v_mov_b32_e32 v175, v200
	v_mov_b32_e32 v199, v201
	v_pk_add_f32 v[174:175], v[174:175], v[198:199]
	v_mov_b32_e32 v165, v161
	s_nop 1
	v_permlane16_swap_b32 v161, v165
	v_add_f32_e32 v173, v174, v175
	v_mov_b32_e32 v174, v203
	v_mov_b32_e32 v175, v204
	v_mov_b32_e32 v203, v205
	v_pk_add_f32 v[174:175], v[174:175], v[202:203]
	s_waitcnt lgkmcnt(1)
	v_add_f32_e32 v163, v163, v176
	v_add_f32_e32 v174, v174, v175
	v_mov_b32_e32 v176, v173
	s_nop 1
	v_permlane16_swap_b32 v173, v176
	v_mov_b32_e32 v149, v174
	s_nop 1
	v_permlane16_swap_b32 v174, v149
	v_fmamk_f32 v153, v153, 0x3a800000, v172
	v_rsq_f32_e32 v153, v153
	s_waitcnt lgkmcnt(2)
	v_add_f32_e32 v161, v161, v165
	v_mov_b32_e32 v165, v161
	s_nop 1
	v_permlane32_swap_b32 v161, v165
	s_waitcnt lgkmcnt(1)
	v_add_f32_e32 v149, v174, v149
	v_mov_b32_e32 v174, v149
	s_nop 1
	v_permlane32_swap_b32 v149, v174
	v_mul_f32_e32 v178, v153, v153
	v_pk_mul_f32 v[124:125], v[124:125], v[178:179] op_sel_hi:[1,0]
	s_waitcnt lgkmcnt(1)
	v_add_f32_e32 v161, v161, v165
	v_add_f32_e32 v165, v173, v176
	s_waitcnt lgkmcnt(0)
	v_add_f32_e32 v149, v149, v174
	v_mul_f32_e32 v174, 0xbfb8aa3b, v153
	v_pk_mul_f32 v[180:181], v[128:129], v[174:175] op_sel_hi:[1,0]
	v_pk_mul_f32 v[176:177], v[126:127], v[174:175] op_sel_hi:[1,0]
	v_exp_f32_e32 v180, v180
	v_exp_f32_e32 v181, v181
	v_pk_mul_f32 v[128:129], v[118:119], v[174:175] op_sel_hi:[1,0]
	v_exp_f32_e32 v176, v176
	v_exp_f32_e32 v128, v128
	v_pk_add_f32 v[126:127], v[180:181], 1.0 op_sel_hi:[1,0]
	v_exp_f32_e32 v129, v129
	v_rcp_f32_e32 v126, v126
	v_rcp_f32_e32 v127, v127
	v_exp_f32_e32 v177, v177
	v_mov_b32_e32 v173, v165
	s_nop 1
	v_permlane32_swap_b32 v165, v173
	v_fmamk_f32 v155, v155, 0x3a800000, v172
	v_pk_mul_f32 v[124:125], v[124:125], v[126:127]
	v_pk_add_f32 v[126:127], v[128:129], 1.0 op_sel_hi:[1,0]
	v_pk_mul_f32 v[128:129], v[120:121], v[174:175] op_sel_hi:[1,0]
	v_pk_add_f32 v[176:177], v[176:177], 1.0 op_sel_hi:[1,0]
	v_exp_f32_e32 v128, v128
	v_exp_f32_e32 v129, v129
	v_rcp_f32_e32 v126, v126
	v_rcp_f32_e32 v127, v127
	v_rcp_f32_e32 v176, v176
	v_pk_add_f32 v[118:119], v[128:129], 1.0 op_sel_hi:[1,0]
	v_rcp_f32_e32 v177, v177
	v_rcp_f32_e32 v118, v118
	v_rcp_f32_e32 v119, v119
	v_rsq_f32_e32 v155, v155
	v_pk_mul_f32 v[114:115], v[114:115], v[178:179] op_sel_hi:[1,0]
	v_pk_mul_f32 v[122:123], v[122:123], v[178:179] op_sel_hi:[1,0]
	v_pk_mul_f32 v[114:115], v[114:115], v[126:127]
	v_pk_mul_f32 v[116:117], v[116:117], v[178:179] op_sel_hi:[1,0]
	s_waitcnt lgkmcnt(0)
	v_add_f32_e32 v151, v165, v173
	v_ashrrev_i32_e32 v165, 31, v164
	v_pk_mul_f32 v[122:123], v[122:123], v[176:177]
	v_pk_mul_f32 v[116:117], v[116:117], v[118:119]
	v_cvt_pk_bf16_f32 v118, v122, v123
	v_cvt_pk_bf16_f32 v119, v124, v125
	v_cvt_pk_bf16_f32 v120, v114, v115
	v_mov_b64_e32 v[114:115], s[8:9]
	v_cvt_pk_bf16_f32 v121, v116, v117
	v_mad_i64_i32 v[122:123], s[24:25], v162, s44, v[114:115]
	v_lshlrev_b64 v[116:117], 1, v[164:165]
	v_mul_f32_e32 v124, 0xbfb8aa3b, v155
	v_lshl_add_u64 v[122:123], v[122:123], 0, v[116:117]
	global_store_dwordx4 v[122:123], v[118:121], off nt
	v_pk_mul_f32 v[122:123], v[112:113], v[124:125] op_sel_hi:[1,0]
	v_pk_mul_f32 v[126:127], v[110:111], v[124:125] op_sel_hi:[1,0]
	v_exp_f32_e32 v122, v122
	v_exp_f32_e32 v123, v123
	v_pk_mul_f32 v[112:113], v[102:103], v[124:125] op_sel_hi:[1,0]
	v_mul_f32_e32 v118, v155, v155
	v_exp_f32_e32 v112, v112
	v_pk_add_f32 v[110:111], v[122:123], 1.0 op_sel_hi:[1,0]
	v_exp_f32_e32 v113, v113
	v_rcp_f32_e32 v110, v110
	v_rcp_f32_e32 v111, v111
	v_pk_mul_f32 v[108:109], v[108:109], v[118:119] op_sel_hi:[1,0]
	v_exp_f32_e32 v126, v126
	v_exp_f32_e32 v127, v127
	v_pk_mul_f32 v[108:109], v[108:109], v[110:111]
	v_pk_add_f32 v[110:111], v[112:113], 1.0 op_sel_hi:[1,0]
	v_pk_mul_f32 v[112:113], v[104:105], v[124:125] op_sel_hi:[1,0]
	v_rcp_f32_e32 v110, v110
	v_exp_f32_e32 v112, v112
	v_exp_f32_e32 v113, v113
	v_rcp_f32_e32 v111, v111
	v_pk_add_f32 v[120:121], v[126:127], 1.0 op_sel_hi:[1,0]
	v_fmamk_f32 v157, v157, 0x3a800000, v172
	v_pk_add_f32 v[102:103], v[112:113], 1.0 op_sel_hi:[1,0]
	v_rcp_f32_e32 v120, v120
	v_rcp_f32_e32 v102, v102
	v_rcp_f32_e32 v103, v103
	v_rcp_f32_e32 v121, v121
	v_rsq_f32_e32 v157, v157
	v_pk_mul_f32 v[98:99], v[98:99], v[118:119] op_sel_hi:[1,0]
	v_pk_mul_f32 v[106:107], v[106:107], v[118:119] op_sel_hi:[1,0]
	v_pk_mul_f32 v[104:105], v[98:99], v[110:111]
	v_pk_mul_f32 v[98:99], v[100:101], v[118:119] op_sel_hi:[1,0]
	v_pk_mul_f32 v[106:107], v[106:107], v[120:121]
	v_pk_mul_f32 v[102:103], v[98:99], v[102:103]
	v_cvt_pk_bf16_f32 v98, v106, v107
	v_cvt_pk_bf16_f32 v99, v108, v109
	v_cvt_pk_bf16_f32 v100, v104, v105
	v_mul_f32_e32 v104, 0xbfb8aa3b, v157
	v_cvt_pk_bf16_f32 v101, v102, v103
	v_mad_i64_i32 v[102:103], s[24:25], v160, s44, v[114:115]
	v_lshl_add_u64 v[102:103], v[102:103], 0, v[116:117]
	global_store_dwordx4 v[102:103], v[98:101], off nt
	v_pk_mul_f32 v[102:103], v[96:97], v[104:105] op_sel_hi:[1,0]
	v_pk_mul_f32 v[106:107], v[94:95], v[104:105] op_sel_hi:[1,0]
	v_exp_f32_e32 v102, v102
	v_exp_f32_e32 v103, v103
	v_pk_mul_f32 v[96:97], v[86:87], v[104:105] op_sel_hi:[1,0]
	v_mul_f32_e32 v98, v157, v157
	v_exp_f32_e32 v96, v96
	v_pk_add_f32 v[94:95], v[102:103], 1.0 op_sel_hi:[1,0]
	v_exp_f32_e32 v97, v97
	v_rcp_f32_e32 v94, v94
	v_rcp_f32_e32 v95, v95
	v_pk_mul_f32 v[92:93], v[92:93], v[98:99] op_sel_hi:[1,0]
; __device__ __forceinline__ unsigned cvt_pk_bf16(float lo, float hi) { unsigned r; asm volatile("v_cvt_pk_bf16_f32 %0, %1, %2" : "=v"(r) : "v"(lo), "v"(hi)); return r; }
;     __device__ __forceinline__ void operator()(const pg8::f32x4 (&acc)[2][2][4][2], const Unit& u, int wr, int wc, int fr, int fq) const {
;     ...
;         for (int ai = 0; ai < 2; ++ai)
; #pragma unroll
;             for (int m = 0; m < 4; ++m) { float r[8]; const float rs = rsv[ai * 4 + m]; const float c1 = -1.4426950408889634f * rs, rs2 = rs * rs;
; #pragma unroll
;                 for (int n = 0; n < 2; ++n)
; #pragma unroll
;                     for (int e = 0; e < 4; e += 2) { const f32x2 ag = {acc[ai][0][m][n][e], acc[ai][0][m][n][e + 1]}, au = {acc[ai][1][m][n][e], acc[ai][1][m][n][e + 1]};
;                         const f32x2 t = ag * c1; f32x2 d; d.x = __builtin_amdgcn_exp2f(t.x); d.y = __builtin_amdgcn_exp2f(t.y); d = d + 1.0f;
;                         f32x2 q; q.x = __builtin_amdgcn_rcpf(d.x); q.y = __builtin_amdgcn_rcpf(d.y); const f32x2 o = (ag * au) * rs2 * q; r[4 * n + e] = o.x; r[4 * n + e + 1] = o.y; }
;                 v4u w; w.x = cvt_pk_bf16(r[0], r[1]); w.y = cvt_pk_bf16(r[2], r[3]); w.z = cvt_pk_bf16(r[4], r[5]); w.w = cvt_pk_bf16(r[6], r[7]);
;                 __builtin_nontemporal_store(w, (v4u*)(O + (size_t)(row0 + ai * HALF + m * 16) * FF + col0)); }
	v_exp_f32_e32 v106, v106
	v_exp_f32_e32 v107, v107
	v_pk_mul_f32 v[92:93], v[92:93], v[94:95]
	v_pk_add_f32 v[94:95], v[96:97], 1.0 op_sel_hi:[1,0]
	v_pk_mul_f32 v[96:97], v[88:89], v[104:105] op_sel_hi:[1,0]
	v_rcp_f32_e32 v94, v94
	v_exp_f32_e32 v96, v96
	v_exp_f32_e32 v97, v97
	v_rcp_f32_e32 v95, v95
	v_pk_add_f32 v[100:101], v[106:107], 1.0 op_sel_hi:[1,0]
	v_fmamk_f32 v159, v159, 0x3a800000, v172
	v_pk_add_f32 v[86:87], v[96:97], 1.0 op_sel_hi:[1,0]
	v_rcp_f32_e32 v100, v100
	v_rcp_f32_e32 v86, v86
	v_rcp_f32_e32 v87, v87
	v_rcp_f32_e32 v101, v101
	v_rsq_f32_e32 v159, v159
	v_pk_mul_f32 v[82:83], v[82:83], v[98:99] op_sel_hi:[1,0]
	v_pk_mul_f32 v[90:91], v[90:91], v[98:99] op_sel_hi:[1,0]
	v_pk_mul_f32 v[88:89], v[82:83], v[94:95]
	v_pk_mul_f32 v[82:83], v[84:85], v[98:99] op_sel_hi:[1,0]
	v_pk_mul_f32 v[90:91], v[90:91], v[100:101]
	v_pk_mul_f32 v[86:87], v[82:83], v[86:87]
	v_cvt_pk_bf16_f32 v82, v90, v91
	v_cvt_pk_bf16_f32 v83, v92, v93
	v_cvt_pk_bf16_f32 v84, v88, v89
	v_mul_f32_e32 v88, 0xbfb8aa3b, v159
	v_cvt_pk_bf16_f32 v85, v86, v87
	v_mad_i64_i32 v[86:87], s[24:25], v158, s44, v[114:115]
	v_lshl_add_u64 v[86:87], v[86:87], 0, v[116:117]
	global_store_dwordx4 v[86:87], v[82:85], off nt
	v_pk_mul_f32 v[86:87], v[80:81], v[88:89] op_sel_hi:[1,0]
	v_pk_mul_f32 v[90:91], v[78:79], v[88:89] op_sel_hi:[1,0]
	v_exp_f32_e32 v86, v86
	v_exp_f32_e32 v87, v87
	v_pk_mul_f32 v[80:81], v[70:71], v[88:89] op_sel_hi:[1,0]
	v_mul_f32_e32 v82, v159, v159
	v_exp_f32_e32 v80, v80
	v_pk_add_f32 v[78:79], v[86:87], 1.0 op_sel_hi:[1,0]
	v_exp_f32_e32 v81, v81
	v_rcp_f32_e32 v78, v78
	v_rcp_f32_e32 v79, v79
	v_pk_mul_f32 v[76:77], v[76:77], v[82:83] op_sel_hi:[1,0]
	v_exp_f32_e32 v90, v90
	v_exp_f32_e32 v91, v91
	v_pk_mul_f32 v[76:77], v[76:77], v[78:79]
	v_pk_add_f32 v[78:79], v[80:81], 1.0 op_sel_hi:[1,0]
	v_pk_mul_f32 v[80:81], v[72:73], v[88:89] op_sel_hi:[1,0]
	v_rcp_f32_e32 v78, v78
	v_exp_f32_e32 v80, v80
	v_exp_f32_e32 v81, v81
	v_rcp_f32_e32 v79, v79
	v_pk_add_f32 v[84:85], v[90:91], 1.0 op_sel_hi:[1,0]
	v_fmamk_f32 v163, v163, 0x3a800000, v172
	v_pk_add_f32 v[70:71], v[80:81], 1.0 op_sel_hi:[1,0]
	v_rcp_f32_e32 v84, v84
	v_rcp_f32_e32 v70, v70
	v_rcp_f32_e32 v71, v71
	v_rcp_f32_e32 v85, v85
	v_rsq_f32_e32 v163, v163
	v_pk_mul_f32 v[66:67], v[66:67], v[82:83] op_sel_hi:[1,0]
	v_pk_mul_f32 v[74:75], v[74:75], v[82:83] op_sel_hi:[1,0]
	v_pk_mul_f32 v[72:73], v[66:67], v[78:79]
	v_pk_mul_f32 v[66:67], v[68:69], v[82:83] op_sel_hi:[1,0]
	v_pk_mul_f32 v[74:75], v[74:75], v[84:85]
	v_pk_mul_f32 v[70:71], v[66:67], v[70:71]
	v_cvt_pk_bf16_f32 v66, v74, v75
	v_cvt_pk_bf16_f32 v67, v76, v77
	v_cvt_pk_bf16_f32 v68, v72, v73
	v_mul_f32_e32 v72, 0xbfb8aa3b, v163
	v_cvt_pk_bf16_f32 v69, v70, v71
	v_mad_i64_i32 v[70:71], s[24:25], v156, s44, v[114:115]
	v_lshl_add_u64 v[70:71], v[70:71], 0, v[116:117]
	global_store_dwordx4 v[70:71], v[66:69], off nt
	v_pk_mul_f32 v[70:71], v[64:65], v[72:73] op_sel_hi:[1,0]
	v_pk_mul_f32 v[74:75], v[62:63], v[72:73] op_sel_hi:[1,0]
	v_exp_f32_e32 v70, v70
	v_exp_f32_e32 v71, v71
	v_pk_mul_f32 v[64:65], v[54:55], v[72:73] op_sel_hi:[1,0]
	v_mul_f32_e32 v66, v163, v163
	v_exp_f32_e32 v64, v64
	v_pk_add_f32 v[62:63], v[70:71], 1.0 op_sel_hi:[1,0]
	v_exp_f32_e32 v65, v65
	v_rcp_f32_e32 v62, v62
	v_rcp_f32_e32 v63, v63
	v_pk_mul_f32 v[60:61], v[60:61], v[66:67] op_sel_hi:[1,0]
	v_exp_f32_e32 v74, v74
	v_exp_f32_e32 v75, v75
	v_pk_mul_f32 v[60:61], v[60:61], v[62:63]
	v_pk_add_f32 v[62:63], v[64:65], 1.0 op_sel_hi:[1,0]
	v_pk_mul_f32 v[64:65], v[56:57], v[72:73] op_sel_hi:[1,0]
	v_rcp_f32_e32 v62, v62
	v_exp_f32_e32 v64, v64
	v_exp_f32_e32 v65, v65
	v_rcp_f32_e32 v63, v63
	v_pk_add_f32 v[68:69], v[74:75], 1.0 op_sel_hi:[1,0]
	v_fmamk_f32 v161, v161, 0x3a800000, v172
	v_pk_add_f32 v[54:55], v[64:65], 1.0 op_sel_hi:[1,0]
	v_rcp_f32_e32 v68, v68
	v_rcp_f32_e32 v54, v54
	v_rcp_f32_e32 v55, v55
	v_rcp_f32_e32 v69, v69
	v_rsq_f32_e32 v161, v161
	v_pk_mul_f32 v[50:51], v[50:51], v[66:67] op_sel_hi:[1,0]
	v_pk_mul_f32 v[58:59], v[58:59], v[66:67] op_sel_hi:[1,0]
	v_pk_mul_f32 v[56:57], v[50:51], v[62:63]
	v_pk_mul_f32 v[50:51], v[52:53], v[66:67] op_sel_hi:[1,0]
	v_pk_mul_f32 v[58:59], v[58:59], v[68:69]
	v_pk_mul_f32 v[54:55], v[50:51], v[54:55]
	v_cvt_pk_bf16_f32 v50, v58, v59
	v_cvt_pk_bf16_f32 v51, v60, v61
	v_cvt_pk_bf16_f32 v52, v56, v57
	v_mul_f32_e32 v56, 0xbfb8aa3b, v161
	v_cvt_pk_bf16_f32 v53, v54, v55
	v_mad_i64_i32 v[54:55], s[24:25], v154, s44, v[114:115]
	v_lshl_add_u64 v[54:55], v[54:55], 0, v[116:117]
	global_store_dwordx4 v[54:55], v[50:53], off nt
	v_pk_mul_f32 v[54:55], v[48:49], v[56:57] op_sel_hi:[1,0]
	v_pk_mul_f32 v[58:59], v[46:47], v[56:57] op_sel_hi:[1,0]
	v_exp_f32_e32 v54, v54
	v_exp_f32_e32 v55, v55
	v_pk_mul_f32 v[48:49], v[38:39], v[56:57] op_sel_hi:[1,0]
; __device__ __forceinline__ unsigned cvt_pk_bf16(float lo, float hi) { unsigned r; asm volatile("v_cvt_pk_bf16_f32 %0, %1, %2" : "=v"(r) : "v"(lo), "v"(hi)); return r; }
; #define PG8_BAR __builtin_amdgcn_s_barrier()
; template <class Epi, class Sched, bool ALIGN_EPI = false, bool SP2 = false>
; __device__ __forceinline__ void gemm_phase(PG8_LAS unsigned char* lds, const Gemm g, const Sched& S, const Epi& E) {
;     ...
;         if (!has_next) break;
; #pragma unroll
;         for (int a = 0; a < 2; ++a)
; #pragma unroll
;             for (int b = 0; b < 2; ++b)
; #pragma unroll
;                 for (int m = 0; m < 4; ++m)
; #pragma unroll
;                     for (int n = 0; n < 2; ++n) acc[a][b][m][n] = (f32x4){0.f, 0.f, 0.f, 0.f};
;         cur = nxt; cA = nA; cB = nB; ++ui;
;         if constexpr (ALIGN_EPI) { if (wr == 1) PG8_BAR; }
;     __device__ __forceinline__ void operator()(const pg8::f32x4 (&acc)[2][2][4][2], const Unit& u, int wr, int wc, int fr, int fq) const {
;     ...
;         for (int ai = 0; ai < 2; ++ai)
; #pragma unroll
;             for (int m = 0; m < 4; ++m) { float r[8]; const float rs = rsv[ai * 4 + m]; const float c1 = -1.4426950408889634f * rs, rs2 = rs * rs;
; #pragma unroll
;                 for (int n = 0; n < 2; ++n)
; #pragma unroll
;                     for (int e = 0; e < 4; e += 2) { const f32x2 ag = {acc[ai][0][m][n][e], acc[ai][0][m][n][e + 1]}, au = {acc[ai][1][m][n][e], acc[ai][1][m][n][e + 1]};
;                         const f32x2 t = ag * c1; f32x2 d; d.x = __builtin_amdgcn_exp2f(t.x); d.y = __builtin_amdgcn_exp2f(t.y); d = d + 1.0f;
;                         f32x2 q; q.x = __builtin_amdgcn_rcpf(d.x); q.y = __builtin_amdgcn_rcpf(d.y); const f32x2 o = (ag * au) * rs2 * q; r[4 * n + e] = o.x; r[4 * n + e + 1] = o.y; }
;                 v4u w; w.x = cvt_pk_bf16(r[0], r[1]); w.y = cvt_pk_bf16(r[2], r[3]); w.z = cvt_pk_bf16(r[4], r[5]); w.w = cvt_pk_bf16(r[6], r[7]);
;                 __builtin_nontemporal_store(w, (v4u*)(O + (size_t)(row0 + ai * HALF + m * 16) * FF + col0)); }
	v_mul_f32_e32 v50, v161, v161
	v_exp_f32_e32 v48, v48
	v_pk_add_f32 v[46:47], v[54:55], 1.0 op_sel_hi:[1,0]
	v_exp_f32_e32 v49, v49
	v_rcp_f32_e32 v46, v46
	v_rcp_f32_e32 v47, v47
	v_pk_mul_f32 v[44:45], v[44:45], v[50:51] op_sel_hi:[1,0]
	v_exp_f32_e32 v58, v58
	v_exp_f32_e32 v59, v59
	v_pk_mul_f32 v[44:45], v[44:45], v[46:47]
	v_pk_add_f32 v[46:47], v[48:49], 1.0 op_sel_hi:[1,0]
	v_pk_mul_f32 v[48:49], v[40:41], v[56:57] op_sel_hi:[1,0]
	v_rcp_f32_e32 v46, v46
	v_exp_f32_e32 v48, v48
	v_exp_f32_e32 v49, v49
	v_rcp_f32_e32 v47, v47
	v_pk_add_f32 v[52:53], v[58:59], 1.0 op_sel_hi:[1,0]
	v_fmamk_f32 v151, v151, 0x3a800000, v172
	v_pk_add_f32 v[38:39], v[48:49], 1.0 op_sel_hi:[1,0]
	v_rcp_f32_e32 v52, v52
	v_rcp_f32_e32 v38, v38
	v_rcp_f32_e32 v39, v39
	v_rcp_f32_e32 v53, v53
	v_rsq_f32_e32 v151, v151
	v_pk_mul_f32 v[34:35], v[34:35], v[50:51] op_sel_hi:[1,0]
	v_pk_mul_f32 v[42:43], v[42:43], v[50:51] op_sel_hi:[1,0]
	v_pk_mul_f32 v[40:41], v[34:35], v[46:47]
	v_pk_mul_f32 v[34:35], v[36:37], v[50:51] op_sel_hi:[1,0]
	v_pk_mul_f32 v[42:43], v[42:43], v[52:53]
	v_pk_mul_f32 v[38:39], v[34:35], v[38:39]
	v_cvt_pk_bf16_f32 v34, v42, v43
	v_cvt_pk_bf16_f32 v35, v44, v45
	v_cvt_pk_bf16_f32 v36, v40, v41
	v_mul_f32_e32 v40, 0xbfb8aa3b, v151
	v_cvt_pk_bf16_f32 v37, v38, v39
	v_mad_i64_i32 v[38:39], s[24:25], v152, s44, v[114:115]
	v_lshl_add_u64 v[38:39], v[38:39], 0, v[116:117]
	global_store_dwordx4 v[38:39], v[34:37], off nt
	v_pk_mul_f32 v[38:39], v[32:33], v[40:41] op_sel_hi:[1,0]
	v_pk_mul_f32 v[42:43], v[30:31], v[40:41] op_sel_hi:[1,0]
	v_exp_f32_e32 v38, v38
	v_exp_f32_e32 v39, v39
	v_pk_mul_f32 v[32:33], v[22:23], v[40:41] op_sel_hi:[1,0]
	v_mul_f32_e32 v34, v151, v151
	v_exp_f32_e32 v32, v32
	v_pk_add_f32 v[30:31], v[38:39], 1.0 op_sel_hi:[1,0]
	v_exp_f32_e32 v33, v33
	v_rcp_f32_e32 v30, v30
	v_rcp_f32_e32 v31, v31
	v_pk_mul_f32 v[28:29], v[28:29], v[34:35] op_sel_hi:[1,0]
	v_exp_f32_e32 v42, v42
	v_exp_f32_e32 v43, v43
	v_pk_mul_f32 v[28:29], v[28:29], v[30:31]
	v_pk_add_f32 v[30:31], v[32:33], 1.0 op_sel_hi:[1,0]
	v_pk_mul_f32 v[32:33], v[24:25], v[40:41] op_sel_hi:[1,0]
	v_rcp_f32_e32 v30, v30
	v_exp_f32_e32 v32, v32
	v_exp_f32_e32 v33, v33
	v_rcp_f32_e32 v31, v31
	v_pk_add_f32 v[36:37], v[42:43], 1.0 op_sel_hi:[1,0]
	v_fmamk_f32 v149, v149, 0x3a800000, v172
	v_pk_add_f32 v[22:23], v[32:33], 1.0 op_sel_hi:[1,0]
	v_rcp_f32_e32 v36, v36
	v_rcp_f32_e32 v22, v22
	v_rcp_f32_e32 v23, v23
	v_rcp_f32_e32 v37, v37
	v_rsq_f32_e32 v149, v149
	v_pk_mul_f32 v[18:19], v[18:19], v[34:35] op_sel_hi:[1,0]
	v_pk_mul_f32 v[26:27], v[26:27], v[34:35] op_sel_hi:[1,0]
	v_pk_mul_f32 v[24:25], v[18:19], v[30:31]
	v_pk_mul_f32 v[18:19], v[20:21], v[34:35] op_sel_hi:[1,0]
	v_pk_mul_f32 v[26:27], v[26:27], v[36:37]
	v_pk_mul_f32 v[22:23], v[18:19], v[22:23]
	v_cvt_pk_bf16_f32 v18, v26, v27
	v_cvt_pk_bf16_f32 v19, v28, v29
	v_cvt_pk_bf16_f32 v20, v24, v25
	v_mul_f32_e32 v24, 0xbfb8aa3b, v149
	v_cvt_pk_bf16_f32 v21, v22, v23
	v_mad_i64_i32 v[22:23], s[24:25], v150, s44, v[114:115]
	v_lshl_add_u64 v[22:23], v[22:23], 0, v[116:117]
	global_store_dwordx4 v[22:23], v[18:21], off nt
	v_pk_mul_f32 v[22:23], v[16:17], v[24:25] op_sel_hi:[1,0]
	v_pk_mul_f32 v[26:27], v[14:15], v[24:25] op_sel_hi:[1,0]
	v_exp_f32_e32 v22, v22
	v_exp_f32_e32 v23, v23
	v_pk_mul_f32 v[16:17], v[6:7], v[24:25] op_sel_hi:[1,0]
	v_mul_f32_e32 v18, v149, v149
	v_exp_f32_e32 v16, v16
	v_pk_add_f32 v[14:15], v[22:23], 1.0 op_sel_hi:[1,0]
	v_exp_f32_e32 v17, v17
	v_rcp_f32_e32 v14, v14
	v_rcp_f32_e32 v15, v15
	v_pk_mul_f32 v[12:13], v[12:13], v[18:19] op_sel_hi:[1,0]
	v_exp_f32_e32 v26, v26
	v_exp_f32_e32 v27, v27
	v_pk_mul_f32 v[12:13], v[12:13], v[14:15]
	v_pk_add_f32 v[14:15], v[16:17], 1.0 op_sel_hi:[1,0]
	v_pk_mul_f32 v[16:17], v[8:9], v[24:25] op_sel_hi:[1,0]
	v_rcp_f32_e32 v14, v14
	v_exp_f32_e32 v16, v16
	v_exp_f32_e32 v17, v17
	v_rcp_f32_e32 v15, v15
	v_pk_add_f32 v[20:21], v[26:27], 1.0 op_sel_hi:[1,0]
	v_pk_mul_f32 v[2:3], v[2:3], v[18:19] op_sel_hi:[1,0]
	v_pk_add_f32 v[6:7], v[16:17], 1.0 op_sel_hi:[1,0]
	v_rcp_f32_e32 v20, v20
	v_rcp_f32_e32 v6, v6
	v_rcp_f32_e32 v7, v7
	v_rcp_f32_e32 v21, v21
	v_pk_mul_f32 v[8:9], v[2:3], v[14:15]
	v_pk_mul_f32 v[2:3], v[4:5], v[18:19] op_sel_hi:[1,0]
	v_pk_mul_f32 v[10:11], v[10:11], v[18:19] op_sel_hi:[1,0]
	v_pk_mul_f32 v[6:7], v[2:3], v[6:7]
	v_pk_mul_f32 v[10:11], v[10:11], v[20:21]
	s_nop 0
	v_cvt_pk_bf16_f32 v2, v10, v11
	v_cvt_pk_bf16_f32 v3, v12, v13
	v_cvt_pk_bf16_f32 v4, v8, v9
	v_cvt_pk_bf16_f32 v5, v6, v7
	v_mad_i64_i32 v[6:7], s[24:25], v148, s44, v[114:115]
	v_lshl_add_u64 v[6:7], v[6:7], 0, v[116:117]
	global_store_dwordx4 v[6:7], v[2:5], off nt
	s_cbranch_vccnz .LBB0_687
	s_andn2_b64 vcc, exec, s[4:5]
	s_cbranch_vccnz .LBB0_686
	s_barrier
	s_branch .LBB0_686

; __device__ __forceinline__ unsigned cvt_pk_bf16(float lo, float hi) { unsigned r; asm volatile("v_cvt_pk_bf16_f32 %0, %1, %2" : "=v"(r) : "v"(lo), "v"(hi)); return r; }
; __device__ __forceinline__ float bflo(unsigned w) { return __uint_as_float(w << 16); }
; __device__ __forceinline__ float bfhi(unsigned w) { return __uint_as_float(w & 0xffff0000u); }
;     __device__ __forceinline__ void ld(Ld& L, size_t o) const {
; #pragma unroll
;         for (int bj = 0; bj < 2; ++bj) { if (BASEF32) { L.a[bj][0] = *(const f32x4*)((const float*)base + o + bj * HALF); L.a[bj][1] = *(const f32x4*)((const float*)base + o + bj * HALF + 4); }
;             else { const v4u w = *(const v4u*)((const bf16*)base + o + bj * HALF); L.a[bj][0] = __builtin_bit_cast(f32x4, w); } }
;     }
;     __device__ __forceinline__ void operator()(const pg8::f32x4 (&acc)[2][2][4][2], const Unit& u, int wr, int wc, int fr, int fq) const {
;         const int row0 = u.pm * BM + wr * 64 + fr, col0 = u.pn * BM + wc * 32 + 8 * fq;
;         Ld nx; ld(nx, (size_t)row0 * DM_ + col0);
; #pragma unroll
;         for (int k = 0; k < 8; ++k) { const int ai = k >> 2, m = k & 3; const int row = row0 + ai * HALF + m * 16; float q = 0.f; const Ld cu = nx;
;             if (k < 7) ld(nx, (size_t)(row0 + ((k + 1) >> 2) * HALF + ((k + 1) & 3) * 16) * DM_ + col0);
; #pragma unroll
;             for (int bj = 0; bj < 2; ++bj) { const size_t o = (size_t)row * DM_ + col0 + bj * HALF; f32x4 b0, b1;
;                 if (BASEF32) { b0 = cu.a[bj][0]; b1 = cu.a[bj][1]; }
;                 else { const v4u w = __builtin_bit_cast(v4u, cu.a[bj][0]); b0 = (f32x4){bflo(w.x), bfhi(w.x), bflo(w.y), bfhi(w.y)}; b1 = (f32x4){bflo(w.z), bfhi(w.z), bflo(w.w), bfhi(w.w)}; }
;                 const f32x4 r0 = b0 + acc[ai][bj][m][0], r1 = b1 + acc[ai][bj][m][1];
;                 q += (r0[0] * r0[0] + r0[1] * r0[1]) + (r0[2] * r0[2] + r0[3] * r0[3]) + (r1[0] * r1[0] + r1[1] * r1[1]) + (r1[2] * r1[2] + r1[3] * r1[3]);
;                 v4u w; w.x = cvt_pk_bf16(r0[0], r0[1]); w.y = cvt_pk_bf16(r0[2], r0[3]); w.z = cvt_pk_bf16(r1[0], r1[1]); w.w = cvt_pk_bf16(r1[2], r1[3]); *(v4u*)(out + o) = w; }
;             q += __shfl_xor(q, 16); q += __shfl_xor(q, 32); if (fq == 0) ssq[(size_t)row * 16 + u.pn * 4 + wc] = q; }
.LBB0_779:
	v_lshl_add_u32 v156, s52, 8, v1
	v_lshl_or_b32 v154, s51, 8, v163
	v_ashrrev_i32_e32 v157, 31, v156
	v_ashrrev_i32_e32 v155, 31, v154
	v_lshlrev_b64 v[130:131], 11, v[156:157]
	v_lshl_add_u64 v[130:131], s[16:17], 0, v[130:131]
	v_lshlrev_b64 v[132:133], 1, v[154:155]
	v_lshl_add_u64 v[178:179], v[130:131], 0, v[132:133]
	global_load_dwordx4 v[170:173], v[178:179], off
	global_load_dwordx4 v[174:177], v[178:179], off offset:256
	v_or_b32_e32 v158, 16, v156
	v_ashrrev_i32_e32 v159, 31, v158
	v_lshlrev_b64 v[130:131], 11, v[158:159]
	v_lshl_add_u64 v[130:131], s[16:17], 0, v[130:131]
	v_lshl_add_u64 v[160:161], v[130:131], 0, v[132:133]
	global_load_dwordx4 v[134:137], v[160:161], off
	global_load_dwordx4 v[130:133], v[160:161], off offset:256
	v_and_b32_e32 v169, 64, v167
	v_xor_b32_e32 v168, 16, v167
	v_add_u32_e32 v169, 64, v169
	v_xor_b32_e32 v180, 32, v167
	v_cmp_lt_i32_e32 vcc, v168, v169
	s_lshl_b32 s26, s51, 2
	s_ashr_i32 s27, s26, 31
	v_cndmask_b32_e32 v168, v167, v168, vcc
	v_cmp_lt_i32_e32 vcc, v180, v169
	v_lshlrev_b32_e32 v168, 2, v168
	s_and_b64 s[98:99], exec, s[22:23]
	s_cbranch_scc0 .Lal_5
	s_barrier
.Lal_5:
	s_waitcnt vmcnt(0)
	v_and_b32_e32 v181, 0xffff0000, v170
	v_cndmask_b32_e32 v169, v167, v180, vcc
	v_lshlrev_b32_e32 v180, 16, v170
	v_lshlrev_b32_e32 v170, 16, v171
	v_and_b32_e32 v171, 0xffff0000, v171
	v_lshlrev_b32_e32 v184, 16, v174
	v_and_b32_e32 v185, 0xffff0000, v174
	v_lshlrev_b32_e32 v174, 16, v175
	v_and_b32_e32 v175, 0xffff0000, v175
	v_lshlrev_b32_e32 v182, 16, v172
	v_and_b32_e32 v183, 0xffff0000, v172
	v_lshlrev_b32_e32 v172, 16, v173
	v_and_b32_e32 v173, 0xffff0000, v173
	v_lshlrev_b32_e32 v186, 16, v176
	v_and_b32_e32 v187, 0xffff0000, v176
	v_lshlrev_b32_e32 v176, 16, v177
	v_and_b32_e32 v177, 0xffff0000, v177
	v_pk_add_f32 v[128:129], v[128:129], v[170:171]
	v_pk_add_f32 v[126:127], v[126:127], v[180:181]
	v_pk_add_f32 v[120:121], v[120:121], v[174:175]
	v_pk_add_f32 v[118:119], v[118:119], v[184:185]
	v_pk_add_f32 v[124:125], v[124:125], v[172:173]
	v_pk_add_f32 v[122:123], v[122:123], v[182:183]
	v_pk_add_f32 v[170:171], v[116:117], v[176:177]
	v_pk_add_f32 v[172:173], v[114:115], v[186:187]
	v_mul_f32_e32 v116, v127, v127
	v_mul_f32_e32 v117, v129, v129
	v_cvt_pk_bf16_f32 v114, v126, v127
	v_cvt_pk_bf16_f32 v115, v128, v129
	v_mul_f32_e32 v127, v119, v119
	v_mul_f32_e32 v129, v121, v121
	v_mul_f32_e32 v174, v123, v123
	v_mul_f32_e32 v176, v173, v173
	v_fmac_f32_e32 v116, v126, v126
	v_fmac_f32_e32 v117, v128, v128
	v_fmac_f32_e32 v127, v118, v118
	v_fmac_f32_e32 v129, v120, v120
	v_mul_f32_e32 v175, v125, v125
	v_mul_f32_e32 v177, v171, v171
	v_fmac_f32_e32 v174, v122, v122
	v_fmac_f32_e32 v176, v172, v172
	v_add_f32_e32 v116, v116, v117
	v_add_f32_e32 v117, v127, v129
	v_fmac_f32_e32 v175, v124, v124
	v_fmac_f32_e32 v177, v170, v170
	v_add_f32_e32 v116, v174, v116
	v_add_f32_e32 v117, v176, v117
	v_add_f32_e32 v116, v175, v116
	v_add_f32_e32 v117, v177, v117
	v_add_f32_e32 v126, v116, v117
	v_mov_b32_e32 v127, v126
	s_nop 1
	v_permlane16_swap_b32 v126, v127
	v_cvt_pk_bf16_f32 v116, v122, v123
	v_cvt_pk_bf16_f32 v117, v124, v125
	global_store_dwordx4 v[178:179], v[114:117], off
	s_waitcnt lgkmcnt(0)
	s_nop 0
	v_add_f32_e32 v114, v126, v127
	v_lshlrev_b32_e32 v126, 2, v169
	v_mov_b32_e32 v115, v114
	s_nop 1
	v_permlane32_swap_b32 v114, v115
	v_cvt_pk_bf16_f32 v116, v118, v119
	v_cvt_pk_bf16_f32 v117, v120, v121
	v_cvt_pk_bf16_f32 v118, v172, v173
	v_cvt_pk_bf16_f32 v119, v170, v171
	global_store_dwordx4 v[178:179], v[116:119], off offset:256
	s_and_saveexec_b64 s[28:29], s[8:9]
	s_cbranch_execz .LBB0_781
	v_lshlrev_b64 v[116:117], 6, v[156:157]
	v_lshl_add_u64 v[116:117], s[18:19], 0, v[116:117]
	v_lshl_add_u64 v[116:117], s[26:27], 2, v[116:117]
	s_lshl_b32 s4, s40, 2
	v_lshl_add_u64 v[116:117], v[116:117], 0, s[4:5]
	s_waitcnt lgkmcnt(0)
	v_add_f32_e32 v114, v114, v115
	global_store_dword v[116:117], v114, off

; __device__ __forceinline__ void rstd8(const float* ss, int row0, int fq, float (&rs)[8]) {
;     f32x4 a[8];
; #pragma unroll
;     for (int k = 0; k < 8; ++k) a[k] = *(const f32x4*)(ss + (size_t)(row0 + (k >> 2) * 128 + (k & 3) * 16) * 16 + 4 * fq);
; #pragma unroll
;     for (int k = 0; k < 8; ++k) { float s = (a[k][0] + a[k][1]) + (a[k][2] + a[k][3]); s += __shfl_xor(s, 16); s += __shfl_xor(s, 32); rs[k] = __builtin_amdgcn_rsqf(s * (1.f / 1024.f) + EPS); }
;     __device__ __forceinline__ void operator()(const pg8::f32x4 (&acc)[2][2][4][2], const Unit& u, int wr, int wc, int fr, int fq) const {
;         const int row0 = u.pm * BM + wr * 64 + fr, col0 = u.pn * BM + wc * 32 + 8 * fq;
;         float rsv[8]; rstd8(ss, row0, fq, rsv);
;         v4u nb[2], np[2];
; #pragma unroll
;         for (int bj = 0; bj < 2; ++bj) { const size_t o = (size_t)row0 * DM_ + col0 + bj * HALF; nb[bj] = *(const v4u*)(base + o); np[bj] = *(const v4u*)(pp + o); }
; #pragma unroll
;         for (int k = 0; k < 8; ++k) { const int ai = k >> 2, m = k & 3; const int row = row0 + ai * HALF + m * 16; const float rs = rsv[k]; float q = 0.f;
;             v4u cb[2], cp[2];
; #pragma unroll
;             for (int bj = 0; bj < 2; ++bj) { cb[bj] = nb[bj]; cp[bj] = np[bj]; }
;             if (k < 7) {
; #pragma unroll
;                 for (int bj = 0; bj < 2; ++bj) { const size_t o = (size_t)(row0 + ((k + 1) >> 2) * HALF + ((k + 1) & 3) * 16) * DM_ + col0 + bj * HALF; nb[bj] = *(const v4u*)(base + o); np[bj] = *(const v4u*)(pp + o); } }
.LBB0_906:
	v_lshl_add_u32 v226, s12, 8, v1
	v_or_b32_e32 v180, 16, v226
	v_ashrrev_i32_e32 v227, 31, v226
	v_ashrrev_i32_e32 v181, 31, v180
	v_or_b32_e32 v176, 32, v226
	v_or_b32_e32 v172, 48, v226
	v_add_u32_e32 v166, 0x80, v226
	v_lshlrev_b64 v[182:183], 6, v[226:227]
	v_lshlrev_b64 v[178:179], 6, v[180:181]
	v_ashrrev_i32_e32 v177, 31, v176
	v_ashrrev_i32_e32 v173, 31, v172
	v_ashrrev_i32_e32 v167, 31, v166
	v_lshl_add_u64 v[164:165], v[154:155], 0, v[182:183]
	v_lshl_add_u64 v[134:135], v[154:155], 0, v[178:179]
	v_lshlrev_b64 v[174:175], 6, v[176:177]
	v_lshlrev_b64 v[170:171], 6, v[172:173]
	v_lshlrev_b64 v[168:169], 6, v[166:167]
	global_load_dwordx4 v[130:133], v[164:165], off
	s_nop 0
	global_load_dwordx4 v[134:137], v[134:135], off
	v_lshl_add_u64 v[138:139], v[154:155], 0, v[174:175]
	v_lshl_add_u64 v[142:143], v[154:155], 0, v[170:171]
	v_lshl_add_u64 v[192:193], v[154:155], 0, v[168:169]
	global_load_dwordx4 v[138:141], v[138:139], off
	s_nop 0
	global_load_dwordx4 v[142:145], v[142:143], off
	v_add_co_u32_e32 v164, vcc, s48, v164
	global_load_dwordx4 v[194:197], v[192:193], off
	s_nop 0
	v_addc_co_u32_e32 v165, vcc, 0, v165, vcc
	global_load_dwordx4 v[198:201], v[164:165], off offset:1024
	global_load_dwordx4 v[202:205], v[164:165], off offset:2048
	global_load_dwordx4 v[206:209], v[164:165], off offset:3072
	v_and_b32_e32 v165, 64, v189
	v_xor_b32_e32 v191, 16, v189
	v_add_u32_e32 v193, 64, v165
	v_xor_b32_e32 v192, 32, v189
	v_cmp_lt_i32_e32 vcc, v191, v193
	v_lshl_or_b32 v164, s4, 8, v185
	v_ashrrev_i32_e32 v165, 31, v164
	v_cndmask_b32_e32 v191, v189, v191, vcc
	v_cmp_lt_i32_e32 vcc, v192, v193
	v_lshlrev_b64 v[210:211], 10, v[226:227]
	v_lshl_add_u64 v[210:211], v[210:211], 0, v[164:165]
	v_cndmask_b32_e32 v193, v189, v192, vcc
	v_lshlrev_b32_e32 v192, 2, v191
	v_lshlrev_b32_e32 v191, 2, v193
	v_lshlrev_b64 v[222:223], 1, v[210:211]
	v_lshl_add_u64 v[210:211], s[10:11], 0, v[222:223]
	v_lshl_add_u64 v[214:215], s[16:17], 0, v[222:223]
	global_load_dwordx4 v[210:213], v[210:211], off
	s_nop 0
	global_load_dwordx4 v[214:217], v[214:215], off
	v_or_b32_e32 v222, 0x100, v222
	v_lshlrev_b64 v[226:227], 11, v[226:227]
	s_lshl_b32 s4, s4, 2
	s_ashr_i32 s5, s4, 31
	s_and_b64 s[98:99], exec, s[24:25]
	s_cbranch_scc0 .Lal_6
	s_barrier
.Lal_6:
	s_waitcnt vmcnt(0)
	v_mov_b32_e32 v218, v131
	v_mov_b32_e32 v219, v132
	v_mov_b32_e32 v131, v133
	v_pk_add_f32 v[130:131], v[218:219], v[130:131]
	v_add_f32_e32 v132, v134, v135
	v_add_f32_e32 v133, v136, v137
	v_add_f32_e32 v134, v138, v139
	v_add_f32_e32 v135, v140, v141
	v_add_f32_e32 v138, v194, v195
	v_add_f32_e32 v139, v196, v197
	v_add_f32_e32 v130, v130, v131
	v_add_f32_e32 v131, v132, v133
	v_add_f32_e32 v132, v134, v135
	v_add_f32_e32 v134, v138, v139
	v_mov_b32_e32 v138, v130
	s_nop 1
	v_permlane16_swap_b32 v130, v138
	v_mov_b32_e32 v139, v131
	s_nop 1
	v_permlane16_swap_b32 v131, v139
	v_add_f32_e32 v136, v142, v143
	v_add_f32_e32 v137, v144, v145
	v_add_f32_e32 v142, v202, v203
	s_waitcnt lgkmcnt(1)
	v_add_f32_e32 v130, v130, v138
	v_add_f32_e32 v143, v204, v205
	s_waitcnt lgkmcnt(0)
	v_add_f32_e32 v205, v131, v139
	v_mov_b32_e32 v131, v130
	s_nop 1
	v_permlane32_swap_b32 v130, v131
	v_add_f32_e32 v144, v206, v207
	v_add_f32_e32 v145, v208, v209
	v_add_f32_e32 v133, v136, v137
	v_add_f32_e32 v136, v142, v143
	v_add_f32_e32 v137, v144, v145
	v_mov_b32_e32 v144, v136
	s_nop 1
	v_permlane16_swap_b32 v136, v144
	s_waitcnt lgkmcnt(1)
	v_add_f32_e32 v130, v130, v131
	v_fmamk_f32 v130, v130, 0x3a800000, v190
	v_add_f32_e32 v140, v198, v199
	v_add_f32_e32 v141, v200, v201
	s_waitcnt lgkmcnt(0)
	v_add_f32_e32 v195, v136, v144
	v_rsq_f32_e32 v136, v130
	v_lshl_add_u64 v[130:131], s[10:11], 0, v[222:223]
	global_load_dwordx4 v[218:221], v[130:131], off
	v_lshl_add_u64 v[130:131], s[16:17], 0, v[222:223]
	global_load_dwordx4 v[222:225], v[130:131], off
	v_add_f32_e32 v135, v140, v141
	v_mov_b32_e32 v140, v132
	s_nop 1
	v_permlane16_swap_b32 v132, v140
	v_mov_b32_e32 v141, v133
	s_nop 1
	v_permlane16_swap_b32 v133, v141
	v_mov_b32_e32 v142, v134
	s_nop 1
	v_permlane16_swap_b32 v134, v142
	v_mov_b32_e32 v143, v135
	s_nop 1
	v_permlane16_swap_b32 v135, v143
	v_mov_b32_e32 v145, v137
	s_nop 1
	v_permlane16_swap_b32 v137, v145
	v_lshlrev_b64 v[130:131], 10, v[180:181]
	v_lshl_add_u64 v[130:131], v[130:131], 0, v[164:165]
	v_lshlrev_b64 v[130:131], 1, v[130:131]
	s_waitcnt lgkmcnt(4)
	v_add_f32_e32 v203, v132, v140
	s_waitcnt lgkmcnt(3)
	v_add_f32_e32 v201, v133, v141
	s_waitcnt lgkmcnt(2)
	v_add_f32_e32 v199, v134, v142
	s_waitcnt lgkmcnt(1)
	v_add_f32_e32 v197, v135, v143
	v_lshl_add_u64 v[132:133], s[10:11], 0, v[130:131]
	v_lshl_add_u64 v[134:135], s[16:17], 0, v[130:131]
	v_or_b32_e32 v130, 0x100, v130
	s_waitcnt lgkmcnt(0)
; __device__ __forceinline__ unsigned cvt_pk_bf16(float lo, float hi) { unsigned r; asm volatile("v_cvt_pk_bf16_f32 %0, %1, %2" : "=v"(r) : "v"(lo), "v"(hi)); return r; }
; #define PLE2(kk, A, e0, BW, PW) { const f32x2 t = (f32x2){A[e0], A[e0 + 1]} * c1; f32x2 d; d.x = __builtin_amdgcn_exp2f(t.x); d.y = __builtin_amdgcn_exp2f(t.y); d = d + 1.0f; \
;                     f32x2 q2; q2.x = __builtin_amdgcn_rcpf(d.x); q2.y = __builtin_amdgcn_rcpf(d.y); const f32x2 o2 = (f32x2){bflo(BW), bfhi(BW)} + (f32x2){bflo(PW), bfhi(PW)} * q2; r[kk] = o2.x; r[kk + 1] = o2.y; }
;     __device__ __forceinline__ void operator()(const pg8::f32x4 (&acc)[2][2][4][2], const Unit& u, int wr, int wc, int fr, int fq) const {
;     ...
;                 for (int bj = 0; bj < 2; ++bj) { const size_t o = (size_t)(row0 + ((k + 1) >> 2) * HALF + ((k + 1) & 3) * 16) * DM_ + col0 + bj * HALF; nb[bj] = *(const v4u*)(base + o); np[bj] = *(const v4u*)(pp + o); } }
; #pragma unroll
;             for (int bj = 0; bj < 2; ++bj) { const size_t o = (size_t)row * DM_ + col0 + bj * HALF; const v4u bw = cb[bj], pw = cp[bj];
;                 const float c1 = -1.4426950408889634f * rs; float r[8];
;     ...
;                 { const f32x4 a0 = acc[ai][bj][m][0], a1 = acc[ai][bj][m][1];
;                   PLE2(0, a0, 0, bw.x, pw.x) PLE2(2, a0, 2, bw.y, pw.y) PLE2(4, a1, 0, bw.z, pw.z) PLE2(6, a1, 2, bw.w, pw.w) }
;     ...
; #pragma unroll
;                 for (int e = 0; e < 8; ++e) q += r[e] * r[e];
;                 v4u w; w.x = cvt_pk_bf16(r[0], r[1]); w.y = cvt_pk_bf16(r[2], r[3]); w.z = cvt_pk_bf16(r[4], r[5]); w.w = cvt_pk_bf16(r[6], r[7]); *(v4u*)(out + o) = w; }
;             q += __shfl_xor(q, 16); q += __shfl_xor(q, 32); if (fq == 0) ssq[(size_t)row * 16 + u.pn * 4 + wc] = q; }
	v_add_f32_e32 v193, v137, v145
	global_load_dwordx4 v[142:145], v[132:133], off
	global_load_dwordx4 v[138:141], v[134:135], off
	v_lshl_add_u64 v[132:133], s[10:11], 0, v[130:131]
	v_lshl_add_u64 v[130:131], s[16:17], 0, v[130:131]
	v_mul_f32_e32 v208, 0xbfb8aa3b, v136
	global_load_dwordx4 v[134:137], v[132:133], off
	s_nop 0
	global_load_dwordx4 v[130:133], v[130:131], off
	v_pk_mul_f32 v[128:129], v[128:129], v[208:209] op_sel_hi:[1,0]
	v_pk_mul_f32 v[122:123], v[122:123], v[208:209] op_sel_hi:[1,0]
	v_exp_f32_e32 v128, v128
	v_exp_f32_e32 v129, v129
	v_exp_f32_e32 v122, v122
	v_exp_f32_e32 v123, v123
	v_pk_mul_f32 v[126:127], v[126:127], v[208:209] op_sel_hi:[1,0]
	v_pk_add_f32 v[128:129], v[128:129], 1.0 op_sel_hi:[1,0]
	v_exp_f32_e32 v126, v126
	v_exp_f32_e32 v127, v127
	v_rcp_f32_e32 v128, v128
	v_rcp_f32_e32 v129, v129
	v_pk_add_f32 v[122:123], v[122:123], 1.0 op_sel_hi:[1,0]
	v_pk_mul_f32 v[124:125], v[124:125], v[208:209] op_sel_hi:[1,0]
	v_rcp_f32_e32 v122, v122
	v_rcp_f32_e32 v123, v123
	v_exp_f32_e32 v124, v124
	v_exp_f32_e32 v125, v125
	v_pk_mul_f32 v[118:119], v[118:119], v[208:209] op_sel_hi:[1,0]
	v_pk_mul_f32 v[120:121], v[120:121], v[208:209] op_sel_hi:[1,0]
	v_exp_f32_e32 v118, v118
	v_exp_f32_e32 v119, v119
	v_lshlrev_b32_e32 v228, 16, v210
	v_and_b32_e32 v229, 0xffff0000, v210
	v_lshlrev_b32_e32 v230, 16, v214
	v_and_b32_e32 v231, 0xffff0000, v214
	v_lshlrev_b32_e32 v210, 16, v211
	v_and_b32_e32 v211, 0xffff0000, v211
	v_lshlrev_b32_e32 v214, 16, v215
	v_and_b32_e32 v215, 0xffff0000, v215
	v_exp_f32_e32 v120, v120
	v_exp_f32_e32 v121, v121
	v_pk_mul_f32 v[114:115], v[114:115], v[208:209] op_sel_hi:[1,0]
	v_pk_add_f32 v[126:127], v[126:127], 1.0 op_sel_hi:[1,0]
	v_pk_fma_f32 v[128:129], v[128:129], v[214:215], v[210:211]
	v_lshlrev_b32_e32 v210, 16, v212
	v_and_b32_e32 v211, 0xffff0000, v212
	v_lshlrev_b32_e32 v214, 16, v216
	v_and_b32_e32 v215, 0xffff0000, v216
	v_exp_f32_e32 v114, v114
	v_exp_f32_e32 v115, v115
	v_rcp_f32_e32 v126, v126
	v_rcp_f32_e32 v127, v127
	v_pk_fma_f32 v[210:211], v[122:123], v[214:215], v[210:211]
	v_pk_add_f32 v[122:123], v[124:125], 1.0 op_sel_hi:[1,0]
	v_pk_add_f32 v[118:119], v[118:119], 1.0 op_sel_hi:[1,0]
	v_rcp_f32_e32 v122, v122
	v_rcp_f32_e32 v123, v123
	v_rcp_f32_e32 v118, v118
	v_rcp_f32_e32 v119, v119
	v_pk_add_f32 v[120:121], v[120:121], 1.0 op_sel_hi:[1,0]
	v_pk_add_f32 v[114:115], v[114:115], 1.0 op_sel_hi:[1,0]
	v_rcp_f32_e32 v120, v120
	v_rcp_f32_e32 v121, v121
	v_pk_mul_f32 v[116:117], v[116:117], v[208:209] op_sel_hi:[1,0]
	v_pk_fma_f32 v[126:127], v[126:127], v[230:231], v[228:229]
	v_lshlrev_b32_e32 v124, 16, v213
	v_and_b32_e32 v125, 0xffff0000, v213
	v_lshlrev_b32_e32 v212, 16, v217
	v_and_b32_e32 v213, 0xffff0000, v217
	v_rcp_f32_e32 v114, v114
	v_rcp_f32_e32 v115, v115
	v_exp_f32_e32 v116, v116
	v_exp_f32_e32 v117, v117
	v_pk_fma_f32 v[212:213], v[122:123], v[212:213], v[124:125]
	v_pk_mul_f32 v[214:215], v[126:127], v[126:127]
	v_pk_mul_f32 v[216:217], v[128:129], v[128:129]
	v_cvt_pk_bf16_f32 v122, v126, v127
	v_cvt_pk_bf16_f32 v123, v128, v129
	s_waitcnt vmcnt(5)
	v_lshlrev_b32_e32 v126, 16, v218
	v_and_b32_e32 v127, 0xffff0000, v218
	s_waitcnt vmcnt(4)
	v_lshlrev_b32_e32 v128, 16, v222
	v_and_b32_e32 v129, 0xffff0000, v222
	v_pk_fma_f32 v[118:119], v[118:119], v[128:129], v[126:127]
	v_lshlrev_b32_e32 v126, 16, v219
	v_and_b32_e32 v127, 0xffff0000, v219
	v_lshlrev_b32_e32 v128, 16, v223
	v_and_b32_e32 v129, 0xffff0000, v223
	v_pk_fma_f32 v[120:121], v[120:121], v[128:129], v[126:127]
	v_lshlrev_b32_e32 v126, 16, v220
	v_and_b32_e32 v127, 0xffff0000, v220
	v_lshlrev_b32_e32 v128, 16, v224
	v_and_b32_e32 v129, 0xffff0000, v224
	v_add_f32_e32 v207, v214, v215
	v_pk_fma_f32 v[126:127], v[114:115], v[128:129], v[126:127]
	v_pk_add_f32 v[114:115], v[116:117], 1.0 op_sel_hi:[1,0]
	v_add_f32_e32 v207, v216, v207
	v_pk_mul_f32 v[228:229], v[210:211], v[210:211]
	v_rcp_f32_e32 v114, v114
	v_rcp_f32_e32 v115, v115
	v_add_f32_e32 v207, v217, v207
	v_add_f32_e32 v207, v228, v207
	v_pk_mul_f32 v[230:231], v[212:213], v[212:213]
	v_add_f32_e32 v207, v229, v207
	v_lshlrev_b32_e32 v116, 16, v221
	v_and_b32_e32 v117, 0xffff0000, v221
	v_lshlrev_b32_e32 v128, 16, v225
	v_and_b32_e32 v129, 0xffff0000, v225
	v_add_f32_e32 v207, v230, v207
	v_pk_fma_f32 v[128:129], v[114:115], v[128:129], v[116:117]
	v_pk_mul_f32 v[114:115], v[118:119], v[118:119]
	v_add_f32_e32 v207, v231, v207
	v_add_f32_e32 v114, v114, v207
	v_pk_mul_f32 v[116:117], v[120:121], v[120:121]
	v_add_f32_e32 v114, v115, v114
	v_add_f32_e32 v114, v116, v114
	v_pk_mul_f32 v[208:209], v[126:127], v[126:127]
	v_add_f32_e32 v114, v117, v114
	v_add_f32_e32 v114, v208, v114
	v_cvt_pk_bf16_f32 v124, v210, v211
	v_pk_mul_f32 v[210:211], v[128:129], v[128:129]
	v_add_f32_e32 v114, v209, v114
	v_add_f32_e32 v114, v210, v114
	v_add_f32_e32 v117, v211, v114
	v_mov_b32_e32 v207, v117
	s_nop 1
	v_permlane16_swap_b32 v117, v207
	v_lshl_add_u64 v[114:115], s[18:19], 0, v[226:227]
	v_lshl_add_u64 v[208:209], v[164:165], 1, v[114:115]
	v_mov_b32_e32 v206, v205
	s_nop 1
	v_permlane32_swap_b32 v205, v206
	v_mov_b32_e32 v204, v203
	s_nop 1
	v_permlane32_swap_b32 v203, v204
	s_waitcnt lgkmcnt(2)
	v_add_f32_e32 v114, v117, v207
	v_mov_b32_e32 v202, v201
	s_nop 1
	v_permlane32_swap_b32 v201, v202
	v_mov_b32_e32 v200, v199
	s_nop 1
	v_permlane32_swap_b32 v199, v200
	v_mov_b32_e32 v198, v197
	s_nop 1
	v_permlane32_swap_b32 v197, v198
	v_mov_b32_e32 v196, v195
	s_nop 1
	v_permlane32_swap_b32 v195, v196
	v_mov_b32_e32 v194, v193
	s_nop 1
	v_permlane32_swap_b32 v193, v194
	v_mov_b32_e32 v115, v114
	s_nop 1
	v_permlane32_swap_b32 v114, v115
	v_cvt_pk_bf16_f32 v125, v212, v213
	global_store_dwordx4 v[208:209], v[122:125], off
	v_cvt_pk_bf16_f32 v116, v118, v119
	v_cvt_pk_bf16_f32 v117, v120, v121
	v_cvt_pk_bf16_f32 v118, v126, v127
	v_cvt_pk_bf16_f32 v119, v128, v129
	global_store_dwordx4 v[208:209], v[116:119], off offset:256
	s_and_saveexec_b64 s[36:37], s[6:7]
	s_cbranch_execz .LBB0_908
	v_lshl_add_u64 v[116:117], s[20:21], 0, v[182:183]
	v_lshl_add_u64 v[116:117], s[4:5], 2, v[116:117]
	s_lshl_b32 s12, s49, 2
	v_lshl_add_u64 v[116:117], v[116:117], 0, s[12:13]
	s_waitcnt lgkmcnt(0)
	v_add_f32_e32 v114, v114, v115
	global_store_dword v[116:117], v114, off

; __device__ __forceinline__ void rstd8(const float* ss, int row0, int fq, float (&rs)[8]) {
;     f32x4 a[8];
; #pragma unroll
;     for (int k = 0; k < 8; ++k) a[k] = *(const f32x4*)(ss + (size_t)(row0 + (k >> 2) * 128 + (k & 3) * 16) * 16 + 4 * fq);
; #pragma unroll
;     for (int k = 0; k < 8; ++k) { float s = (a[k][0] + a[k][1]) + (a[k][2] + a[k][3]); s += __shfl_xor(s, 16); s += __shfl_xor(s, 32); rs[k] = __builtin_amdgcn_rsqf(s * (1.f / 1024.f) + EPS); }
;     __device__ __forceinline__ void operator()(const pg8::f32x4 (&acc)[2][2][4][2], const Unit& u, int wr, int wc, int fr, int fq) const {
;         const int pn = u.pn; const int row0 = u.pm * BM + wr * 64 + fr; const int sp = pn / tps, pt = pn - sp * tps; bf16* const Ob = O + (size_t)sp * sstride;
;         float rsv[8]; rstd8(ss, row0, fq, rsv);
;         if (pn < rope_tiles) {
;             const float s_ = (pn >= sc_lo && pn < sc_hi) ? sc : 1.f;
;             const int i0 = 16 * (wc & 1) + 4 * fq;
;             f32x4 cN = *(const f32x4*)(cs + (row0 & (SEQL - 1)) * 64 + i0), sN = *(const f32x4*)(cs + (row0 & (SEQL - 1)) * 64 + 32 + i0);
; #pragma unroll
;             for (int k = 0; k < 8; ++k) { const int ai = k >> 2, m = k & 3; const int row = row0 + ai * HALF + m * 16; const float s = s_ * rsv[k];
;                 const f32x4 c = cN, sn = sN;
;                 if (k < 7) { const int rown = row0 + ((k + 1) >> 2) * HALF + ((k + 1) & 3) * 16, posn = rown & (SEQL - 1); cN = *(const f32x4*)(cs + posn * 64 + i0); sN = *(const f32x4*)(cs + posn * 64 + 32 + i0); }
.LBB0_992:
	s_lshl_b32 s1, s4, 8
	s_add_i32 s1, s1, s46
	v_or_b32_e32 v174, s1, v1
	v_or_b32_e32 v168, 16, v174
	v_ashrrev_i32_e32 v175, 31, v174
	v_ashrrev_i32_e32 v169, 31, v168
	v_lshlrev_b64 v[154:155], 6, v[174:175]
	v_lshlrev_b64 v[164:165], 6, v[168:169]
	v_or_b32_e32 v210, 32, v174
	v_lshl_add_u64 v[154:155], v[142:143], 0, v[154:155]
	v_lshl_add_u64 v[176:177], v[142:143], 0, v[164:165]
	v_ashrrev_i32_e32 v211, 31, v210
	v_or_b32_e32 v212, 48, v174
	global_load_dwordx4 v[164:167], v[154:155], off
	s_nop 0
	global_load_dwordx4 v[176:179], v[176:177], off
	v_lshlrev_b64 v[154:155], 6, v[210:211]
	v_ashrrev_i32_e32 v213, 31, v212
	v_lshl_add_u64 v[154:155], v[142:143], 0, v[154:155]
	v_lshlrev_b64 v[180:181], 6, v[212:213]
	v_lshl_add_u64 v[184:185], v[142:143], 0, v[180:181]
	global_load_dwordx4 v[180:183], v[154:155], off
	global_load_dwordx4 v[190:193], v[184:185], off
	v_add_u32_e32 v154, 0x80, v174
	v_ashrrev_i32_e32 v155, 31, v154
	v_lshlrev_b64 v[184:185], 6, v[154:155]
	v_lshl_add_u64 v[184:185], v[142:143], 0, v[184:185]
	global_load_dwordx4 v[194:197], v[184:185], off
	v_add_u32_e32 v186, 0xa0, v174
	v_ashrrev_i32_e32 v187, 31, v186
	v_add_u32_e32 v188, 0x90, v174
	v_lshlrev_b64 v[202:203], 6, v[186:187]
	v_ashrrev_i32_e32 v189, 31, v188
	v_lshl_add_u64 v[202:203], v[142:143], 0, v[202:203]
	global_load_dwordx4 v[202:205], v[202:203], off
	v_lshlrev_b64 v[184:185], 6, v[188:189]
	v_lshl_add_u64 v[184:185], v[142:143], 0, v[184:185]
	global_load_dwordx4 v[198:201], v[184:185], off
	v_add_u32_e32 v184, 0xb0, v174
	v_ashrrev_i32_e32 v185, 31, v184
	v_lshlrev_b64 v[206:207], 6, v[184:185]
	v_lshl_add_u64 v[206:207], v[142:143], 0, v[206:207]
	global_load_dwordx4 v[206:209], v[206:207], off
	v_and_b32_e32 v153, 64, v163
	v_xor_b32_e32 v138, 16, v163
	v_add_u32_e32 v153, 64, v153
	v_xor_b32_e32 v156, 32, v163
	v_cmp_lt_i32_e32 vcc, v138, v153
	s_ashr_i32 s1, s0, 31
	s_lshr_b32 s1, s1, 30
	v_cndmask_b32_e32 v138, v163, v138, vcc
	v_cmp_lt_i32_e32 vcc, v156, v153
	v_lshlrev_b32_e32 v138, 2, v138
	s_add_i32 s1, s0, s1
	v_cndmask_b32_e32 v153, v163, v156, vcc
	v_lshlrev_b32_e32 v153, 2, v153
	s_ashr_i32 s4, s1, 2
	s_and_b32 s1, s1, -4
	s_ashr_i32 s5, s4, 31
	s_sub_i32 s19, s0, s1
	s_lshl_b64 s[4:5], s[4:5], 26
	s_add_u32 s17, s44, s4
	s_addc_u32 s1, s45, s5
	s_mov_b64 s[4:5], -1
	s_and_b64 s[98:99], exec, s[14:15]
	s_cbranch_scc0 .Lal_7
	s_barrier
.Lal_7:
	s_cmp_gt_i32 s0, 7
	s_waitcnt vmcnt(0)
	v_add_f32_e32 v156, v164, v165
	v_add_f32_e32 v158, v166, v167
	v_add_f32_e32 v156, v156, v158
	v_add_f32_e32 v158, v176, v177
	v_add_f32_e32 v160, v178, v179
	v_mov_b32_e32 v172, v156
	s_nop 1
	v_permlane16_swap_b32 v156, v172
	v_add_f32_e32 v162, v180, v181
	v_add_f32_e32 v164, v182, v183
	v_add_f32_e32 v165, v190, v191
	v_add_f32_e32 v166, v192, v193
	v_add_f32_e32 v158, v158, v160
	v_add_f32_e32 v160, v162, v164
	v_add_f32_e32 v162, v165, v166
	v_mov_b32_e32 v165, v158
	s_nop 1
	v_permlane16_swap_b32 v158, v165
	v_mov_b32_e32 v166, v160
	s_nop 1
	v_permlane16_swap_b32 v160, v166
	s_waitcnt lgkmcnt(2)
	v_add_f32_e32 v156, v156, v172
	v_add_f32_e32 v167, v194, v195
	v_add_f32_e32 v170, v196, v197
	v_mov_b32_e32 v172, v156
	s_nop 1
	v_permlane32_swap_b32 v156, v172
	s_waitcnt lgkmcnt(2)
	v_add_f32_e32 v158, v158, v165
	s_waitcnt lgkmcnt(1)
	v_add_f32_e32 v160, v160, v166
	v_add_f32_e32 v164, v167, v170
	v_mov_b32_e32 v167, v162
	s_nop 1
	v_permlane16_swap_b32 v162, v167
	v_mov_b32_e32 v165, v158
	s_nop 1
	v_permlane32_swap_b32 v158, v165
	v_mov_b32_e32 v166, v160
	s_nop 1
	v_permlane32_swap_b32 v160, v166
	v_mov_b32_e32 v170, v164
	s_nop 1
	v_permlane16_swap_b32 v164, v170
	s_waitcnt lgkmcnt(4)
	v_add_f32_e32 v156, v156, v172
	s_waitcnt lgkmcnt(3)
	v_add_f32_e32 v162, v162, v167
	v_fmamk_f32 v156, v156, 0x3a800000, v171
	s_waitcnt lgkmcnt(2)
	v_add_f32_e32 v158, v158, v165
	s_waitcnt lgkmcnt(1)
	v_add_f32_e32 v160, v160, v166
	v_mov_b32_e32 v167, v162
	s_nop 1
	v_permlane32_swap_b32 v162, v167
	v_rsq_f32_e32 v182, v156
	v_fmamk_f32 v156, v158, 0x3a800000, v171
	v_fmamk_f32 v158, v160, 0x3a800000, v171
	s_waitcnt lgkmcnt(1)
	v_add_f32_e32 v164, v164, v170
	v_rsq_f32_e32 v180, v156
	v_rsq_f32_e32 v170, v158
	v_add_f32_e32 v156, v198, v199
	v_add_f32_e32 v158, v200, v201
	v_mov_b32_e32 v176, v164
	s_nop 1
	v_permlane32_swap_b32 v164, v176
	v_add_f32_e32 v156, v156, v158
	v_mov_b32_e32 v158, v156
	s_nop 1
	v_permlane16_swap_b32 v156, v158
	s_waitcnt lgkmcnt(2)
	v_add_f32_e32 v162, v162, v167
	v_fmamk_f32 v160, v162, 0x3a800000, v171
	v_rsq_f32_e32 v172, v160
	s_waitcnt lgkmcnt(1)
	v_add_f32_e32 v160, v164, v176
	v_add_f32_e32 v162, v202, v203
	v_add_f32_e32 v164, v204, v205
	v_add_f32_e32 v165, v206, v207
	v_add_f32_e32 v166, v208, v209
	s_waitcnt lgkmcnt(0)
	v_add_f32_e32 v156, v156, v158
	v_add_f32_e32 v162, v162, v164
	v_add_f32_e32 v165, v165, v166
	v_mov_b32_e32 v158, v156
	s_nop 1
	v_permlane32_swap_b32 v156, v158
	v_mov_b32_e32 v164, v162
	s_nop 1
	v_permlane16_swap_b32 v162, v164
	v_mov_b32_e32 v138, v165
	s_nop 1
	v_permlane16_swap_b32 v165, v138
	v_fmamk_f32 v160, v160, 0x3a800000, v171
	v_rsq_f32_e32 v160, v160
	s_waitcnt lgkmcnt(2)
	v_add_f32_e32 v156, v156, v158
	s_waitcnt lgkmcnt(1)
	v_add_f32_e32 v158, v162, v164
	s_waitcnt lgkmcnt(0)
	v_add_f32_e32 v138, v165, v138
	v_mov_b32_e32 v164, v158
	s_nop 1
	v_permlane32_swap_b32 v158, v164
	v_mov_b32_e32 v153, v138
	s_nop 1
	v_permlane32_swap_b32 v138, v153
	v_fmamk_f32 v156, v156, 0x3a800000, v171
	v_rsq_f32_e32 v162, v156
	v_lshlrev_b64 v[176:177], 11, v[174:175]
	s_waitcnt lgkmcnt(1)
	v_add_f32_e32 v156, v158, v164
	s_waitcnt lgkmcnt(0)
	v_add_f32_e32 v138, v138, v153
	v_fmamk_f32 v156, v156, 0x3a800000, v171
	v_fmamk_f32 v138, v138, 0x3a800000, v171
	v_rsq_f32_e32 v156, v156
	v_rsq_f32_e32 v158, v138
	v_lshlrev_b64 v[178:179], 11, v[168:169]
	v_lshlrev_b64 v[166:167], 11, v[210:211]
	v_lshlrev_b64 v[168:169], 11, v[212:213]
	v_lshlrev_b64 v[164:165], 11, v[154:155]
	s_cbranch_scc1 .LBB0_995
	s_andn2_b64 vcc, exec, s[4:5]
	s_cbranch_vccz .LBB0_996

; __device__ __forceinline__ unsigned cvt_pk_bf16(float lo, float hi) { unsigned r; asm volatile("v_cvt_pk_bf16_f32 %0, %1, %2" : "=v"(r) : "v"(lo), "v"(hi)); return r; }
; __device__ __forceinline__ float bflo(unsigned w) { return __uint_as_float(w << 16); }
; __device__ __forceinline__ float bfhi(unsigned w) { return __uint_as_float(w & 0xffff0000u); }
;     __device__ __forceinline__ void ld(Ld& L, size_t o) const {
; #pragma unroll
;         for (int bj = 0; bj < 2; ++bj) { if (BASEF32) { L.a[bj][0] = *(const f32x4*)((const float*)base + o + bj * HALF); L.a[bj][1] = *(const f32x4*)((const float*)base + o + bj * HALF + 4); }
;             else { const v4u w = *(const v4u*)((const bf16*)base + o + bj * HALF); L.a[bj][0] = __builtin_bit_cast(f32x4, w); } }
;     }
;     __device__ __forceinline__ void operator()(const pg8::f32x4 (&acc)[2][2][4][2], const Unit& u, int wr, int wc, int fr, int fq) const {
;         const int row0 = u.pm * BM + wr * 64 + fr, col0 = u.pn * BM + wc * 32 + 8 * fq;
;         Ld nx; ld(nx, (size_t)row0 * DM_ + col0);
; #pragma unroll
;         for (int k = 0; k < 8; ++k) { const int ai = k >> 2, m = k & 3; const int row = row0 + ai * HALF + m * 16; float q = 0.f; const Ld cu = nx;
;             if (k < 7) ld(nx, (size_t)(row0 + ((k + 1) >> 2) * HALF + ((k + 1) & 3) * 16) * DM_ + col0);
; #pragma unroll
;             for (int bj = 0; bj < 2; ++bj) { const size_t o = (size_t)row * DM_ + col0 + bj * HALF; f32x4 b0, b1;
;                 if (BASEF32) { b0 = cu.a[bj][0]; b1 = cu.a[bj][1]; }
;                 else { const v4u w = __builtin_bit_cast(v4u, cu.a[bj][0]); b0 = (f32x4){bflo(w.x), bfhi(w.x), bflo(w.y), bfhi(w.y)}; b1 = (f32x4){bflo(w.z), bfhi(w.z), bflo(w.w), bfhi(w.w)}; }
;                 const f32x4 r0 = b0 + acc[ai][bj][m][0], r1 = b1 + acc[ai][bj][m][1];
;                 q += (r0[0] * r0[0] + r0[1] * r0[1]) + (r0[2] * r0[2] + r0[3] * r0[3]) + (r1[0] * r1[0] + r1[1] * r1[1]) + (r1[2] * r1[2] + r1[3] * r1[3]);
;                 v4u w; w.x = cvt_pk_bf16(r0[0], r0[1]); w.y = cvt_pk_bf16(r0[2], r0[3]); w.z = cvt_pk_bf16(r1[0], r1[1]); w.w = cvt_pk_bf16(r1[2], r1[3]); *(v4u*)(out + o) = w; }
;             q += __shfl_xor(q, 16); q += __shfl_xor(q, 32); if (fq == 0) ssq[(size_t)row * 16 + u.pn * 4 + wc] = q; }
.LBB0_1470:
	v_lshl_add_u32 v156, s28, 8, v1
	v_lshl_or_b32 v154, s4, 8, v163
	v_ashrrev_i32_e32 v157, 31, v156
	v_ashrrev_i32_e32 v155, 31, v154
	v_lshlrev_b64 v[130:131], 11, v[156:157]
	v_lshl_add_u64 v[130:131], s[12:13], 0, v[130:131]
	v_lshlrev_b64 v[132:133], 1, v[154:155]
	v_lshl_add_u64 v[178:179], v[130:131], 0, v[132:133]
	global_load_dwordx4 v[170:173], v[178:179], off
	global_load_dwordx4 v[174:177], v[178:179], off offset:256
	v_or_b32_e32 v158, 16, v156
	v_ashrrev_i32_e32 v159, 31, v158
	v_lshlrev_b64 v[130:131], 11, v[158:159]
	v_lshl_add_u64 v[130:131], s[12:13], 0, v[130:131]
	v_lshl_add_u64 v[160:161], v[130:131], 0, v[132:133]
	global_load_dwordx4 v[134:137], v[160:161], off
	global_load_dwordx4 v[130:133], v[160:161], off offset:256
	v_and_b32_e32 v169, 64, v167
	v_xor_b32_e32 v168, 16, v167
	v_add_u32_e32 v169, 64, v169
	v_xor_b32_e32 v180, 32, v167
	v_cmp_lt_i32_e32 vcc, v168, v169
	s_lshl_b32 s28, s4, 2
	s_ashr_i32 s29, s28, 31
	v_cndmask_b32_e32 v168, v167, v168, vcc
	v_cmp_lt_i32_e32 vcc, v180, v169
	v_lshlrev_b32_e32 v168, 2, v168
	s_and_b64 s[98:99], exec, s[18:19]
	s_cbranch_scc0 .Lal_8
	s_barrier
.Lal_8:
	s_waitcnt vmcnt(0)
	v_and_b32_e32 v181, 0xffff0000, v170
	v_cndmask_b32_e32 v169, v167, v180, vcc
	v_lshlrev_b32_e32 v180, 16, v170
	v_lshlrev_b32_e32 v170, 16, v171
	v_and_b32_e32 v171, 0xffff0000, v171
	v_lshlrev_b32_e32 v184, 16, v174
	v_and_b32_e32 v185, 0xffff0000, v174
	v_lshlrev_b32_e32 v174, 16, v175
	v_and_b32_e32 v175, 0xffff0000, v175
	v_lshlrev_b32_e32 v182, 16, v172
	v_and_b32_e32 v183, 0xffff0000, v172
	v_lshlrev_b32_e32 v172, 16, v173
	v_and_b32_e32 v173, 0xffff0000, v173
	v_lshlrev_b32_e32 v186, 16, v176
	v_and_b32_e32 v187, 0xffff0000, v176
	v_lshlrev_b32_e32 v176, 16, v177
	v_and_b32_e32 v177, 0xffff0000, v177
	v_pk_add_f32 v[128:129], v[128:129], v[170:171]
	v_pk_add_f32 v[126:127], v[126:127], v[180:181]
	v_pk_add_f32 v[120:121], v[120:121], v[174:175]
	v_pk_add_f32 v[118:119], v[118:119], v[184:185]
	v_pk_add_f32 v[124:125], v[124:125], v[172:173]
	v_pk_add_f32 v[122:123], v[122:123], v[182:183]
	v_pk_add_f32 v[170:171], v[116:117], v[176:177]
	v_pk_add_f32 v[172:173], v[114:115], v[186:187]
	v_mul_f32_e32 v116, v127, v127
	v_mul_f32_e32 v117, v129, v129
	v_cvt_pk_bf16_f32 v114, v126, v127
	v_cvt_pk_bf16_f32 v115, v128, v129
	v_mul_f32_e32 v127, v119, v119
	v_mul_f32_e32 v129, v121, v121
	v_mul_f32_e32 v174, v123, v123
	v_mul_f32_e32 v176, v173, v173
	v_fmac_f32_e32 v116, v126, v126
	v_fmac_f32_e32 v117, v128, v128
	v_fmac_f32_e32 v127, v118, v118
	v_fmac_f32_e32 v129, v120, v120
	v_mul_f32_e32 v175, v125, v125
	v_mul_f32_e32 v177, v171, v171
	v_fmac_f32_e32 v174, v122, v122
	v_fmac_f32_e32 v176, v172, v172
	v_add_f32_e32 v116, v116, v117
	v_add_f32_e32 v117, v127, v129
	v_fmac_f32_e32 v175, v124, v124
	v_fmac_f32_e32 v177, v170, v170
	v_add_f32_e32 v116, v174, v116
	v_add_f32_e32 v117, v176, v117
	v_add_f32_e32 v116, v175, v116
	v_add_f32_e32 v117, v177, v117
	v_add_f32_e32 v126, v116, v117
	v_mov_b32_e32 v127, v126
	s_nop 1
	v_permlane16_swap_b32 v126, v127
	v_cvt_pk_bf16_f32 v116, v122, v123
	v_cvt_pk_bf16_f32 v117, v124, v125
	global_store_dwordx4 v[178:179], v[114:117], off
	s_waitcnt lgkmcnt(0)
	s_nop 0
	v_add_f32_e32 v114, v126, v127
	v_lshlrev_b32_e32 v126, 2, v169
	v_mov_b32_e32 v115, v114
	s_nop 1
	v_permlane32_swap_b32 v114, v115
	v_cvt_pk_bf16_f32 v116, v118, v119
	v_cvt_pk_bf16_f32 v117, v120, v121
	v_cvt_pk_bf16_f32 v118, v172, v173
	v_cvt_pk_bf16_f32 v119, v170, v171
	global_store_dwordx4 v[178:179], v[116:119], off offset:256
	s_and_saveexec_b64 s[30:31], s[6:7]
	s_cbranch_execz .LBB0_1472
	v_lshlrev_b64 v[116:117], 6, v[156:157]
	v_lshl_add_u64 v[116:117], s[14:15], 0, v[116:117]
	v_lshl_add_u64 v[116:117], s[28:29], 2, v[116:117]
	s_lshl_b32 s4, s42, 2
	v_lshl_add_u64 v[116:117], v[116:117], 0, s[4:5]
	s_waitcnt lgkmcnt(0)
	v_add_f32_e32 v114, v114, v115
	global_store_dword v[116:117], v114, off

; __device__ __forceinline__ unsigned cvt_pk_bf16(float lo, float hi) { unsigned r; asm volatile("v_cvt_pk_bf16_f32 %0, %1, %2" : "=v"(r) : "v"(lo), "v"(hi)); return r; }
; __device__ __forceinline__ void rstd8(const float* ss, int row0, int fq, float (&rs)[8]) {
;     f32x4 a[8];
; #pragma unroll
;     for (int k = 0; k < 8; ++k) a[k] = *(const f32x4*)(ss + (size_t)(row0 + (k >> 2) * 128 + (k & 3) * 16) * 16 + 4 * fq);
; #pragma unroll
;     for (int k = 0; k < 8; ++k) { float s = (a[k][0] + a[k][1]) + (a[k][2] + a[k][3]); s += __shfl_xor(s, 16); s += __shfl_xor(s, 32); rs[k] = __builtin_amdgcn_rsqf(s * (1.f / 1024.f) + EPS); }
;     __device__ __forceinline__ void operator()(const pg8::f32x4 (&acc)[2][2][4][2], const Unit& u, int wr, int wc, int fr, int fq) const {
;     ...
;         for (int k = 0; k < 8; ++k) { const int ai = k >> 2, m = k & 3; const int row = row0 + ai * HALF + m * 16; const float rs = rsv[k]; float q = 0.f;
;             v4u cb[2], cp[2];
; #pragma unroll
;             for (int bj = 0; bj < 2; ++bj) { cb[bj] = nb[bj]; cp[bj] = np[bj]; }
;             if (k < 7) {
; #pragma unroll
;                 for (int bj = 0; bj < 2; ++bj) { const size_t o = (size_t)(row0 + ((k + 1) >> 2) * HALF + ((k + 1) & 3) * 16) * DM_ + col0 + bj * HALF; nb[bj] = *(const v4u*)(base + o); np[bj] = *(const v4u*)(pp + o); } }
; #pragma unroll
;             for (int bj = 0; bj < 2; ++bj) { const size_t o = (size_t)row * DM_ + col0 + bj * HALF; const v4u bw = cb[bj], pw = cp[bj];
;                 const float c1 = -1.4426950408889634f * rs; float r[8];
;     ...
;                 { const f32x4 a0 = acc[ai][bj][m][0], a1 = acc[ai][bj][m][1];
;                   PLE2(0, a0, 0, bw.x, pw.x) PLE2(2, a0, 2, bw.y, pw.y) PLE2(4, a1, 0, bw.z, pw.z) PLE2(6, a1, 2, bw.w, pw.w) }
;     ...
; #pragma unroll
;                 for (int e = 0; e < 8; ++e) q += r[e] * r[e];
;                 v4u w; w.x = cvt_pk_bf16(r[0], r[1]); w.y = cvt_pk_bf16(r[2], r[3]); w.z = cvt_pk_bf16(r[4], r[5]); w.w = cvt_pk_bf16(r[6], r[7]); *(v4u*)(out + o) = w; }
;             q += __shfl_xor(q, 16); q += __shfl_xor(q, 32); if (fq == 0) ssq[(size_t)row * 16 + u.pn * 4 + wc] = q; }
.Lal_11:
	s_waitcnt vmcnt(0)
	v_mov_b32_e32 v218, v131
	v_mov_b32_e32 v219, v132
	v_mov_b32_e32 v131, v133
	v_pk_add_f32 v[130:131], v[218:219], v[130:131]
	v_add_f32_e32 v132, v134, v135
	v_add_f32_e32 v133, v136, v137
	v_add_f32_e32 v134, v138, v139
	v_add_f32_e32 v135, v140, v141
	v_add_f32_e32 v138, v194, v195
	v_add_f32_e32 v139, v196, v197
	v_add_f32_e32 v130, v130, v131
	v_add_f32_e32 v131, v132, v133
	v_add_f32_e32 v132, v134, v135
	v_add_f32_e32 v134, v138, v139
	v_mov_b32_e32 v138, v130
	s_nop 1
	v_permlane16_swap_b32 v130, v138
	v_mov_b32_e32 v139, v131
	s_nop 1
	v_permlane16_swap_b32 v131, v139
	v_add_f32_e32 v136, v142, v143
	v_add_f32_e32 v137, v144, v145
	v_add_f32_e32 v142, v202, v203
	s_waitcnt lgkmcnt(1)
	v_add_f32_e32 v130, v130, v138
	v_add_f32_e32 v143, v204, v205
	s_waitcnt lgkmcnt(0)
	v_add_f32_e32 v205, v131, v139
	v_mov_b32_e32 v131, v130
	s_nop 1
	v_permlane32_swap_b32 v130, v131
	v_add_f32_e32 v144, v206, v207
	v_add_f32_e32 v145, v208, v209
	v_add_f32_e32 v133, v136, v137
	v_add_f32_e32 v136, v142, v143
	v_add_f32_e32 v137, v144, v145
	v_mov_b32_e32 v144, v136
	s_nop 1
	v_permlane16_swap_b32 v136, v144
	s_waitcnt lgkmcnt(1)
	v_add_f32_e32 v130, v130, v131
	v_fmamk_f32 v130, v130, 0x3a800000, v190
	v_add_f32_e32 v140, v198, v199
	v_add_f32_e32 v141, v200, v201
	s_waitcnt lgkmcnt(0)
	v_add_f32_e32 v195, v136, v144
	v_rsq_f32_e32 v136, v130
	v_lshl_add_u64 v[130:131], s[10:11], 0, v[222:223]
	global_load_dwordx4 v[218:221], v[130:131], off
	v_lshl_add_u64 v[130:131], s[16:17], 0, v[222:223]
	global_load_dwordx4 v[222:225], v[130:131], off
	v_add_f32_e32 v135, v140, v141
	v_mov_b32_e32 v140, v132
	s_nop 1
	v_permlane16_swap_b32 v132, v140
	v_mov_b32_e32 v141, v133
	s_nop 1
	v_permlane16_swap_b32 v133, v141
	v_mov_b32_e32 v142, v134
	s_nop 1
	v_permlane16_swap_b32 v134, v142
	v_mov_b32_e32 v143, v135
	s_nop 1
	v_permlane16_swap_b32 v135, v143
	v_mov_b32_e32 v145, v137
	s_nop 1
	v_permlane16_swap_b32 v137, v145
	v_lshlrev_b64 v[130:131], 10, v[180:181]
	v_lshl_add_u64 v[130:131], v[130:131], 0, v[164:165]
	v_lshlrev_b64 v[130:131], 1, v[130:131]
	s_waitcnt lgkmcnt(4)
	v_add_f32_e32 v203, v132, v140
	s_waitcnt lgkmcnt(3)
	v_add_f32_e32 v201, v133, v141
	s_waitcnt lgkmcnt(2)
	v_add_f32_e32 v199, v134, v142
	s_waitcnt lgkmcnt(1)
	v_add_f32_e32 v197, v135, v143
	v_lshl_add_u64 v[132:133], s[10:11], 0, v[130:131]
	v_lshl_add_u64 v[134:135], s[16:17], 0, v[130:131]
	v_or_b32_e32 v130, 0x100, v130
	s_waitcnt lgkmcnt(0)
	v_add_f32_e32 v193, v137, v145
	global_load_dwordx4 v[142:145], v[132:133], off
	global_load_dwordx4 v[138:141], v[134:135], off
	v_lshl_add_u64 v[132:133], s[10:11], 0, v[130:131]
	v_lshl_add_u64 v[130:131], s[16:17], 0, v[130:131]
	v_mul_f32_e32 v208, 0xbfb8aa3b, v136
	global_load_dwordx4 v[134:137], v[132:133], off
	s_nop 0
	global_load_dwordx4 v[130:133], v[130:131], off
	v_pk_mul_f32 v[128:129], v[128:129], v[208:209] op_sel_hi:[1,0]
	v_pk_mul_f32 v[122:123], v[122:123], v[208:209] op_sel_hi:[1,0]
	v_exp_f32_e32 v128, v128
	v_exp_f32_e32 v129, v129
	v_exp_f32_e32 v122, v122
	v_exp_f32_e32 v123, v123
	v_pk_mul_f32 v[126:127], v[126:127], v[208:209] op_sel_hi:[1,0]
	v_pk_add_f32 v[128:129], v[128:129], 1.0 op_sel_hi:[1,0]
	v_exp_f32_e32 v126, v126
	v_exp_f32_e32 v127, v127
	v_rcp_f32_e32 v128, v128
	v_rcp_f32_e32 v129, v129
	v_pk_add_f32 v[122:123], v[122:123], 1.0 op_sel_hi:[1,0]
	v_pk_mul_f32 v[124:125], v[124:125], v[208:209] op_sel_hi:[1,0]
	v_rcp_f32_e32 v122, v122
	v_rcp_f32_e32 v123, v123
	v_exp_f32_e32 v124, v124
	v_exp_f32_e32 v125, v125
	v_pk_mul_f32 v[118:119], v[118:119], v[208:209] op_sel_hi:[1,0]
	v_pk_mul_f32 v[120:121], v[120:121], v[208:209] op_sel_hi:[1,0]
	v_exp_f32_e32 v118, v118
	v_exp_f32_e32 v119, v119
	v_lshlrev_b32_e32 v228, 16, v210
	v_and_b32_e32 v229, 0xffff0000, v210
	v_lshlrev_b32_e32 v230, 16, v214
	v_and_b32_e32 v231, 0xffff0000, v214
	v_lshlrev_b32_e32 v210, 16, v211
	v_and_b32_e32 v211, 0xffff0000, v211
	v_lshlrev_b32_e32 v214, 16, v215
	v_and_b32_e32 v215, 0xffff0000, v215
	v_exp_f32_e32 v120, v120
	v_exp_f32_e32 v121, v121
	v_pk_mul_f32 v[114:115], v[114:115], v[208:209] op_sel_hi:[1,0]
	v_pk_add_f32 v[126:127], v[126:127], 1.0 op_sel_hi:[1,0]
	v_pk_fma_f32 v[128:129], v[128:129], v[214:215], v[210:211]
	v_lshlrev_b32_e32 v210, 16, v212
	v_and_b32_e32 v211, 0xffff0000, v212
	v_lshlrev_b32_e32 v214, 16, v216
	v_and_b32_e32 v215, 0xffff0000, v216
	v_exp_f32_e32 v114, v114
	v_exp_f32_e32 v115, v115
	v_rcp_f32_e32 v126, v126
	v_rcp_f32_e32 v127, v127
	v_pk_fma_f32 v[210:211], v[122:123], v[214:215], v[210:211]
	v_pk_add_f32 v[122:123], v[124:125], 1.0 op_sel_hi:[1,0]
	v_pk_add_f32 v[118:119], v[118:119], 1.0 op_sel_hi:[1,0]
	v_rcp_f32_e32 v122, v122
	v_rcp_f32_e32 v123, v123
	v_rcp_f32_e32 v118, v118
	v_rcp_f32_e32 v119, v119
	v_pk_add_f32 v[120:121], v[120:121], 1.0 op_sel_hi:[1,0]
	v_pk_add_f32 v[114:115], v[114:115], 1.0 op_sel_hi:[1,0]
	v_rcp_f32_e32 v120, v120
	v_rcp_f32_e32 v121, v121
	v_pk_mul_f32 v[116:117], v[116:117], v[208:209] op_sel_hi:[1,0]
	v_pk_fma_f32 v[126:127], v[126:127], v[230:231], v[228:229]
	v_lshlrev_b32_e32 v124, 16, v213
	v_and_b32_e32 v125, 0xffff0000, v213
	v_lshlrev_b32_e32 v212, 16, v217
	v_and_b32_e32 v213, 0xffff0000, v217
	v_rcp_f32_e32 v114, v114
	v_rcp_f32_e32 v115, v115
	v_exp_f32_e32 v116, v116
	v_exp_f32_e32 v117, v117
	v_pk_fma_f32 v[212:213], v[122:123], v[212:213], v[124:125]
	v_pk_mul_f32 v[214:215], v[126:127], v[126:127]
	v_pk_mul_f32 v[216:217], v[128:129], v[128:129]
	v_cvt_pk_bf16_f32 v122, v126, v127
	v_cvt_pk_bf16_f32 v123, v128, v129
	s_waitcnt vmcnt(5)
; __device__ __forceinline__ unsigned cvt_pk_bf16(float lo, float hi) { unsigned r; asm volatile("v_cvt_pk_bf16_f32 %0, %1, %2" : "=v"(r) : "v"(lo), "v"(hi)); return r; }
; #define PLE2(kk, A, e0, BW, PW) { const f32x2 t = (f32x2){A[e0], A[e0 + 1]} * c1; f32x2 d; d.x = __builtin_amdgcn_exp2f(t.x); d.y = __builtin_amdgcn_exp2f(t.y); d = d + 1.0f; \
;                     f32x2 q2; q2.x = __builtin_amdgcn_rcpf(d.x); q2.y = __builtin_amdgcn_rcpf(d.y); const f32x2 o2 = (f32x2){bflo(BW), bfhi(BW)} + (f32x2){bflo(PW), bfhi(PW)} * q2; r[kk] = o2.x; r[kk + 1] = o2.y; }
;     __device__ __forceinline__ void operator()(const pg8::f32x4 (&acc)[2][2][4][2], const Unit& u, int wr, int wc, int fr, int fq) const {
;     ...
;             for (int bj = 0; bj < 2; ++bj) { const size_t o = (size_t)row * DM_ + col0 + bj * HALF; const v4u bw = cb[bj], pw = cp[bj];
;                 const float c1 = -1.4426950408889634f * rs; float r[8];
;     ...
;                 { const f32x4 a0 = acc[ai][bj][m][0], a1 = acc[ai][bj][m][1];
;                   PLE2(0, a0, 0, bw.x, pw.x) PLE2(2, a0, 2, bw.y, pw.y) PLE2(4, a1, 0, bw.z, pw.z) PLE2(6, a1, 2, bw.w, pw.w) }
;     ...
; #pragma unroll
;                 for (int e = 0; e < 8; ++e) q += r[e] * r[e];
;                 v4u w; w.x = cvt_pk_bf16(r[0], r[1]); w.y = cvt_pk_bf16(r[2], r[3]); w.z = cvt_pk_bf16(r[4], r[5]); w.w = cvt_pk_bf16(r[6], r[7]); *(v4u*)(out + o) = w; }
;             q += __shfl_xor(q, 16); q += __shfl_xor(q, 32); if (fq == 0) ssq[(size_t)row * 16 + u.pn * 4 + wc] = q; }
	v_lshlrev_b32_e32 v126, 16, v218
	v_and_b32_e32 v127, 0xffff0000, v218
	s_waitcnt vmcnt(4)
	v_lshlrev_b32_e32 v128, 16, v222
	v_and_b32_e32 v129, 0xffff0000, v222
	v_pk_fma_f32 v[118:119], v[118:119], v[128:129], v[126:127]
	v_lshlrev_b32_e32 v126, 16, v219
	v_and_b32_e32 v127, 0xffff0000, v219
	v_lshlrev_b32_e32 v128, 16, v223
	v_and_b32_e32 v129, 0xffff0000, v223
	v_pk_fma_f32 v[120:121], v[120:121], v[128:129], v[126:127]
	v_lshlrev_b32_e32 v126, 16, v220
	v_and_b32_e32 v127, 0xffff0000, v220
	v_lshlrev_b32_e32 v128, 16, v224
	v_and_b32_e32 v129, 0xffff0000, v224
	v_add_f32_e32 v207, v214, v215
	v_pk_fma_f32 v[126:127], v[114:115], v[128:129], v[126:127]
	v_pk_add_f32 v[114:115], v[116:117], 1.0 op_sel_hi:[1,0]
	v_add_f32_e32 v207, v216, v207
	v_pk_mul_f32 v[228:229], v[210:211], v[210:211]
	v_rcp_f32_e32 v114, v114
	v_rcp_f32_e32 v115, v115
	v_add_f32_e32 v207, v217, v207
	v_add_f32_e32 v207, v228, v207
	v_pk_mul_f32 v[230:231], v[212:213], v[212:213]
	v_add_f32_e32 v207, v229, v207
	v_lshlrev_b32_e32 v116, 16, v221
	v_and_b32_e32 v117, 0xffff0000, v221
	v_lshlrev_b32_e32 v128, 16, v225
	v_and_b32_e32 v129, 0xffff0000, v225
	v_add_f32_e32 v207, v230, v207
	v_pk_fma_f32 v[128:129], v[114:115], v[128:129], v[116:117]
	v_pk_mul_f32 v[114:115], v[118:119], v[118:119]
	v_add_f32_e32 v207, v231, v207
	v_add_f32_e32 v114, v114, v207
	v_pk_mul_f32 v[116:117], v[120:121], v[120:121]
	v_add_f32_e32 v114, v115, v114
	v_add_f32_e32 v114, v116, v114
	v_pk_mul_f32 v[208:209], v[126:127], v[126:127]
	v_add_f32_e32 v114, v117, v114
	v_add_f32_e32 v114, v208, v114
	v_cvt_pk_bf16_f32 v124, v210, v211
	v_pk_mul_f32 v[210:211], v[128:129], v[128:129]
	v_add_f32_e32 v114, v209, v114
	v_add_f32_e32 v114, v210, v114
	v_add_f32_e32 v117, v211, v114
	v_mov_b32_e32 v207, v117
	s_nop 1
	v_permlane16_swap_b32 v117, v207
	v_lshl_add_u64 v[114:115], s[20:21], 0, v[226:227]
	v_lshl_add_u64 v[208:209], v[164:165], 1, v[114:115]
	v_mov_b32_e32 v206, v205
	s_nop 1
	v_permlane32_swap_b32 v205, v206
	v_mov_b32_e32 v204, v203
	s_nop 1
	v_permlane32_swap_b32 v203, v204
	s_waitcnt lgkmcnt(2)
	v_add_f32_e32 v114, v117, v207
	v_mov_b32_e32 v202, v201
	s_nop 1
	v_permlane32_swap_b32 v201, v202
	v_mov_b32_e32 v200, v199
	s_nop 1
	v_permlane32_swap_b32 v199, v200
	v_mov_b32_e32 v198, v197
	s_nop 1
	v_permlane32_swap_b32 v197, v198
	v_mov_b32_e32 v196, v195
	s_nop 1
	v_permlane32_swap_b32 v195, v196
	v_mov_b32_e32 v194, v193
	s_nop 1
	v_permlane32_swap_b32 v193, v194
	v_mov_b32_e32 v115, v114
	s_nop 1
	v_permlane32_swap_b32 v114, v115
	v_cvt_pk_bf16_f32 v125, v212, v213
	global_store_dwordx4 v[208:209], v[122:125], off
	v_cvt_pk_bf16_f32 v116, v118, v119
	v_cvt_pk_bf16_f32 v117, v120, v121
	v_cvt_pk_bf16_f32 v118, v126, v127
	v_cvt_pk_bf16_f32 v119, v128, v129
	global_store_dwordx4 v[208:209], v[116:119], off offset:256
	s_and_saveexec_b64 s[36:37], s[6:7]
	s_cbranch_execz .LBB0_1770
	v_lshl_add_u64 v[116:117], s[18:19], 0, v[182:183]
	v_lshl_add_u64 v[116:117], s[4:5], 2, v[116:117]
	s_lshl_b32 s12, s49, 2
	v_lshl_add_u64 v[116:117], v[116:117], 0, s[12:13]
	s_waitcnt lgkmcnt(0)
	v_add_f32_e32 v114, v114, v115
	global_store_dword v[116:117], v114, off
